# up and residual loops: four of the six second-memory-phase LDS-DMA pieces issued between the MFMAs of the next compute phase, vmcnt(2)
# baseline (speedup 1.0000x reference)
.LBB0_103:
	s_ashr_i32 s23, s22, 31
	s_lshl_b64 s[2:3], s[22:23], 19
	s_add_u32 s58, s90, s2
	s_addc_u32 s59, s77, s3
	s_and_b64 s[2:3], s[46:47], exec
	s_cselect_b32 s1, s59, s49
	s_cselect_b32 s23, s58, s48
	s_add_u32 s34, s34, 0x3e080
	s_addc_u32 s35, s35, 0
	s_add_u32 s51, s48, 0x100
	v_mov_b32_e32 v2, 0
	s_addc_u32 s52, s49, 0
	s_mov_b32 s53, -2
	s_add_u32 s2, s34, 0xfffc2080
	s_addc_u32 s3, s35, -1
	s_add_i32 s12, 0, 0x10000
	v_add_u32_e32 v110, s12, v179
	ds_read_b128 v[98:101], v110
	ds_read_b128 v[102:105], v110 offset:1024
	ds_read_b128 v[106:109], v110 offset:2048
	ds_read_b128 v[110:113], v110 offset:3072
	s_cmp_eq_u32 s53, 12
	s_cselect_b32 s49, s97, s3
	s_cselect_b32 s48, s96, s2
	s_cselect_b32 s3, s1, s52
	s_cselect_b32 s2, s23, s51
	v_lshl_add_u64 v[174:175], s[34:35], 0, v[170:171]
	s_add_i32 m0, s85, 0xc000
	ds_read_b128 v[114:117], v184
	ds_read_b128 v[118:121], v184 offset:1024
	ds_read_b128 v[122:125], v184 offset:2048
	ds_read_b128 v[126:129], v184 offset:3072
	ds_read_b128 v[186:189], v184 offset:4096
	ds_read_b128 v[190:193], v184 offset:5120
	ds_read_b128 v[194:197], v184 offset:6144
	ds_read_b128 v[198:201], v184 offset:7168
	global_load_lds_dwordx4 v[174:175], off
	v_lshl_add_u64 v[174:175], s[34:35], 0, v[172:173]
	s_add_i32 m0, s85, 0xe000
	s_nop 0
	global_load_lds_dwordx4 v[174:175], off
	s_waitcnt lgkmcnt(8)
	s_add_i32 s54, 0, 0x14000
	v_add_u32_e32 v174, s54, v179
	s_add_i32 s12, s12, s78
	ds_read_b128 v[226:229], v174
	ds_read_b128 v[230:233], v174 offset:1024
	ds_read_b128 v[234:237], v174 offset:2048
	ds_read_b128 v[242:245], v174 offset:3072
	s_barrier
	s_waitcnt lgkmcnt(0)
	s_waitcnt lgkmcnt(0)
	s_nop 0
	v_mfma_f32_16x16x32_bf16 v[158:161], v[98:101], v[114:117], 0
	v_mfma_f32_16x16x32_bf16 v[154:157], v[106:109], v[114:117], 0
	v_mfma_f32_16x16x32_bf16 v[150:153], v[98:101], v[122:125], 0
	v_mfma_f32_16x16x32_bf16 v[146:149], v[106:109], v[122:125], 0
	v_mfma_f32_16x16x32_bf16 v[142:145], v[98:101], v[186:189], 0
	v_mfma_f32_16x16x32_bf16 v[138:141], v[106:109], v[186:189], 0
	v_mfma_f32_16x16x32_bf16 v[134:137], v[98:101], v[194:197], 0
	v_mfma_f32_16x16x32_bf16 v[130:133], v[106:109], v[194:197], 0
	v_mfma_f32_16x16x32_bf16 v[158:161], v[102:105], v[118:121], v[158:161]
	v_mfma_f32_16x16x32_bf16 v[154:157], v[110:113], v[118:121], v[154:157]
	v_mfma_f32_16x16x32_bf16 v[150:153], v[102:105], v[126:129], v[150:153]
	v_mfma_f32_16x16x32_bf16 v[146:149], v[110:113], v[126:129], v[146:149]
	v_mfma_f32_16x16x32_bf16 v[142:145], v[102:105], v[190:193], v[142:145]
	v_mfma_f32_16x16x32_bf16 v[138:141], v[110:113], v[190:193], v[138:141]
	v_mfma_f32_16x16x32_bf16 v[134:137], v[102:105], v[198:201], v[134:137]
	v_mfma_f32_16x16x32_bf16 v[130:133], v[110:113], v[198:201], v[130:133]
	s_waitcnt lgkmcnt(0)
	s_waitcnt lgkmcnt(0)
	v_mfma_f32_16x16x32_bf16 v[62:65], v[226:229], v[114:117], 0
	v_mfma_f32_16x16x32_bf16 v[58:61], v[234:237], v[114:117], 0
	v_mfma_f32_16x16x32_bf16 v[54:57], v[226:229], v[122:125], 0
	v_mfma_f32_16x16x32_bf16 v[50:53], v[234:237], v[122:125], 0
	v_mfma_f32_16x16x32_bf16 v[46:49], v[226:229], v[186:189], 0
	v_mfma_f32_16x16x32_bf16 v[42:45], v[234:237], v[186:189], 0
	v_mfma_f32_16x16x32_bf16 v[38:41], v[226:229], v[194:197], 0
	v_mfma_f32_16x16x32_bf16 v[34:37], v[234:237], v[194:197], 0
	v_mfma_f32_16x16x32_bf16 v[62:65], v[230:233], v[118:121], v[62:65]
	v_mfma_f32_16x16x32_bf16 v[58:61], v[242:245], v[118:121], v[58:61]
	v_mfma_f32_16x16x32_bf16 v[54:57], v[230:233], v[126:129], v[54:57]
	v_mfma_f32_16x16x32_bf16 v[50:53], v[242:245], v[126:129], v[50:53]
	v_mfma_f32_16x16x32_bf16 v[46:49], v[230:233], v[190:193], v[46:49]
	v_mfma_f32_16x16x32_bf16 v[42:45], v[242:245], v[190:193], v[42:45]
	v_mfma_f32_16x16x32_bf16 v[38:41], v[230:233], v[198:201], v[38:41]
	v_mfma_f32_16x16x32_bf16 v[34:37], v[242:245], v[198:201], v[34:37]
	s_mov_b32 m0, s85
	v_lshl_add_u64 v[248:249], s[48:49], 0, v[162:163]
	s_barrier
	ds_read_b128 v[114:117], v184 offset:16384
	ds_read_b128 v[118:121], v184 offset:17408
	ds_read_b128 v[122:125], v184 offset:18432
	ds_read_b128 v[126:129], v184 offset:19456
	ds_read_b128 v[186:189], v184 offset:20480
	ds_read_b128 v[190:193], v184 offset:21504
	ds_read_b128 v[194:197], v184 offset:22528
	ds_read_b128 v[198:201], v184 offset:23552
	global_load_lds_dwordx4 v[248:249], off
	v_lshl_add_u64 v[250:251], s[48:49], 0, v[164:165]
	s_mov_b32 m0, s82
	s_nop 0
	global_load_lds_dwordx4 v[250:251], off
	s_waitcnt vmcnt(2)
	s_barrier
	s_waitcnt lgkmcnt(0)
	s_waitcnt lgkmcnt(0)
	v_mfma_f32_16x16x32_bf16 v[94:97], v[98:101], v[114:117], 0
	v_mfma_f32_16x16x32_bf16 v[90:93], v[106:109], v[114:117], 0
	v_mfma_f32_16x16x32_bf16 v[86:89], v[98:101], v[122:125], 0
	v_mfma_f32_16x16x32_bf16 v[82:85], v[106:109], v[122:125], 0
	v_lshl_add_u64 v[174:175], s[2:3], 0, v[0:1]
	s_mov_b32 m0, s12
	v_lshl_add_u64 v[246:247], s[2:3], 0, v[166:167]
	global_load_lds_dwordx4 v[174:175], off
	s_nop 0
	v_mfma_f32_16x16x32_bf16 v[78:81], v[98:101], v[186:189], 0
	v_mfma_f32_16x16x32_bf16 v[74:77], v[106:109], v[186:189], 0
	v_mfma_f32_16x16x32_bf16 v[70:73], v[98:101], v[194:197], 0
	v_mfma_f32_16x16x32_bf16 v[66:69], v[106:109], v[194:197], 0
	v_mfma_f32_16x16x32_bf16 v[94:97], v[102:105], v[118:121], v[94:97]
	v_mfma_f32_16x16x32_bf16 v[90:93], v[110:113], v[118:121], v[90:93]
	v_mfma_f32_16x16x32_bf16 v[86:89], v[102:105], v[126:129], v[86:89]
	v_mfma_f32_16x16x32_bf16 v[82:85], v[110:113], v[126:129], v[82:85]
	s_add_i32 m0, s12, 0x2000
	s_nop 0
	global_load_lds_dwordx4 v[246:247], off
	s_nop 0
	v_mfma_f32_16x16x32_bf16 v[78:81], v[102:105], v[190:193], v[78:81]
	v_mfma_f32_16x16x32_bf16 v[74:77], v[110:113], v[190:193], v[74:77]
	v_mfma_f32_16x16x32_bf16 v[70:73], v[102:105], v[198:201], v[70:73]
	v_mfma_f32_16x16x32_bf16 v[66:69], v[110:113], v[198:201], v[66:69]
	v_mfma_f32_16x16x32_bf16 v[30:33], v[226:229], v[114:117], 0
	v_mfma_f32_16x16x32_bf16 v[26:29], v[234:237], v[114:117], 0
	v_mfma_f32_16x16x32_bf16 v[22:25], v[226:229], v[122:125], 0
	v_mfma_f32_16x16x32_bf16 v[18:21], v[234:237], v[122:125], 0
	s_add_u32 s12, s2, 0x40000
	s_addc_u32 s13, s3, 0
	s_add_i32 s54, s54, s78
	v_lshl_add_u64 v[174:175], s[12:13], 0, v[0:1]
	s_mov_b32 m0, s54
	s_nop 0
	global_load_lds_dwordx4 v[174:175], off
	v_mfma_f32_16x16x32_bf16 v[14:17], v[226:229], v[186:189], 0
	v_mfma_f32_16x16x32_bf16 v[10:13], v[234:237], v[186:189], 0
	v_mfma_f32_16x16x32_bf16 v[6:9], v[226:229], v[194:197], 0
	v_mfma_f32_16x16x32_bf16 v[2:5], v[234:237], v[194:197], 0
	v_mfma_f32_16x16x32_bf16 v[30:33], v[230:233], v[118:121], v[30:33]
	v_mfma_f32_16x16x32_bf16 v[26:29], v[242:245], v[118:121], v[26:29]
	v_mfma_f32_16x16x32_bf16 v[22:25], v[230:233], v[126:129], v[22:25]
	v_mfma_f32_16x16x32_bf16 v[18:21], v[242:245], v[126:129], v[18:21]
	v_lshl_add_u64 v[174:175], s[12:13], 0, v[166:167]
	s_add_i32 m0, s54, 0x2000
	s_nop 0
	global_load_lds_dwordx4 v[174:175], off
	v_mfma_f32_16x16x32_bf16 v[14:17], v[230:233], v[190:193], v[14:17]
	v_mfma_f32_16x16x32_bf16 v[10:13], v[242:245], v[190:193], v[10:13]
	v_mfma_f32_16x16x32_bf16 v[6:9], v[230:233], v[198:201], v[6:9]
	v_mfma_f32_16x16x32_bf16 v[2:5], v[242:245], v[198:201], v[2:5]
	s_add_i32 s54, 0, 0x18000
	v_add_u32_e32 v110, s54, v179
	s_barrier
	ds_read_b128 v[98:101], v110
	ds_read_b128 v[102:105], v110 offset:1024
	ds_read_b128 v[106:109], v110 offset:2048
	ds_read_b128 v[110:113], v110 offset:3072
	s_add_u32 s12, s48, 0x3e000
	s_addc_u32 s13, s49, 0
	s_mov_b32 m0, s89
	v_lshl_add_u64 v[226:227], s[12:13], 0, v[162:163]
	ds_read_b128 v[114:117], v184 offset:32768
	ds_read_b128 v[118:121], v184 offset:33792
	ds_read_b128 v[122:125], v184 offset:34816
	ds_read_b128 v[126:129], v184 offset:35840
	ds_read_b128 v[186:189], v184 offset:36864
	ds_read_b128 v[190:193], v184 offset:37888
	ds_read_b128 v[194:197], v184 offset:38912
	ds_read_b128 v[198:201], v184 offset:39936
	global_load_lds_dwordx4 v[226:227], off
	v_lshl_add_u64 v[226:227], s[12:13], 0, v[164:165]
	s_mov_b32 m0, s91
	s_nop 0
	global_load_lds_dwordx4 v[226:227], off
	s_waitcnt lgkmcnt(8)
	s_add_i32 s12, 0, 0x1c000
	s_add_i32 s13, s54, s78
	v_add_u32_e32 v242, s12, v179
	ds_read_b128 v[226:229], v242
	ds_read_b128 v[230:233], v242 offset:1024
	ds_read_b128 v[234:237], v242 offset:2048
	ds_read_b128 v[242:245], v242 offset:3072
	s_barrier
	s_waitcnt lgkmcnt(0)
	s_waitcnt lgkmcnt(0)
	s_nop 0
	v_mfma_f32_16x16x32_bf16 v[158:161], v[98:101], v[114:117], v[158:161]
	v_mfma_f32_16x16x32_bf16 v[154:157], v[106:109], v[114:117], v[154:157]
	v_mfma_f32_16x16x32_bf16 v[150:153], v[98:101], v[122:125], v[150:153]
	v_mfma_f32_16x16x32_bf16 v[146:149], v[106:109], v[122:125], v[146:149]
	v_mfma_f32_16x16x32_bf16 v[142:145], v[98:101], v[186:189], v[142:145]
	v_mfma_f32_16x16x32_bf16 v[138:141], v[106:109], v[186:189], v[138:141]
	v_mfma_f32_16x16x32_bf16 v[134:137], v[98:101], v[194:197], v[134:137]
	v_mfma_f32_16x16x32_bf16 v[130:133], v[106:109], v[194:197], v[130:133]
	v_mfma_f32_16x16x32_bf16 v[158:161], v[102:105], v[118:121], v[158:161]
	v_mfma_f32_16x16x32_bf16 v[154:157], v[110:113], v[118:121], v[154:157]
	v_mfma_f32_16x16x32_bf16 v[150:153], v[102:105], v[126:129], v[150:153]
	v_mfma_f32_16x16x32_bf16 v[146:149], v[110:113], v[126:129], v[146:149]
	v_mfma_f32_16x16x32_bf16 v[142:145], v[102:105], v[190:193], v[142:145]
	v_mfma_f32_16x16x32_bf16 v[138:141], v[110:113], v[190:193], v[138:141]
	v_mfma_f32_16x16x32_bf16 v[134:137], v[102:105], v[198:201], v[134:137]
	v_mfma_f32_16x16x32_bf16 v[130:133], v[110:113], v[198:201], v[130:133]
	s_waitcnt lgkmcnt(0)
	s_waitcnt lgkmcnt(0)
	v_mfma_f32_16x16x32_bf16 v[62:65], v[226:229], v[114:117], v[62:65]
	v_mfma_f32_16x16x32_bf16 v[58:61], v[234:237], v[114:117], v[58:61]
	v_mfma_f32_16x16x32_bf16 v[54:57], v[226:229], v[122:125], v[54:57]
	v_mfma_f32_16x16x32_bf16 v[50:53], v[234:237], v[122:125], v[50:53]
	v_mfma_f32_16x16x32_bf16 v[46:49], v[226:229], v[186:189], v[46:49]
	v_mfma_f32_16x16x32_bf16 v[42:45], v[234:237], v[186:189], v[42:45]
	v_mfma_f32_16x16x32_bf16 v[38:41], v[226:229], v[194:197], v[38:41]
	v_mfma_f32_16x16x32_bf16 v[34:37], v[234:237], v[194:197], v[34:37]
	v_mfma_f32_16x16x32_bf16 v[62:65], v[230:233], v[118:121], v[62:65]
	v_mfma_f32_16x16x32_bf16 v[58:61], v[242:245], v[118:121], v[58:61]
	v_mfma_f32_16x16x32_bf16 v[54:57], v[230:233], v[126:129], v[54:57]
	v_mfma_f32_16x16x32_bf16 v[50:53], v[242:245], v[126:129], v[50:53]
	v_mfma_f32_16x16x32_bf16 v[46:49], v[230:233], v[190:193], v[46:49]
	v_mfma_f32_16x16x32_bf16 v[42:45], v[242:245], v[190:193], v[42:45]
	v_mfma_f32_16x16x32_bf16 v[38:41], v[230:233], v[198:201], v[38:41]
	v_mfma_f32_16x16x32_bf16 v[34:37], v[242:245], v[198:201], v[34:37]
	s_mov_b32 m0, s79
	v_lshl_add_u64 v[174:175], v[248:249], 0, s[20:21]
	s_barrier
	ds_read_b128 v[114:117], v184 offset:49152
	ds_read_b128 v[118:121], v184 offset:50176
	ds_read_b128 v[122:125], v184 offset:51200
	ds_read_b128 v[126:129], v184 offset:52224
	ds_read_b128 v[186:189], v184 offset:53248
	ds_read_b128 v[190:193], v184 offset:54272
	ds_read_b128 v[194:197], v184 offset:55296
	ds_read_b128 v[198:201], v184 offset:56320
	global_load_lds_dwordx4 v[174:175], off
	v_lshl_add_u64 v[174:175], v[250:251], 0, s[20:21]
	s_mov_b32 m0, s87
	s_nop 0
	global_load_lds_dwordx4 v[174:175], off
	s_waitcnt vmcnt(2)
	s_barrier
	s_waitcnt lgkmcnt(0)
	s_waitcnt lgkmcnt(0)
	v_mfma_f32_16x16x32_bf16 v[94:97], v[98:101], v[114:117], v[94:97]
	v_mfma_f32_16x16x32_bf16 v[90:93], v[106:109], v[114:117], v[90:93]
	v_mfma_f32_16x16x32_bf16 v[86:89], v[98:101], v[122:125], v[86:89]
	v_mfma_f32_16x16x32_bf16 v[82:85], v[106:109], v[122:125], v[82:85]
	v_lshl_add_u64 v[174:175], s[2:3], 0, v[0:1]
	v_lshl_add_u64 v[174:175], v[174:175], 0, s[20:21]
	s_mov_b32 m0, s13
	s_nop 0
	global_load_lds_dwordx4 v[174:175], off
	v_mfma_f32_16x16x32_bf16 v[78:81], v[98:101], v[186:189], v[78:81]
	v_mfma_f32_16x16x32_bf16 v[74:77], v[106:109], v[186:189], v[74:77]
	v_mfma_f32_16x16x32_bf16 v[70:73], v[98:101], v[194:197], v[70:73]
	v_mfma_f32_16x16x32_bf16 v[66:69], v[106:109], v[194:197], v[66:69]
	v_mfma_f32_16x16x32_bf16 v[94:97], v[102:105], v[118:121], v[94:97]
	v_mfma_f32_16x16x32_bf16 v[90:93], v[110:113], v[118:121], v[90:93]
	v_mfma_f32_16x16x32_bf16 v[86:89], v[102:105], v[126:129], v[86:89]
	v_mfma_f32_16x16x32_bf16 v[82:85], v[110:113], v[126:129], v[82:85]
	v_lshl_add_u64 v[174:175], v[246:247], 0, s[20:21]
	s_add_i32 m0, s13, 0x2000
	s_nop 0
	global_load_lds_dwordx4 v[174:175], off
	s_nop 0
	v_mfma_f32_16x16x32_bf16 v[78:81], v[102:105], v[190:193], v[78:81]
	v_mfma_f32_16x16x32_bf16 v[74:77], v[110:113], v[190:193], v[74:77]
	v_mfma_f32_16x16x32_bf16 v[70:73], v[102:105], v[198:201], v[70:73]
	v_mfma_f32_16x16x32_bf16 v[66:69], v[110:113], v[198:201], v[66:69]
	v_mfma_f32_16x16x32_bf16 v[30:33], v[226:229], v[114:117], v[30:33]
	v_mfma_f32_16x16x32_bf16 v[26:29], v[234:237], v[114:117], v[26:29]
	v_mfma_f32_16x16x32_bf16 v[22:25], v[226:229], v[122:125], v[22:25]
	v_mfma_f32_16x16x32_bf16 v[18:21], v[234:237], v[122:125], v[18:21]
	s_add_u32 s2, s2, 0x40080
	s_addc_u32 s3, s3, 0
	s_add_i32 s12, s12, s78
	v_lshl_add_u64 v[174:175], s[2:3], 0, v[0:1]
	s_mov_b32 m0, s12
	s_nop 0
	global_load_lds_dwordx4 v[174:175], off
	v_mfma_f32_16x16x32_bf16 v[14:17], v[226:229], v[186:189], v[14:17]
	v_mfma_f32_16x16x32_bf16 v[10:13], v[234:237], v[186:189], v[10:13]
	v_mfma_f32_16x16x32_bf16 v[6:9], v[226:229], v[194:197], v[6:9]
	v_mfma_f32_16x16x32_bf16 v[2:5], v[234:237], v[194:197], v[2:5]
	v_mfma_f32_16x16x32_bf16 v[30:33], v[230:233], v[118:121], v[30:33]
	v_mfma_f32_16x16x32_bf16 v[26:29], v[242:245], v[118:121], v[26:29]
	v_mfma_f32_16x16x32_bf16 v[22:25], v[230:233], v[126:129], v[22:25]
	v_mfma_f32_16x16x32_bf16 v[18:21], v[242:245], v[126:129], v[18:21]
	v_lshl_add_u64 v[174:175], s[2:3], 0, v[166:167]
	s_add_i32 m0, s12, 0x2000
	s_nop 0
	global_load_lds_dwordx4 v[174:175], off
	v_mfma_f32_16x16x32_bf16 v[14:17], v[230:233], v[190:193], v[14:17]
	v_mfma_f32_16x16x32_bf16 v[10:13], v[242:245], v[190:193], v[10:13]
	v_mfma_f32_16x16x32_bf16 v[6:9], v[230:233], v[198:201], v[6:9]
	v_mfma_f32_16x16x32_bf16 v[2:5], v[242:245], v[198:201], v[2:5]
	s_add_i32 s53, s53, 2
	s_add_u32 s34, s34, 0x100
	s_addc_u32 s35, s35, 0
	s_add_u32 s51, s51, 0x100
	s_addc_u32 s52, s52, 0
	s_cmp_gt_u32 s53, 13
	s_barrier
	s_cbranch_scc1 .Lpeel_x_104
.LBB0_104:
	s_add_u32 s2, s34, 0xfffc2080
	s_addc_u32 s3, s35, -1
	s_add_i32 s12, 0, 0x10000
	v_add_u32_e32 v110, s12, v179
	ds_read_b128 v[98:101], v110
	ds_read_b128 v[102:105], v110 offset:1024
	ds_read_b128 v[106:109], v110 offset:2048
	ds_read_b128 v[110:113], v110 offset:3072
	s_cmp_eq_u32 s53, 12
	s_cselect_b32 s49, s97, s3
	s_cselect_b32 s48, s96, s2
	s_cselect_b32 s3, s1, s52
	s_cselect_b32 s2, s23, s51
	v_lshl_add_u64 v[174:175], s[34:35], 0, v[170:171]
	s_add_i32 m0, s85, 0xc000
	ds_read_b128 v[114:117], v184
	ds_read_b128 v[118:121], v184 offset:1024
	ds_read_b128 v[122:125], v184 offset:2048
	ds_read_b128 v[126:129], v184 offset:3072
	ds_read_b128 v[186:189], v184 offset:4096
	ds_read_b128 v[190:193], v184 offset:5120
	ds_read_b128 v[194:197], v184 offset:6144
	ds_read_b128 v[198:201], v184 offset:7168
	global_load_lds_dwordx4 v[174:175], off
	v_lshl_add_u64 v[174:175], s[34:35], 0, v[172:173]
	s_add_i32 m0, s85, 0xe000
	s_nop 0
	global_load_lds_dwordx4 v[174:175], off
	s_waitcnt lgkmcnt(8)
	s_add_i32 s54, 0, 0x14000
	v_add_u32_e32 v174, s54, v179
	s_add_i32 s12, s12, s78
	ds_read_b128 v[226:229], v174
	ds_read_b128 v[230:233], v174 offset:1024
	ds_read_b128 v[234:237], v174 offset:2048
	ds_read_b128 v[242:245], v174 offset:3072
	s_barrier
	s_waitcnt lgkmcnt(0)
	s_waitcnt lgkmcnt(0)
	s_nop 0
	v_mfma_f32_16x16x32_bf16 v[158:161], v[98:101], v[114:117], v[158:161]
	v_mfma_f32_16x16x32_bf16 v[154:157], v[106:109], v[114:117], v[154:157]
	v_mfma_f32_16x16x32_bf16 v[150:153], v[98:101], v[122:125], v[150:153]
	v_mfma_f32_16x16x32_bf16 v[146:149], v[106:109], v[122:125], v[146:149]
	v_mfma_f32_16x16x32_bf16 v[142:145], v[98:101], v[186:189], v[142:145]
	v_mfma_f32_16x16x32_bf16 v[138:141], v[106:109], v[186:189], v[138:141]
	v_mfma_f32_16x16x32_bf16 v[134:137], v[98:101], v[194:197], v[134:137]
	v_mfma_f32_16x16x32_bf16 v[130:133], v[106:109], v[194:197], v[130:133]
	v_mfma_f32_16x16x32_bf16 v[158:161], v[102:105], v[118:121], v[158:161]
	v_mfma_f32_16x16x32_bf16 v[154:157], v[110:113], v[118:121], v[154:157]
	v_mfma_f32_16x16x32_bf16 v[150:153], v[102:105], v[126:129], v[150:153]
	v_mfma_f32_16x16x32_bf16 v[146:149], v[110:113], v[126:129], v[146:149]
	v_mfma_f32_16x16x32_bf16 v[142:145], v[102:105], v[190:193], v[142:145]
	v_mfma_f32_16x16x32_bf16 v[138:141], v[110:113], v[190:193], v[138:141]
	v_mfma_f32_16x16x32_bf16 v[134:137], v[102:105], v[198:201], v[134:137]
	v_mfma_f32_16x16x32_bf16 v[130:133], v[110:113], v[198:201], v[130:133]
	s_waitcnt lgkmcnt(0)
	s_waitcnt lgkmcnt(0)
	v_mfma_f32_16x16x32_bf16 v[62:65], v[226:229], v[114:117], v[62:65]
	v_mfma_f32_16x16x32_bf16 v[58:61], v[234:237], v[114:117], v[58:61]
	v_mfma_f32_16x16x32_bf16 v[54:57], v[226:229], v[122:125], v[54:57]
	v_mfma_f32_16x16x32_bf16 v[50:53], v[234:237], v[122:125], v[50:53]
	v_mfma_f32_16x16x32_bf16 v[46:49], v[226:229], v[186:189], v[46:49]
	v_mfma_f32_16x16x32_bf16 v[42:45], v[234:237], v[186:189], v[42:45]
	v_mfma_f32_16x16x32_bf16 v[38:41], v[226:229], v[194:197], v[38:41]
	v_mfma_f32_16x16x32_bf16 v[34:37], v[234:237], v[194:197], v[34:37]
	v_mfma_f32_16x16x32_bf16 v[62:65], v[230:233], v[118:121], v[62:65]
	v_mfma_f32_16x16x32_bf16 v[58:61], v[242:245], v[118:121], v[58:61]
	v_mfma_f32_16x16x32_bf16 v[54:57], v[230:233], v[126:129], v[54:57]
	v_mfma_f32_16x16x32_bf16 v[50:53], v[242:245], v[126:129], v[50:53]
	v_mfma_f32_16x16x32_bf16 v[46:49], v[230:233], v[190:193], v[46:49]
	v_mfma_f32_16x16x32_bf16 v[42:45], v[242:245], v[190:193], v[42:45]
	v_mfma_f32_16x16x32_bf16 v[38:41], v[230:233], v[198:201], v[38:41]
	v_mfma_f32_16x16x32_bf16 v[34:37], v[242:245], v[198:201], v[34:37]
	s_mov_b32 m0, s85
	v_lshl_add_u64 v[248:249], s[48:49], 0, v[162:163]
	s_barrier
	ds_read_b128 v[114:117], v184 offset:16384
	ds_read_b128 v[118:121], v184 offset:17408
	ds_read_b128 v[122:125], v184 offset:18432
	ds_read_b128 v[126:129], v184 offset:19456
	ds_read_b128 v[186:189], v184 offset:20480
	ds_read_b128 v[190:193], v184 offset:21504
	ds_read_b128 v[194:197], v184 offset:22528
	ds_read_b128 v[198:201], v184 offset:23552
	global_load_lds_dwordx4 v[248:249], off
	v_lshl_add_u64 v[250:251], s[48:49], 0, v[164:165]
	s_mov_b32 m0, s82
	s_nop 0
	global_load_lds_dwordx4 v[250:251], off
	s_waitcnt vmcnt(2)
	s_barrier
	s_waitcnt lgkmcnt(0)
	s_waitcnt lgkmcnt(0)
	v_mfma_f32_16x16x32_bf16 v[94:97], v[98:101], v[114:117], v[94:97]
	v_mfma_f32_16x16x32_bf16 v[90:93], v[106:109], v[114:117], v[90:93]
	v_mfma_f32_16x16x32_bf16 v[86:89], v[98:101], v[122:125], v[86:89]
	v_mfma_f32_16x16x32_bf16 v[82:85], v[106:109], v[122:125], v[82:85]
	v_lshl_add_u64 v[174:175], s[2:3], 0, v[0:1]
	s_mov_b32 m0, s12
	v_lshl_add_u64 v[246:247], s[2:3], 0, v[166:167]
	global_load_lds_dwordx4 v[174:175], off
	s_nop 0
	v_mfma_f32_16x16x32_bf16 v[78:81], v[98:101], v[186:189], v[78:81]
	v_mfma_f32_16x16x32_bf16 v[74:77], v[106:109], v[186:189], v[74:77]
	v_mfma_f32_16x16x32_bf16 v[70:73], v[98:101], v[194:197], v[70:73]
	v_mfma_f32_16x16x32_bf16 v[66:69], v[106:109], v[194:197], v[66:69]
	v_mfma_f32_16x16x32_bf16 v[94:97], v[102:105], v[118:121], v[94:97]
	v_mfma_f32_16x16x32_bf16 v[90:93], v[110:113], v[118:121], v[90:93]
	v_mfma_f32_16x16x32_bf16 v[86:89], v[102:105], v[126:129], v[86:89]
	v_mfma_f32_16x16x32_bf16 v[82:85], v[110:113], v[126:129], v[82:85]
	s_add_i32 m0, s12, 0x2000
	s_nop 0
	global_load_lds_dwordx4 v[246:247], off
	s_nop 0
	v_mfma_f32_16x16x32_bf16 v[78:81], v[102:105], v[190:193], v[78:81]
	v_mfma_f32_16x16x32_bf16 v[74:77], v[110:113], v[190:193], v[74:77]
	v_mfma_f32_16x16x32_bf16 v[70:73], v[102:105], v[198:201], v[70:73]
	v_mfma_f32_16x16x32_bf16 v[66:69], v[110:113], v[198:201], v[66:69]
	v_mfma_f32_16x16x32_bf16 v[30:33], v[226:229], v[114:117], v[30:33]
	v_mfma_f32_16x16x32_bf16 v[26:29], v[234:237], v[114:117], v[26:29]
	v_mfma_f32_16x16x32_bf16 v[22:25], v[226:229], v[122:125], v[22:25]
	v_mfma_f32_16x16x32_bf16 v[18:21], v[234:237], v[122:125], v[18:21]
	s_add_u32 s12, s2, 0x40000
	s_addc_u32 s13, s3, 0
	s_add_i32 s54, s54, s78
	v_lshl_add_u64 v[174:175], s[12:13], 0, v[0:1]
	s_mov_b32 m0, s54
	s_nop 0
	global_load_lds_dwordx4 v[174:175], off
	v_mfma_f32_16x16x32_bf16 v[14:17], v[226:229], v[186:189], v[14:17]
	v_mfma_f32_16x16x32_bf16 v[10:13], v[234:237], v[186:189], v[10:13]
	v_mfma_f32_16x16x32_bf16 v[6:9], v[226:229], v[194:197], v[6:9]
	v_mfma_f32_16x16x32_bf16 v[2:5], v[234:237], v[194:197], v[2:5]
	v_mfma_f32_16x16x32_bf16 v[30:33], v[230:233], v[118:121], v[30:33]
	v_mfma_f32_16x16x32_bf16 v[26:29], v[242:245], v[118:121], v[26:29]
	v_mfma_f32_16x16x32_bf16 v[22:25], v[230:233], v[126:129], v[22:25]
	v_mfma_f32_16x16x32_bf16 v[18:21], v[242:245], v[126:129], v[18:21]
	v_lshl_add_u64 v[174:175], s[12:13], 0, v[166:167]
	s_add_i32 m0, s54, 0x2000
	s_nop 0
	global_load_lds_dwordx4 v[174:175], off
	v_mfma_f32_16x16x32_bf16 v[14:17], v[230:233], v[190:193], v[14:17]
	v_mfma_f32_16x16x32_bf16 v[10:13], v[242:245], v[190:193], v[10:13]
	v_mfma_f32_16x16x32_bf16 v[6:9], v[230:233], v[198:201], v[6:9]
	v_mfma_f32_16x16x32_bf16 v[2:5], v[242:245], v[198:201], v[2:5]
	s_add_i32 s54, 0, 0x18000
	v_add_u32_e32 v110, s54, v179
	s_barrier
	ds_read_b128 v[98:101], v110
	ds_read_b128 v[102:105], v110 offset:1024
	ds_read_b128 v[106:109], v110 offset:2048
	ds_read_b128 v[110:113], v110 offset:3072
	s_add_u32 s12, s48, 0x3e000
	s_addc_u32 s13, s49, 0
	s_mov_b32 m0, s89
	v_lshl_add_u64 v[226:227], s[12:13], 0, v[162:163]
	ds_read_b128 v[114:117], v184 offset:32768
	ds_read_b128 v[118:121], v184 offset:33792
	ds_read_b128 v[122:125], v184 offset:34816
	ds_read_b128 v[126:129], v184 offset:35840
	ds_read_b128 v[186:189], v184 offset:36864
	ds_read_b128 v[190:193], v184 offset:37888
	ds_read_b128 v[194:197], v184 offset:38912
	ds_read_b128 v[198:201], v184 offset:39936
	global_load_lds_dwordx4 v[226:227], off
	v_lshl_add_u64 v[226:227], s[12:13], 0, v[164:165]
	s_mov_b32 m0, s91
	s_nop 0
	global_load_lds_dwordx4 v[226:227], off
	s_waitcnt lgkmcnt(8)
	s_add_i32 s12, 0, 0x1c000
	s_add_i32 s13, s54, s78
	v_add_u32_e32 v242, s12, v179
	ds_read_b128 v[226:229], v242
	ds_read_b128 v[230:233], v242 offset:1024
	ds_read_b128 v[234:237], v242 offset:2048
	ds_read_b128 v[242:245], v242 offset:3072
	s_barrier
	s_waitcnt lgkmcnt(0)
	s_waitcnt lgkmcnt(0)
	s_nop 0
	v_mfma_f32_16x16x32_bf16 v[158:161], v[98:101], v[114:117], v[158:161]
	v_mfma_f32_16x16x32_bf16 v[154:157], v[106:109], v[114:117], v[154:157]
	v_mfma_f32_16x16x32_bf16 v[150:153], v[98:101], v[122:125], v[150:153]
	v_mfma_f32_16x16x32_bf16 v[146:149], v[106:109], v[122:125], v[146:149]
	v_mfma_f32_16x16x32_bf16 v[142:145], v[98:101], v[186:189], v[142:145]
	v_mfma_f32_16x16x32_bf16 v[138:141], v[106:109], v[186:189], v[138:141]
	v_mfma_f32_16x16x32_bf16 v[134:137], v[98:101], v[194:197], v[134:137]
	v_mfma_f32_16x16x32_bf16 v[130:133], v[106:109], v[194:197], v[130:133]
	v_mfma_f32_16x16x32_bf16 v[158:161], v[102:105], v[118:121], v[158:161]
	v_mfma_f32_16x16x32_bf16 v[154:157], v[110:113], v[118:121], v[154:157]
	v_mfma_f32_16x16x32_bf16 v[150:153], v[102:105], v[126:129], v[150:153]
	v_mfma_f32_16x16x32_bf16 v[146:149], v[110:113], v[126:129], v[146:149]
	v_mfma_f32_16x16x32_bf16 v[142:145], v[102:105], v[190:193], v[142:145]
	v_mfma_f32_16x16x32_bf16 v[138:141], v[110:113], v[190:193], v[138:141]
	v_mfma_f32_16x16x32_bf16 v[134:137], v[102:105], v[198:201], v[134:137]
	v_mfma_f32_16x16x32_bf16 v[130:133], v[110:113], v[198:201], v[130:133]
	s_waitcnt lgkmcnt(0)
	s_waitcnt lgkmcnt(0)
	v_mfma_f32_16x16x32_bf16 v[62:65], v[226:229], v[114:117], v[62:65]
	v_mfma_f32_16x16x32_bf16 v[58:61], v[234:237], v[114:117], v[58:61]
	v_mfma_f32_16x16x32_bf16 v[54:57], v[226:229], v[122:125], v[54:57]
	v_mfma_f32_16x16x32_bf16 v[50:53], v[234:237], v[122:125], v[50:53]
	v_mfma_f32_16x16x32_bf16 v[46:49], v[226:229], v[186:189], v[46:49]
	v_mfma_f32_16x16x32_bf16 v[42:45], v[234:237], v[186:189], v[42:45]
	v_mfma_f32_16x16x32_bf16 v[38:41], v[226:229], v[194:197], v[38:41]
	v_mfma_f32_16x16x32_bf16 v[34:37], v[234:237], v[194:197], v[34:37]
	v_mfma_f32_16x16x32_bf16 v[62:65], v[230:233], v[118:121], v[62:65]
	v_mfma_f32_16x16x32_bf16 v[58:61], v[242:245], v[118:121], v[58:61]
	v_mfma_f32_16x16x32_bf16 v[54:57], v[230:233], v[126:129], v[54:57]
	v_mfma_f32_16x16x32_bf16 v[50:53], v[242:245], v[126:129], v[50:53]
	v_mfma_f32_16x16x32_bf16 v[46:49], v[230:233], v[190:193], v[46:49]
	v_mfma_f32_16x16x32_bf16 v[42:45], v[242:245], v[190:193], v[42:45]
	v_mfma_f32_16x16x32_bf16 v[38:41], v[230:233], v[198:201], v[38:41]
	v_mfma_f32_16x16x32_bf16 v[34:37], v[242:245], v[198:201], v[34:37]
	s_mov_b32 m0, s79
	v_lshl_add_u64 v[174:175], v[248:249], 0, s[20:21]
	s_barrier
	ds_read_b128 v[114:117], v184 offset:49152
	ds_read_b128 v[118:121], v184 offset:50176
	ds_read_b128 v[122:125], v184 offset:51200
	ds_read_b128 v[126:129], v184 offset:52224
	ds_read_b128 v[186:189], v184 offset:53248
	ds_read_b128 v[190:193], v184 offset:54272
	ds_read_b128 v[194:197], v184 offset:55296
	ds_read_b128 v[198:201], v184 offset:56320
	global_load_lds_dwordx4 v[174:175], off
	v_lshl_add_u64 v[174:175], v[250:251], 0, s[20:21]
	s_mov_b32 m0, s87
	s_nop 0
	global_load_lds_dwordx4 v[174:175], off
	s_waitcnt vmcnt(2)
	s_barrier
	s_waitcnt lgkmcnt(0)
	s_waitcnt lgkmcnt(0)
	v_mfma_f32_16x16x32_bf16 v[94:97], v[98:101], v[114:117], v[94:97]
	v_mfma_f32_16x16x32_bf16 v[90:93], v[106:109], v[114:117], v[90:93]
	v_mfma_f32_16x16x32_bf16 v[86:89], v[98:101], v[122:125], v[86:89]
	v_mfma_f32_16x16x32_bf16 v[82:85], v[106:109], v[122:125], v[82:85]
	v_lshl_add_u64 v[174:175], s[2:3], 0, v[0:1]
	v_lshl_add_u64 v[174:175], v[174:175], 0, s[20:21]
	s_mov_b32 m0, s13
	s_nop 0
	global_load_lds_dwordx4 v[174:175], off
	v_mfma_f32_16x16x32_bf16 v[78:81], v[98:101], v[186:189], v[78:81]
	v_mfma_f32_16x16x32_bf16 v[74:77], v[106:109], v[186:189], v[74:77]
	v_mfma_f32_16x16x32_bf16 v[70:73], v[98:101], v[194:197], v[70:73]
	v_mfma_f32_16x16x32_bf16 v[66:69], v[106:109], v[194:197], v[66:69]
	v_mfma_f32_16x16x32_bf16 v[94:97], v[102:105], v[118:121], v[94:97]
	v_mfma_f32_16x16x32_bf16 v[90:93], v[110:113], v[118:121], v[90:93]
	v_mfma_f32_16x16x32_bf16 v[86:89], v[102:105], v[126:129], v[86:89]
	v_mfma_f32_16x16x32_bf16 v[82:85], v[110:113], v[126:129], v[82:85]
	v_lshl_add_u64 v[174:175], v[246:247], 0, s[20:21]
	s_add_i32 m0, s13, 0x2000
	s_nop 0
	global_load_lds_dwordx4 v[174:175], off
	s_nop 0
	v_mfma_f32_16x16x32_bf16 v[78:81], v[102:105], v[190:193], v[78:81]
	v_mfma_f32_16x16x32_bf16 v[74:77], v[110:113], v[190:193], v[74:77]
	v_mfma_f32_16x16x32_bf16 v[70:73], v[102:105], v[198:201], v[70:73]
	v_mfma_f32_16x16x32_bf16 v[66:69], v[110:113], v[198:201], v[66:69]
	v_mfma_f32_16x16x32_bf16 v[30:33], v[226:229], v[114:117], v[30:33]
	v_mfma_f32_16x16x32_bf16 v[26:29], v[234:237], v[114:117], v[26:29]
	v_mfma_f32_16x16x32_bf16 v[22:25], v[226:229], v[122:125], v[22:25]
	v_mfma_f32_16x16x32_bf16 v[18:21], v[234:237], v[122:125], v[18:21]
	s_add_u32 s2, s2, 0x40080
	s_addc_u32 s3, s3, 0
	s_add_i32 s12, s12, s78
	v_lshl_add_u64 v[174:175], s[2:3], 0, v[0:1]
	s_mov_b32 m0, s12
	s_nop 0
	global_load_lds_dwordx4 v[174:175], off
	v_mfma_f32_16x16x32_bf16 v[14:17], v[226:229], v[186:189], v[14:17]
	v_mfma_f32_16x16x32_bf16 v[10:13], v[234:237], v[186:189], v[10:13]
	v_mfma_f32_16x16x32_bf16 v[6:9], v[226:229], v[194:197], v[6:9]
	v_mfma_f32_16x16x32_bf16 v[2:5], v[234:237], v[194:197], v[2:5]
	v_mfma_f32_16x16x32_bf16 v[30:33], v[230:233], v[118:121], v[30:33]
	v_mfma_f32_16x16x32_bf16 v[26:29], v[242:245], v[118:121], v[26:29]
	v_mfma_f32_16x16x32_bf16 v[22:25], v[230:233], v[126:129], v[22:25]
	v_mfma_f32_16x16x32_bf16 v[18:21], v[242:245], v[126:129], v[18:21]
	v_lshl_add_u64 v[174:175], s[2:3], 0, v[166:167]
	s_add_i32 m0, s12, 0x2000
	s_nop 0
	global_load_lds_dwordx4 v[174:175], off
	v_mfma_f32_16x16x32_bf16 v[14:17], v[230:233], v[190:193], v[14:17]
	v_mfma_f32_16x16x32_bf16 v[10:13], v[242:245], v[190:193], v[10:13]
	v_mfma_f32_16x16x32_bf16 v[6:9], v[230:233], v[198:201], v[6:9]
	v_mfma_f32_16x16x32_bf16 v[2:5], v[242:245], v[198:201], v[2:5]
	s_add_i32 s53, s53, 2
	s_add_u32 s34, s34, 0x100
	s_addc_u32 s35, s35, 0
	s_add_u32 s51, s51, 0x100
	s_addc_u32 s52, s52, 0
	s_cmp_gt_u32 s53, 13
	s_barrier
	s_cbranch_scc0 .LBB0_104

.LBB0_149:
	v_ashrrev_i32_e32 v0, 2, v164
	v_mul_hi_i32 v2, v0, s22
	v_lshrrev_b32_e32 v4, 31, v2
	v_add_u32_e32 v159, v2, v4
	v_mul_lo_u32 v2, v159, 6
	s_waitcnt vmcnt(0)
	v_sub_u32_e32 v130, v0, v2
	s_mul_i32 s3, s62, 6
	v_add_u32_e32 v4, s3, v130
	v_ashrrev_i32_e32 v5, 31, v4
	v_lshlrev_b64 v[4:5], 2, v[4:5]
	v_mov_b32_e32 v3, v202
	v_lshl_add_u64 v[6:7], s[66:67], 0, v[4:5]
	global_load_dword v178, v[6:7], off
	v_and_b32_e32 v158, 15, v3
	v_bfe_u32 v8, v3, 4, 2
	v_lshlrev_b32_e32 v2, 7, v159
	v_lshl_add_u64 v[4:5], s[68:69], 0, v[4:5]
	v_lshlrev_b32_e32 v98, 6, v130
	global_load_dword v179, v[4:5], off
	v_ashrrev_i32_e32 v99, 31, v98
	v_mov_b64_e32 v[4:5], s[16:17]
	v_lshlrev_b64 v[134:135], 1, v[98:99]
	v_lshlrev_b32_e32 v102, 4, v8
	v_mov_b32_e32 v103, v1
	v_and_or_b32 v168, v165, s23, v158
	v_or_b32_e32 v167, v168, v2
	v_or_b32_e32 v166, 16, v167
	v_lshlrev_b32_e32 v0, 3, v8
	v_mad_i64_i32 v[6:7], s[14:15], v167, s57, v[4:5]
	v_mad_i64_i32 v[8:9], s[14:15], v166, s57, v[4:5]
	v_lshl_add_u64 v[100:101], v[6:7], 0, v[134:135]
	v_lshl_add_u64 v[104:105], v[8:9], 0, v[134:135]
	v_lshl_add_u64 v[6:7], v[100:101], 0, v[102:103]
	v_lshl_add_u64 v[8:9], v[104:105], 0, v[102:103]
	v_lshl_add_u64 v[100:101], v[100:101], 0, v[0:1]
	v_lshl_add_u64 v[106:107], v[100:101], 0, s[52:53]
	v_lshl_add_u64 v[132:133], s[24:25], 0, v[102:103]
	v_or_b32_e32 v171, 16, v168
	v_ashrrev_i32_e32 v131, 31, v130
	v_mov_b32_e32 v173, v1
	v_mov_b32_e32 v175, v1
	v_mov_b32_e32 v164, v180
	v_add_u32_e32 v180, v181, v180
	v_lshlrev_b32_e32 v165, 5, v164
	v_lshlrev_b32_e32 v10, 1, v3
	v_and_b32_e32 v10, 24, v10
	v_and_b32_e32 v3, 3, v3
	v_or3_b32 v3, v3, v10, v2
	v_or_b32_e32 v18, 64, v3
	v_mad_i64_i32 v[18:19], s[14:15], v18, s57, v[4:5]
	v_lshl_add_u64 v[18:19], v[18:19], 0, v[134:135]
	v_lshl_add_u64 v[34:35], v[18:19], 0, v[102:103]
	v_or_b32_e32 v18, 0x44, v3
	v_mad_i64_i32 v[18:19], s[14:15], v18, s57, v[4:5]
	v_lshl_add_u64 v[18:19], v[18:19], 0, v[134:135]
	v_lshl_add_u64 v[36:37], v[18:19], 0, v[102:103]
	v_or_b32_e32 v18, 0x60, v3
	v_mad_i64_i32 v[18:19], s[14:15], v18, s57, v[4:5]
	v_mad_i64_i32 v[10:11], s[14:15], v3, s57, v[4:5]
	v_or_b32_e32 v12, 4, v3
	v_or_b32_e32 v14, 32, v3
	v_or_b32_e32 v16, 36, v3
	v_lshl_add_u64 v[18:19], v[18:19], 0, v[134:135]
	v_or_b32_e32 v3, 0x64, v3
	v_mad_i64_i32 v[12:13], s[14:15], v12, s57, v[4:5]
	v_mad_i64_i32 v[14:15], s[14:15], v14, s57, v[4:5]
	v_mad_i64_i32 v[16:17], s[14:15], v16, s57, v[4:5]
	v_lshl_add_u64 v[94:95], v[18:19], 0, v[102:103]
	v_mad_i64_i32 v[4:5], s[14:15], v3, s57, v[4:5]
	v_or_b32_e32 v18, v98, v158
	v_ashrrev_i32_e32 v3, 31, v2
	v_lshl_add_u64 v[2:3], v[2:3], 1, s[18:19]
	v_mul_lo_u32 v18, v18, s35
	v_lshl_add_u64 v[2:3], v[2:3], 0, v[102:103]
	v_ashrrev_i32_e32 v19, 31, v18
	v_lshl_add_u64 v[110:111], v[18:19], 1, v[2:3]
	v_add_co_u32_e32 v112, vcc, s42, v110
	v_lshl_add_u64 v[12:13], v[12:13], 0, v[134:135]
	s_nop 0
	v_addc_co_u32_e32 v113, vcc, 0, v111, vcc
	v_add_co_u32_e32 v152, vcc, s43, v110
	v_lshl_add_u64 v[10:11], v[10:11], 0, v[134:135]
	v_lshl_add_u64 v[12:13], v[12:13], 0, v[102:103]
	v_lshl_add_u64 v[14:15], v[14:15], 0, v[134:135]
	v_lshl_add_u64 v[16:17], v[16:17], 0, v[134:135]
	v_addc_co_u32_e32 v153, vcc, 0, v111, vcc
	v_lshl_add_u64 v[10:11], v[10:11], 0, v[102:103]
	v_lshl_add_u64 v[14:15], v[14:15], 0, v[102:103]
	v_lshl_add_u64 v[16:17], v[16:17], 0, v[102:103]
	v_lshl_add_u64 v[4:5], v[4:5], 0, v[134:135]
	global_load_dwordx4 v[66:69], v[12:13], off offset:3648
	global_load_dwordx4 v[70:73], v[12:13], off offset:3584
	global_load_dwordx4 v[74:77], v[10:11], off offset:3648
	global_load_dwordx4 v[78:81], v[10:11], off offset:3584
	global_load_dwordx4 v[18:21], v[8:9], off offset:2880
	global_load_dwordx4 v[26:29], v[8:9], off offset:2816
	global_load_dwordx4 v[22:25], v[6:7], off offset:2880
	global_load_dwordx4 v[30:33], v[6:7], off offset:2816
	global_load_dwordx4 v[114:117], v[36:37], off offset:3648
	global_load_dwordx4 v[118:121], v[36:37], off offset:3584
	global_load_dwordx4 v[122:125], v[34:35], off offset:3648
	global_load_dwordx4 v[126:129], v[34:35], off offset:3584
	s_nop 0
	global_load_dwordx4 v[34:37], v[16:17], off offset:3648
	global_load_dwordx4 v[38:41], v[16:17], off offset:3584
	global_load_dwordx4 v[42:45], v[14:15], off offset:3648
	global_load_dwordx4 v[46:49], v[14:15], off offset:3584
	v_add_co_u32_e32 v154, vcc, s50, v110
	v_lshl_add_u64 v[4:5], v[4:5], 0, v[102:103]
	s_nop 0
	v_addc_co_u32_e32 v155, vcc, 0, v111, vcc
	global_load_dwordx4 v[50:53], v[112:113], off
	global_load_dwordx4 v[54:57], v[152:153], off
	global_load_dwordx4 v[58:61], v[154:155], off
	global_load_dwordx4 v[62:65], v[110:111], off
	global_load_dwordx4 v[82:85], v[4:5], off offset:3648
	global_load_dwordx4 v[86:89], v[4:5], off offset:3584
	global_load_dwordx4 v[90:93], v[94:95], off offset:3648
	s_nop 0
	global_load_dwordx4 v[94:97], v[94:95], off offset:3584
	s_nop 0
	global_load_dwordx4 v[2:5], v[112:113], off offset:64
	global_load_dwordx4 v[6:9], v[152:153], off offset:64
	global_load_dwordx4 v[10:13], v[154:155], off offset:64
	global_load_dwordx4 v[14:17], v[110:111], off offset:64
	v_add_co_u32_e32 v100, vcc, s51, v100
	v_lshl_add_u64 v[98:99], v[98:99], 2, s[38:39]
	s_nop 0
	v_addc_co_u32_e32 v101, vcc, 0, v101, vcc
	v_lshl_add_u64 v[156:157], v[98:99], 0, v[102:103]
	v_or_b32_e32 v108, 7, v0
	s_waitcnt vmcnt(0)
	v_mul_f32_e32 v169, 0x3fb8aa3b, v178
	v_mul_f32_e32 v170, 0x3fb8aa3b, v179
	global_load_dwordx2 v[150:151], v[100:101], off offset:1024
	global_load_dwordx2 v[148:149], v[106:107], off offset:32
	global_load_dwordx2 v[146:147], v[106:107], off offset:64
	global_load_dwordx2 v[144:145], v[106:107], off offset:96
	v_lshl_add_u64 v[100:101], v[104:105], 0, v[0:1]
	v_lshl_add_u64 v[104:105], v[100:101], 0, s[52:53]
	v_add_co_u32_e32 v100, vcc, s51, v100
	v_or_b32_e32 v106, 5, v0
	s_nop 0
	v_addc_co_u32_e32 v101, vcc, 0, v101, vcc
	global_load_dwordx2 v[142:143], v[100:101], off offset:1024
	global_load_dwordx2 v[140:141], v[104:105], off offset:32
	global_load_dwordx2 v[138:139], v[104:105], off offset:64
	global_load_dwordx2 v[136:137], v[104:105], off offset:96
	v_mfma_f32_16x16x32_bf16 v[98:101], v[78:81], v[30:33], 0
	v_or_b32_e32 v107, 6, v0
	v_mfma_f32_16x16x32_bf16 v[78:81], v[78:81], v[26:29], 0
	v_mfma_f32_16x16x32_bf16 v[98:101], v[74:77], v[22:25], v[98:101]
	v_mfma_f32_16x16x32_bf16 v[74:77], v[74:77], v[18:21], v[78:81]
	v_mfma_f32_16x16x32_bf16 v[78:81], v[70:73], v[30:33], 0
	v_mfma_f32_16x16x32_bf16 v[70:73], v[70:73], v[26:29], 0
	v_mfma_f32_16x16x32_bf16 v[78:81], v[66:69], v[22:25], v[78:81]
	v_mfma_f32_16x16x32_bf16 v[66:69], v[66:69], v[18:21], v[70:73]
	s_nop 5
	v_sub_u32_e32 v71, v168, v0
	v_cvt_f32_u32_e32 v72, v71
	v_cmp_lt_i32_e32 vcc, -1, v71
	v_or_b32_e32 v70, 4, v0
	v_mul_f32_e32 v72, v169, v72
	v_exp_f32_e32 v72, v72
	s_nop 0
	v_cndmask_b32_e32 v72, 0, v72, vcc
	v_cmp_gt_i32_e32 vcc, 1, v71
	v_sub_u32_e32 v71, 0, v71
	v_cvt_f32_u32_e32 v71, v71
	v_mul_f32_e32 v71, v170, v71
	v_exp_f32_e32 v71, v71
	s_nop 0
	v_cndmask_b32_e32 v71, 0, v71, vcc
	v_add_f32_e32 v71, v72, v71
	v_or_b32_e32 v72, 1, v0
	v_sub_u32_e32 v73, v168, v72
	v_mul_f32_e32 v71, v71, v98
	v_cvt_f32_u32_e32 v98, v73
	v_cmp_lt_i32_e32 vcc, -1, v73
	v_sub_u32_e32 v72, v171, v72
	v_mul_f32_e32 v98, v169, v98
	v_exp_f32_e32 v98, v98
	s_nop 0
	v_cndmask_b32_e32 v98, 0, v98, vcc
	v_cmp_gt_i32_e32 vcc, 1, v73
	v_sub_u32_e32 v73, 0, v73
	v_cvt_f32_u32_e32 v73, v73
	v_mul_f32_e32 v73, v170, v73
	v_exp_f32_e32 v73, v73
	s_nop 0
	v_cndmask_b32_e32 v73, 0, v73, vcc
	v_add_f32_e32 v73, v98, v73
	v_or_b32_e32 v98, 2, v0
	v_mul_f32_e32 v73, v73, v99
	v_sub_u32_e32 v99, v168, v98
	v_cvt_f32_u32_e32 v102, v99
	v_cmp_lt_i32_e32 vcc, -1, v99
	v_mul_f32_e32 v102, v169, v102
	v_exp_f32_e32 v102, v102
	s_nop 0
	v_cndmask_b32_e32 v102, 0, v102, vcc
	v_cmp_gt_i32_e32 vcc, 1, v99
	v_sub_u32_e32 v99, 0, v99
	v_cvt_f32_u32_e32 v99, v99
	v_mul_f32_e32 v99, v170, v99
	v_exp_f32_e32 v99, v99
	s_nop 0
	v_cndmask_b32_e32 v99, 0, v99, vcc
	v_add_f32_e32 v99, v102, v99
	v_mul_f32_e32 v99, v99, v100
	v_or_b32_e32 v100, 3, v0
	v_sub_u32_e32 v102, v168, v100
	v_cvt_f32_u32_e32 v103, v102
	v_cmp_lt_i32_e32 vcc, -1, v102
	v_mul_f32_e32 v103, v169, v103
	v_exp_f32_e32 v103, v103
	s_nop 0
	v_cndmask_b32_e32 v103, 0, v103, vcc
	v_cmp_gt_i32_e32 vcc, 1, v102
	v_sub_u32_e32 v102, 0, v102
	v_cvt_f32_u32_e32 v102, v102
	v_mul_f32_e32 v102, v170, v102
	v_exp_f32_e32 v102, v102
	s_nop 0
	v_cndmask_b32_e32 v102, 0, v102, vcc
	v_add_f32_e32 v102, v103, v102
	v_mul_f32_e32 v101, v102, v101
	v_sub_u32_e32 v102, v168, v70
	v_cvt_f32_u32_e32 v103, v102
	v_cmp_lt_i32_e32 vcc, -1, v102
	v_sub_u32_e32 v70, v171, v70
	v_mul_f32_e32 v103, v169, v103
	v_exp_f32_e32 v103, v103
	s_nop 0
	v_cndmask_b32_e32 v103, 0, v103, vcc
	v_cmp_gt_i32_e32 vcc, 1, v102
	v_sub_u32_e32 v102, 0, v102
	v_cvt_f32_u32_e32 v102, v102
	v_mul_f32_e32 v102, v170, v102
	v_exp_f32_e32 v102, v102
	s_nop 0
	v_cndmask_b32_e32 v102, 0, v102, vcc
	v_add_f32_e32 v102, v103, v102
	v_mul_f32_e32 v78, v102, v78
	v_sub_u32_e32 v102, v168, v106
	v_cvt_f32_u32_e32 v103, v102
	v_cmp_lt_i32_e32 vcc, -1, v102
	v_mul_f32_e32 v103, v169, v103
	v_exp_f32_e32 v103, v103
	s_nop 0
	v_cndmask_b32_e32 v103, 0, v103, vcc
	v_cmp_gt_i32_e32 vcc, 1, v102
	v_sub_u32_e32 v102, 0, v102
	v_cvt_f32_u32_e32 v102, v102
	v_mul_f32_e32 v102, v170, v102
	v_exp_f32_e32 v102, v102
	s_nop 0
	v_cndmask_b32_e32 v102, 0, v102, vcc
	v_add_f32_e32 v102, v103, v102
	v_mul_f32_e32 v79, v102, v79
	v_sub_u32_e32 v102, v168, v107
	v_cvt_f32_u32_e32 v103, v102
	v_cmp_lt_i32_e32 vcc, -1, v102
	v_cvt_pk_bf16_f32 v104, v78, v79
	v_mul_f32_e32 v103, v169, v103
	v_exp_f32_e32 v103, v103
	s_nop 0
	v_cndmask_b32_e32 v103, 0, v103, vcc
	v_cmp_gt_i32_e32 vcc, 1, v102
	v_sub_u32_e32 v102, 0, v102
	v_cvt_f32_u32_e32 v102, v102
	v_mul_f32_e32 v102, v170, v102
	v_exp_f32_e32 v102, v102
	s_nop 0
	v_cndmask_b32_e32 v102, 0, v102, vcc
	v_add_f32_e32 v102, v103, v102
	v_mul_f32_e32 v80, v102, v80
	v_sub_u32_e32 v102, v168, v108
	v_cvt_f32_u32_e32 v103, v102
	v_cmp_lt_i32_e32 vcc, -1, v102
	v_mul_f32_e32 v103, v169, v103
	v_exp_f32_e32 v103, v103
	s_nop 0
	v_cndmask_b32_e32 v103, 0, v103, vcc
	v_cmp_gt_i32_e32 vcc, 1, v102
	v_sub_u32_e32 v102, 0, v102
	v_cvt_f32_u32_e32 v102, v102
	v_mul_f32_e32 v102, v170, v102
	v_exp_f32_e32 v102, v102
	s_nop 0
	v_cndmask_b32_e32 v102, 0, v102, vcc
	v_add_f32_e32 v102, v103, v102
	v_mul_f32_e32 v81, v102, v81
	v_cvt_pk_bf16_f32 v102, v71, v73
	v_sub_u32_e32 v71, v171, v0
	v_cvt_f32_u32_e32 v73, v71
	v_cmp_lt_i32_e32 vcc, -1, v71
	v_cvt_pk_bf16_f32 v103, v99, v101
	v_cvt_pk_bf16_f32 v105, v80, v81
	v_mul_f32_e32 v73, v169, v73
	v_exp_f32_e32 v73, v73
	v_mfma_f32_16x16x32_bf16 v[78:81], v[54:57], v[102:105], 0
	v_cndmask_b32_e32 v73, 0, v73, vcc
	v_cmp_gt_i32_e32 vcc, 1, v71
	v_sub_u32_e32 v71, 0, v71
	v_cvt_f32_u32_e32 v71, v71
	v_mul_f32_e32 v71, v170, v71
	v_exp_f32_e32 v71, v71
	s_nop 0
	v_cndmask_b32_e32 v71, 0, v71, vcc
	v_add_f32_e32 v71, v73, v71
	v_cvt_f32_u32_e32 v73, v72
	v_cmp_lt_i32_e32 vcc, -1, v72
	v_mul_f32_e32 v71, v71, v74
	v_mul_f32_e32 v73, v169, v73
	v_exp_f32_e32 v73, v73
	s_nop 0
	v_cndmask_b32_e32 v73, 0, v73, vcc
	v_cmp_gt_i32_e32 vcc, 1, v72
	v_sub_u32_e32 v72, 0, v72
	v_cvt_f32_u32_e32 v72, v72
	v_mul_f32_e32 v72, v170, v72
	v_exp_f32_e32 v72, v72
	s_nop 0
	v_cndmask_b32_e32 v72, 0, v72, vcc
	v_add_f32_e32 v72, v73, v72
	v_sub_u32_e32 v73, v171, v98
	v_cvt_f32_u32_e32 v74, v73
	v_cmp_lt_i32_e32 vcc, -1, v73
	v_mul_f32_e32 v72, v72, v75
	v_mul_f32_e32 v74, v169, v74
	v_exp_f32_e32 v74, v74
	s_nop 0
	v_cndmask_b32_e32 v74, 0, v74, vcc
	v_cmp_gt_i32_e32 vcc, 1, v73
	v_sub_u32_e32 v73, 0, v73
	v_cvt_f32_u32_e32 v73, v73
	v_mul_f32_e32 v73, v170, v73
	v_exp_f32_e32 v73, v73
	s_nop 0
	v_cndmask_b32_e32 v73, 0, v73, vcc
	v_add_f32_e32 v73, v74, v73
	v_sub_u32_e32 v74, v171, v100
	v_cvt_f32_u32_e32 v75, v74
	v_cmp_lt_i32_e32 vcc, -1, v74
	v_mul_f32_e32 v73, v73, v76
	v_mul_f32_e32 v75, v169, v75
	v_exp_f32_e32 v75, v75
	s_nop 0
	v_cndmask_b32_e32 v75, 0, v75, vcc
	v_cmp_gt_i32_e32 vcc, 1, v74
	v_sub_u32_e32 v74, 0, v74
	v_cvt_f32_u32_e32 v74, v74
	v_mul_f32_e32 v74, v170, v74
	v_exp_f32_e32 v74, v74
	s_nop 0
	v_cndmask_b32_e32 v74, 0, v74, vcc
	v_add_f32_e32 v74, v75, v74
	v_cvt_f32_u32_e32 v75, v70
	v_cmp_lt_i32_e32 vcc, -1, v70
	v_mul_f32_e32 v74, v74, v77
	v_mul_f32_e32 v75, v169, v75
	v_exp_f32_e32 v75, v75
	s_nop 0
	v_cndmask_b32_e32 v75, 0, v75, vcc
	v_cmp_gt_i32_e32 vcc, 1, v70
	v_sub_u32_e32 v70, 0, v70
	v_cvt_f32_u32_e32 v70, v70
	v_mul_f32_e32 v70, v170, v70
	v_exp_f32_e32 v70, v70
	s_nop 0
	v_cndmask_b32_e32 v70, 0, v70, vcc
	v_add_f32_e32 v70, v75, v70
	v_mul_f32_e32 v66, v70, v66
	v_sub_u32_e32 v70, v171, v106
	v_cvt_f32_u32_e32 v75, v70
	v_cmp_lt_i32_e32 vcc, -1, v70
	v_cvt_pk_bf16_f32 v106, v71, v72
	v_mul_f32_e32 v75, v169, v75
	v_exp_f32_e32 v75, v75
	s_nop 0
	v_cndmask_b32_e32 v75, 0, v75, vcc
	v_cmp_gt_i32_e32 vcc, 1, v70
	v_sub_u32_e32 v70, 0, v70
	v_cvt_f32_u32_e32 v70, v70
	v_mul_f32_e32 v70, v170, v70
	v_exp_f32_e32 v70, v70
	s_nop 0
	v_cndmask_b32_e32 v70, 0, v70, vcc
	v_add_f32_e32 v70, v75, v70
	v_mul_f32_e32 v67, v70, v67
	v_sub_u32_e32 v70, v171, v107
	v_cvt_f32_u32_e32 v75, v70
	v_cmp_lt_i32_e32 vcc, -1, v70
	v_cvt_pk_bf16_f32 v107, v73, v74
	v_mul_f32_e32 v75, v169, v75
	v_exp_f32_e32 v75, v75
	s_nop 0
	v_cndmask_b32_e32 v75, 0, v75, vcc
	v_cmp_gt_i32_e32 vcc, 1, v70
	v_sub_u32_e32 v70, 0, v70
	v_cvt_f32_u32_e32 v70, v70
	v_mul_f32_e32 v70, v170, v70
	v_exp_f32_e32 v70, v70
	s_nop 0
	v_cndmask_b32_e32 v70, 0, v70, vcc
	v_add_f32_e32 v70, v75, v70
	v_mul_f32_e32 v68, v70, v68
	v_sub_u32_e32 v70, v171, v108
	v_cvt_f32_u32_e32 v75, v70
	v_cmp_lt_i32_e32 vcc, -1, v70
	v_cvt_pk_bf16_f32 v108, v66, v67
	v_mul_f32_e32 v75, v169, v75
	v_exp_f32_e32 v75, v75
	s_nop 0
	v_cndmask_b32_e32 v75, 0, v75, vcc
	v_cmp_gt_i32_e32 vcc, 1, v70
	v_sub_u32_e32 v70, 0, v70
	v_cvt_f32_u32_e32 v70, v70
	v_mul_f32_e32 v70, v170, v70
	v_exp_f32_e32 v70, v70
	s_nop 0
	v_cndmask_b32_e32 v70, 0, v70, vcc
	v_add_f32_e32 v70, v75, v70
	v_mul_f32_e32 v69, v70, v69
	v_cvt_pk_bf16_f32 v109, v68, v69
	v_mfma_f32_16x16x32_bf16 v[66:69], v[62:65], v[102:105], 0
	v_mfma_f32_16x16x32_bf16 v[62:65], v[62:65], v[106:109], 0
	v_mfma_f32_16x16x32_bf16 v[70:73], v[58:61], v[102:105], 0
	v_mfma_f32_16x16x32_bf16 v[74:77], v[58:61], v[106:109], 0
	v_mfma_f32_16x16x32_bf16 v[98:101], v[54:57], v[106:109], 0
	v_or_b32_e32 v55, 32, v0
	v_or_b32_e32 v54, 36, v0
	s_nop 0
	v_mfma_f32_16x16x32_bf16 v[102:105], v[50:53], v[102:105], 0
	v_mfma_f32_16x16x32_bf16 v[106:109], v[50:53], v[106:109], 0
	v_mfma_f32_16x16x32_bf16 v[50:53], v[46:49], v[30:33], 0
	v_mfma_f32_16x16x32_bf16 v[46:49], v[46:49], v[26:29], 0
	v_mfma_f32_16x16x32_bf16 v[50:53], v[42:45], v[22:25], v[50:53]
	v_mfma_f32_16x16x32_bf16 v[42:45], v[42:45], v[18:21], v[46:49]
	v_mfma_f32_16x16x32_bf16 v[46:49], v[38:41], v[30:33], 0
	v_mfma_f32_16x16x32_bf16 v[38:41], v[38:41], v[26:29], 0
	v_mfma_f32_16x16x32_bf16 v[46:49], v[34:37], v[22:25], v[46:49]
	v_mfma_f32_16x16x32_bf16 v[34:37], v[34:37], v[18:21], v[38:41]
	s_nop 5
	v_sub_u32_e32 v38, v168, v55
	v_cvt_f32_u32_e32 v39, v38
	v_cmp_lt_i32_e32 vcc, -1, v38
	v_mul_f32_e32 v39, v169, v39
	v_exp_f32_e32 v39, v39
	s_nop 0
	v_cndmask_b32_e32 v39, 0, v39, vcc
	v_cmp_gt_i32_e32 vcc, 1, v38
	v_sub_u32_e32 v38, 0, v38
	v_cvt_f32_u32_e32 v38, v38
	v_mul_f32_e32 v38, v170, v38
	v_exp_f32_e32 v38, v38
	s_nop 0
	v_cndmask_b32_e32 v38, 0, v38, vcc
	v_add_f32_e32 v38, v39, v38
	v_mul_f32_e32 v38, v38, v50
	v_or_b32_e32 v50, 33, v0
	v_sub_u32_e32 v39, v168, v50
	v_cvt_f32_u32_e32 v40, v39
	v_cmp_lt_i32_e32 vcc, -1, v39
	v_mul_f32_e32 v40, v169, v40
	v_exp_f32_e32 v40, v40
	s_nop 0
	v_cndmask_b32_e32 v40, 0, v40, vcc
	v_cmp_gt_i32_e32 vcc, 1, v39
	v_sub_u32_e32 v39, 0, v39
	v_cvt_f32_u32_e32 v39, v39
	v_mul_f32_e32 v39, v170, v39
	v_exp_f32_e32 v39, v39
	s_nop 0
	v_cndmask_b32_e32 v39, 0, v39, vcc
	v_add_f32_e32 v39, v40, v39
	v_mul_f32_e32 v39, v39, v51
	v_or_b32_e32 v51, 34, v0
	v_sub_u32_e32 v40, v168, v51
	v_cvt_f32_u32_e32 v41, v40
	v_cmp_lt_i32_e32 vcc, -1, v40
	v_cvt_pk_bf16_f32 v38, v38, v39
	v_mul_f32_e32 v41, v169, v41
	v_exp_f32_e32 v41, v41
	s_nop 0
	v_cndmask_b32_e32 v41, 0, v41, vcc
	v_cmp_gt_i32_e32 vcc, 1, v40
	v_sub_u32_e32 v40, 0, v40
	v_cvt_f32_u32_e32 v40, v40
	v_mul_f32_e32 v40, v170, v40
	v_exp_f32_e32 v40, v40
	s_nop 0
	v_cndmask_b32_e32 v40, 0, v40, vcc
	v_add_f32_e32 v40, v41, v40
	v_mul_f32_e32 v40, v40, v52
	v_or_b32_e32 v52, 35, v0
	v_sub_u32_e32 v41, v168, v52
	v_cvt_f32_u32_e32 v56, v41
	v_cmp_lt_i32_e32 vcc, -1, v41
	v_mul_f32_e32 v56, v169, v56
	v_exp_f32_e32 v56, v56
	s_nop 0
	v_cndmask_b32_e32 v56, 0, v56, vcc
	v_cmp_gt_i32_e32 vcc, 1, v41
	v_sub_u32_e32 v41, 0, v41
	v_cvt_f32_u32_e32 v41, v41
	v_mul_f32_e32 v41, v170, v41
	v_exp_f32_e32 v41, v41
	s_nop 0
	v_cndmask_b32_e32 v41, 0, v41, vcc
	v_add_f32_e32 v41, v56, v41
	v_mul_f32_e32 v41, v41, v53
	v_sub_u32_e32 v53, v168, v54
	v_cvt_f32_u32_e32 v56, v53
	v_cmp_lt_i32_e32 vcc, -1, v53
	v_cvt_pk_bf16_f32 v39, v40, v41
	v_mul_f32_e32 v56, v169, v56
	v_exp_f32_e32 v56, v56
	s_nop 0
	v_cndmask_b32_e32 v56, 0, v56, vcc
	v_cmp_gt_i32_e32 vcc, 1, v53
	v_sub_u32_e32 v53, 0, v53
	v_cvt_f32_u32_e32 v53, v53
	v_mul_f32_e32 v53, v170, v53
	v_exp_f32_e32 v53, v53
	s_nop 0
	v_cndmask_b32_e32 v53, 0, v53, vcc
	v_add_f32_e32 v53, v56, v53
	v_mul_f32_e32 v46, v53, v46
	v_or_b32_e32 v53, 37, v0
	v_sub_u32_e32 v56, v168, v53
	v_cvt_f32_u32_e32 v57, v56
	v_cmp_lt_i32_e32 vcc, -1, v56
	v_mul_f32_e32 v57, v169, v57
	v_exp_f32_e32 v57, v57
	s_nop 0
	v_cndmask_b32_e32 v57, 0, v57, vcc
	v_cmp_gt_i32_e32 vcc, 1, v56
	v_sub_u32_e32 v56, 0, v56
	v_cvt_f32_u32_e32 v56, v56
	v_mul_f32_e32 v56, v170, v56
	v_exp_f32_e32 v56, v56
	s_nop 0
	v_cndmask_b32_e32 v56, 0, v56, vcc
	v_add_f32_e32 v56, v57, v56
	v_mul_f32_e32 v47, v56, v47
	v_or_b32_e32 v56, 38, v0
	v_sub_u32_e32 v57, v168, v56
	v_cvt_f32_u32_e32 v58, v57
	v_cmp_lt_i32_e32 vcc, -1, v57
	v_cvt_pk_bf16_f32 v40, v46, v47
	v_sub_u32_e32 v46, v171, v55
	v_mul_f32_e32 v58, v169, v58
	v_exp_f32_e32 v58, v58
	v_cvt_f32_u32_e32 v47, v46
	v_cndmask_b32_e32 v58, 0, v58, vcc
	v_cmp_gt_i32_e32 vcc, 1, v57
	v_sub_u32_e32 v57, 0, v57
	v_cvt_f32_u32_e32 v57, v57
	v_mul_f32_e32 v47, v169, v47
	v_exp_f32_e32 v47, v47
	v_mul_f32_e32 v57, v170, v57
	v_exp_f32_e32 v57, v57
	s_nop 0
	v_cndmask_b32_e32 v57, 0, v57, vcc
	v_add_f32_e32 v57, v58, v57
	v_mul_f32_e32 v48, v57, v48
	v_or_b32_e32 v57, 39, v0
	v_sub_u32_e32 v58, v168, v57
	v_cvt_f32_u32_e32 v59, v58
	v_cmp_lt_i32_e32 vcc, -1, v58
	v_mul_f32_e32 v59, v169, v59
	v_exp_f32_e32 v59, v59
	s_nop 0
	v_cndmask_b32_e32 v59, 0, v59, vcc
	v_cmp_gt_i32_e32 vcc, 1, v58
	v_sub_u32_e32 v58, 0, v58
	v_cvt_f32_u32_e32 v58, v58
	v_mul_f32_e32 v58, v170, v58
	v_exp_f32_e32 v58, v58
	s_nop 0
	v_cndmask_b32_e32 v58, 0, v58, vcc
	v_cmp_lt_i32_e32 vcc, -1, v46
	v_add_f32_e32 v58, v59, v58
	v_mul_f32_e32 v49, v58, v49
	v_cndmask_b32_e32 v47, 0, v47, vcc
	v_cmp_gt_i32_e32 vcc, 1, v46
	v_sub_u32_e32 v46, 0, v46
	v_cvt_f32_u32_e32 v46, v46
	v_cvt_pk_bf16_f32 v41, v48, v49
	v_mul_f32_e32 v46, v170, v46
	v_exp_f32_e32 v46, v46
	v_mfma_f32_16x16x32_bf16 v[58:61], v[10:13], v[38:41], v[70:73]
	v_cndmask_b32_e32 v46, 0, v46, vcc
	v_add_f32_e32 v46, v47, v46
	v_mul_f32_e32 v42, v46, v42
	v_sub_u32_e32 v46, v171, v50
	v_cvt_f32_u32_e32 v47, v46
	v_cmp_lt_i32_e32 vcc, -1, v46
	v_mul_f32_e32 v47, v169, v47
	v_exp_f32_e32 v47, v47
	s_nop 0
	v_cndmask_b32_e32 v47, 0, v47, vcc
	v_cmp_gt_i32_e32 vcc, 1, v46
	v_sub_u32_e32 v46, 0, v46
	v_cvt_f32_u32_e32 v46, v46
	v_mul_f32_e32 v46, v170, v46
	v_exp_f32_e32 v46, v46
	s_nop 0
	v_cndmask_b32_e32 v46, 0, v46, vcc
	v_add_f32_e32 v46, v47, v46
	v_mul_f32_e32 v43, v46, v43
	v_sub_u32_e32 v46, v171, v51
	v_cvt_f32_u32_e32 v47, v46
	v_cmp_lt_i32_e32 vcc, -1, v46
	v_mul_f32_e32 v47, v169, v47
	v_exp_f32_e32 v47, v47
	s_nop 0
	v_cndmask_b32_e32 v47, 0, v47, vcc
	v_cmp_gt_i32_e32 vcc, 1, v46
	v_sub_u32_e32 v46, 0, v46
	v_cvt_f32_u32_e32 v46, v46
	v_mul_f32_e32 v46, v170, v46
	v_exp_f32_e32 v46, v46
	s_nop 0
	v_cndmask_b32_e32 v46, 0, v46, vcc
	v_add_f32_e32 v46, v47, v46
	v_mul_f32_e32 v44, v46, v44
	v_sub_u32_e32 v46, v171, v52
	v_cvt_f32_u32_e32 v47, v46
	v_cmp_lt_i32_e32 vcc, -1, v46
	v_mul_f32_e32 v47, v169, v47
	v_exp_f32_e32 v47, v47
	s_nop 0
	v_cndmask_b32_e32 v47, 0, v47, vcc
	v_cmp_gt_i32_e32 vcc, 1, v46
	v_sub_u32_e32 v46, 0, v46
	v_cvt_f32_u32_e32 v46, v46
	v_mul_f32_e32 v46, v170, v46
	v_exp_f32_e32 v46, v46
	s_nop 0
	v_cndmask_b32_e32 v46, 0, v46, vcc
	v_add_f32_e32 v46, v47, v46
	v_mul_f32_e32 v45, v46, v45
	v_sub_u32_e32 v46, v171, v54
	v_cvt_f32_u32_e32 v47, v46
	v_cmp_lt_i32_e32 vcc, -1, v46
	v_mul_f32_e32 v47, v169, v47
	v_exp_f32_e32 v47, v47
	s_nop 0
	v_cndmask_b32_e32 v47, 0, v47, vcc
	v_cmp_gt_i32_e32 vcc, 1, v46
	v_sub_u32_e32 v46, 0, v46
	v_cvt_f32_u32_e32 v46, v46
	v_mul_f32_e32 v46, v170, v46
	v_exp_f32_e32 v46, v46
	s_nop 0
	v_cndmask_b32_e32 v46, 0, v46, vcc
	v_add_f32_e32 v46, v47, v46
	v_mul_f32_e32 v46, v46, v34
	v_sub_u32_e32 v34, v171, v53
	v_cvt_f32_u32_e32 v47, v34
	v_cmp_lt_i32_e32 vcc, -1, v34
	v_mfma_f32_16x16x32_bf16 v[50:53], v[14:17], v[38:41], v[66:69]
	v_mul_f32_e32 v47, v169, v47
	v_exp_f32_e32 v47, v47
	v_mfma_f32_16x16x32_bf16 v[66:69], v[6:9], v[38:41], v[78:81]
	v_cndmask_b32_e32 v47, 0, v47, vcc
	v_cmp_gt_i32_e32 vcc, 1, v34
	v_sub_u32_e32 v34, 0, v34
	v_cvt_f32_u32_e32 v34, v34
	v_mul_f32_e32 v34, v170, v34
	v_exp_f32_e32 v34, v34
	s_nop 0
	v_cndmask_b32_e32 v34, 0, v34, vcc
	v_add_f32_e32 v34, v47, v34
	v_mul_f32_e32 v47, v34, v35
	v_sub_u32_e32 v34, v171, v56
	v_cvt_f32_u32_e32 v35, v34
	v_cmp_lt_i32_e32 vcc, -1, v34
	v_mul_f32_e32 v35, v169, v35
	v_exp_f32_e32 v35, v35
	s_nop 0
	v_cndmask_b32_e32 v35, 0, v35, vcc
	v_cmp_gt_i32_e32 vcc, 1, v34
	v_sub_u32_e32 v34, 0, v34
	v_cvt_f32_u32_e32 v34, v34
	v_mul_f32_e32 v34, v170, v34
	v_exp_f32_e32 v34, v34
	s_nop 0
	v_cndmask_b32_e32 v34, 0, v34, vcc
	v_add_f32_e32 v34, v35, v34
	v_mul_f32_e32 v48, v34, v36
	v_sub_u32_e32 v34, v171, v57
	v_cvt_f32_u32_e32 v35, v34
	v_cmp_lt_i32_e32 vcc, -1, v34
	v_cvt_pk_bf16_f32 v36, v46, v47
	v_mul_f32_e32 v35, v169, v35
	v_exp_f32_e32 v35, v35
	s_nop 0
	v_cndmask_b32_e32 v35, 0, v35, vcc
	v_cmp_gt_i32_e32 vcc, 1, v34
	v_sub_u32_e32 v34, 0, v34
	v_cvt_f32_u32_e32 v34, v34
	v_mul_f32_e32 v34, v170, v34
	v_exp_f32_e32 v34, v34
	s_nop 0
	v_cndmask_b32_e32 v34, 0, v34, vcc
	v_add_f32_e32 v34, v35, v34
	v_mul_f32_e32 v37, v34, v37
	v_cvt_pk_bf16_f32 v34, v42, v43
	v_cvt_pk_bf16_f32 v35, v44, v45
	v_cvt_pk_bf16_f32 v37, v48, v37
	s_nop 1
	v_mfma_f32_16x16x32_bf16 v[54:57], v[14:17], v[34:37], v[62:65]
	v_mfma_f32_16x16x32_bf16 v[62:65], v[10:13], v[34:37], v[74:77]
	v_mfma_f32_16x16x32_bf16 v[70:73], v[6:9], v[34:37], v[98:101]
	v_mfma_f32_16x16x32_bf16 v[74:77], v[2:5], v[38:41], v[102:105]
	v_mfma_f32_16x16x32_bf16 v[78:81], v[2:5], v[34:37], v[106:109]
	global_load_dwordx4 v[34:37], v[112:113], off offset:192
	global_load_dwordx4 v[38:41], v[152:153], off offset:192
	global_load_dwordx4 v[42:45], v[154:155], off offset:192
	global_load_dwordx4 v[98:101], v[112:113], off offset:128
	global_load_dwordx4 v[102:105], v[152:153], off offset:128
	global_load_dwordx4 v[106:109], v[154:155], off offset:128
	global_load_dwordx4 v[46:49], v[110:111], off offset:192
	s_nop 0
	global_load_dwordx4 v[110:113], v[110:111], off offset:128
	s_nop 0
	global_load_dwordx4 v[2:5], v[156:157], off offset:192
	global_load_dwordx4 v[6:9], v[156:157], off offset:128
	global_load_dwordx4 v[10:13], v[156:157], off offset:64
	global_load_dwordx4 v[14:17], v[156:157], off
	v_mul_lo_u32 v154, v159, 12
	v_ashrrev_i32_e32 v155, 31, v154
	v_lshl_add_u64 v[152:153], v[154:155], 0, v[130:131]
	v_add_u32_e32 v154, 6, v154
	v_ashrrev_i32_e32 v155, 31, v154
	v_lshl_add_u64 v[130:131], v[154:155], 0, v[130:131]
	v_lshlrev_b64 v[152:153], 13, v[152:153]
	v_lshlrev_b32_e32 v156, 7, v158
	v_lshlrev_b64 v[130:131], 13, v[130:131]
	v_lshl_add_u64 v[160:161], v[132:133], 0, v[152:153]
	v_mov_b32_e32 v157, v1
	v_or_b32_e32 v172, 0x1000, v156
	v_or_b32_e32 v174, 0x1800, v156
	v_lshl_add_u64 v[130:131], v[132:133], 0, v[130:131]
	v_lshl_add_u64 v[152:153], v[160:161], 0, v[156:157]
	v_lshl_add_u64 v[158:159], v[160:161], 0, v[172:173]
	v_lshl_add_u64 v[162:163], v[160:161], 0, v[174:175]
	v_lshl_add_u64 v[154:155], v[130:131], 0, v[156:157]
	v_lshl_add_u64 v[156:157], v[130:131], 0, v[172:173]
	v_lshl_add_u64 v[160:161], v[130:131], 0, v[174:175]
	v_mfma_f32_16x16x32_bf16 v[130:133], v[126:129], v[30:33], 0
	v_or_b32_e32 v173, 64, v0
	v_or_b32_e32 v172, 0x44, v0
	s_waitcnt vmcnt(0)
	v_mfma_f32_16x16x32_bf16 v[126:129], v[126:129], v[26:29], 0
	v_mfma_f32_16x16x32_bf16 v[130:133], v[122:125], v[22:25], v[130:133]
	v_mfma_f32_16x16x32_bf16 v[122:125], v[122:125], v[18:21], v[126:129]
	v_mfma_f32_16x16x32_bf16 v[126:129], v[118:121], v[30:33], 0
	v_mfma_f32_16x16x32_bf16 v[118:121], v[118:121], v[26:29], 0
	v_mfma_f32_16x16x32_bf16 v[126:129], v[114:117], v[22:25], v[126:129]
	v_mfma_f32_16x16x32_bf16 v[114:117], v[114:117], v[18:21], v[118:121]
	s_nop 5
	v_sub_u32_e32 v118, v168, v173
	v_cvt_f32_u32_e32 v119, v118
	v_cmp_lt_i32_e32 vcc, -1, v118
	v_mul_f32_e32 v119, v169, v119
	v_exp_f32_e32 v119, v119
	s_nop 0
	v_cndmask_b32_e32 v119, 0, v119, vcc
	v_cmp_gt_i32_e32 vcc, 1, v118
	v_sub_u32_e32 v118, 0, v118
	v_cvt_f32_u32_e32 v118, v118
	v_mul_f32_e32 v118, v170, v118
	v_exp_f32_e32 v118, v118
	s_nop 0
	v_cndmask_b32_e32 v118, 0, v118, vcc
	v_add_f32_e32 v118, v119, v118
	v_mul_f32_e32 v118, v118, v130
	v_or_b32_e32 v130, 0x41, v0
	v_sub_u32_e32 v119, v168, v130
	v_cvt_f32_u32_e32 v120, v119
	v_cmp_lt_i32_e32 vcc, -1, v119
	v_mul_f32_e32 v120, v169, v120
	v_exp_f32_e32 v120, v120
	s_nop 0
	v_cndmask_b32_e32 v120, 0, v120, vcc
	v_cmp_gt_i32_e32 vcc, 1, v119
	v_sub_u32_e32 v119, 0, v119
	v_cvt_f32_u32_e32 v119, v119
	v_mul_f32_e32 v119, v170, v119
	v_exp_f32_e32 v119, v119
	s_nop 0
	v_cndmask_b32_e32 v119, 0, v119, vcc
	v_add_f32_e32 v119, v120, v119
	v_mul_f32_e32 v119, v119, v131
	v_or_b32_e32 v131, 0x42, v0
	v_sub_u32_e32 v120, v168, v131
	v_cvt_f32_u32_e32 v121, v120
	v_cmp_lt_i32_e32 vcc, -1, v120
	v_cvt_pk_bf16_f32 v118, v118, v119
	v_mul_f32_e32 v121, v169, v121
	v_exp_f32_e32 v121, v121
	s_nop 0
	v_cndmask_b32_e32 v121, 0, v121, vcc
	v_cmp_gt_i32_e32 vcc, 1, v120
	v_sub_u32_e32 v120, 0, v120
	v_cvt_f32_u32_e32 v120, v120
	v_mul_f32_e32 v120, v170, v120
	v_exp_f32_e32 v120, v120
	s_nop 0
	v_cndmask_b32_e32 v120, 0, v120, vcc
	v_add_f32_e32 v120, v121, v120
	v_mul_f32_e32 v120, v120, v132
	v_or_b32_e32 v132, 0x43, v0
	v_sub_u32_e32 v121, v168, v132
	v_cvt_f32_u32_e32 v174, v121
	v_cmp_lt_i32_e32 vcc, -1, v121
	v_mul_f32_e32 v174, v169, v174
	v_exp_f32_e32 v174, v174
	s_nop 0
	v_cndmask_b32_e32 v174, 0, v174, vcc
	v_cmp_gt_i32_e32 vcc, 1, v121
	v_sub_u32_e32 v121, 0, v121
	v_cvt_f32_u32_e32 v121, v121
	v_mul_f32_e32 v121, v170, v121
	v_exp_f32_e32 v121, v121
	s_nop 0
	v_cndmask_b32_e32 v121, 0, v121, vcc
	v_add_f32_e32 v121, v174, v121
	v_mul_f32_e32 v121, v121, v133
	v_sub_u32_e32 v133, v168, v172
	v_cvt_f32_u32_e32 v174, v133
	v_cmp_lt_i32_e32 vcc, -1, v133
	v_cvt_pk_bf16_f32 v119, v120, v121
	v_mul_f32_e32 v174, v169, v174
	v_exp_f32_e32 v174, v174
	s_nop 0
	v_cndmask_b32_e32 v174, 0, v174, vcc
	v_cmp_gt_i32_e32 vcc, 1, v133
	v_sub_u32_e32 v133, 0, v133
	v_cvt_f32_u32_e32 v133, v133
	v_mul_f32_e32 v133, v170, v133
	v_exp_f32_e32 v133, v133
	s_nop 0
	v_cndmask_b32_e32 v133, 0, v133, vcc
	v_add_f32_e32 v133, v174, v133
	v_mul_f32_e32 v133, v133, v126
	v_or_b32_e32 v126, 0x45, v0
	v_sub_u32_e32 v174, v168, v126
	v_cvt_f32_u32_e32 v175, v174
	v_cmp_lt_i32_e32 vcc, -1, v174
	v_mul_f32_e32 v175, v169, v175
	v_exp_f32_e32 v175, v175
	s_nop 0
	v_cndmask_b32_e32 v175, 0, v175, vcc
	v_cmp_gt_i32_e32 vcc, 1, v174
	v_sub_u32_e32 v174, 0, v174
	v_cvt_f32_u32_e32 v174, v174
	v_mul_f32_e32 v174, v170, v174
	v_exp_f32_e32 v174, v174
	s_nop 0
	v_cndmask_b32_e32 v174, 0, v174, vcc
	v_add_f32_e32 v174, v175, v174
	v_mul_f32_e32 v174, v174, v127
	v_or_b32_e32 v127, 0x46, v0
	v_sub_u32_e32 v175, v168, v127
	v_cvt_f32_u32_e32 v176, v175
	v_cmp_lt_i32_e32 vcc, -1, v175
	v_cvt_pk_bf16_f32 v120, v133, v174
	v_mul_f32_e32 v176, v169, v176
	v_exp_f32_e32 v176, v176
	s_nop 0
	v_cndmask_b32_e32 v176, 0, v176, vcc
	v_cmp_gt_i32_e32 vcc, 1, v175
	v_sub_u32_e32 v175, 0, v175
	v_cvt_f32_u32_e32 v175, v175
	v_mul_f32_e32 v175, v170, v175
	v_exp_f32_e32 v175, v175
	s_nop 0
	v_cndmask_b32_e32 v175, 0, v175, vcc
	v_add_f32_e32 v175, v176, v175
	v_mul_f32_e32 v175, v175, v128
	v_or_b32_e32 v128, 0x47, v0
	v_sub_u32_e32 v176, v168, v128
	v_cvt_f32_u32_e32 v177, v176
	v_cmp_lt_i32_e32 vcc, -1, v176
	v_mul_f32_e32 v177, v169, v177
	v_exp_f32_e32 v177, v177
	s_nop 0
	v_cndmask_b32_e32 v177, 0, v177, vcc
	v_cmp_gt_i32_e32 vcc, 1, v176
	v_sub_u32_e32 v176, 0, v176
	v_cvt_f32_u32_e32 v176, v176
	v_mul_f32_e32 v176, v170, v176
	v_exp_f32_e32 v176, v176
	s_nop 0
	v_cndmask_b32_e32 v176, 0, v176, vcc
	v_add_f32_e32 v176, v177, v176
	v_mul_f32_e32 v129, v176, v129
	v_cvt_pk_bf16_f32 v121, v175, v129
	v_sub_u32_e32 v129, v171, v173
	v_cvt_f32_u32_e32 v133, v129
	v_cmp_lt_i32_e32 vcc, -1, v129
	v_mfma_f32_16x16x32_bf16 v[74:77], v[98:101], v[118:121], v[74:77]
	v_mul_f32_e32 v133, v169, v133
	v_exp_f32_e32 v133, v133
	v_mfma_f32_16x16x32_bf16 v[66:69], v[102:105], v[118:121], v[66:69]
	v_cndmask_b32_e32 v133, 0, v133, vcc
	v_cmp_gt_i32_e32 vcc, 1, v129
	v_sub_u32_e32 v129, 0, v129
	v_cvt_f32_u32_e32 v129, v129
	v_mfma_f32_16x16x32_bf16 v[58:61], v[106:109], v[118:121], v[58:61]
	v_mul_f32_e32 v129, v170, v129
	v_exp_f32_e32 v129, v129
	v_mfma_f32_16x16x32_bf16 v[50:53], v[110:113], v[118:121], v[50:53]
	v_cndmask_b32_e32 v129, 0, v129, vcc
	v_add_f32_e32 v129, v133, v129
	v_mul_f32_e32 v122, v129, v122
	v_sub_u32_e32 v129, v171, v130
	v_cvt_f32_u32_e32 v130, v129
	v_cmp_lt_i32_e32 vcc, -1, v129
	v_mul_f32_e32 v130, v169, v130
	v_exp_f32_e32 v130, v130
	s_nop 0
	v_cndmask_b32_e32 v130, 0, v130, vcc
	v_cmp_gt_i32_e32 vcc, 1, v129
	v_sub_u32_e32 v129, 0, v129
	v_cvt_f32_u32_e32 v129, v129
	v_mul_f32_e32 v129, v170, v129
	v_exp_f32_e32 v129, v129
	s_nop 0
	v_cndmask_b32_e32 v129, 0, v129, vcc
	v_add_f32_e32 v129, v130, v129
	v_mul_f32_e32 v123, v129, v123
	v_sub_u32_e32 v129, v171, v131
	v_cvt_f32_u32_e32 v130, v129
	v_cmp_lt_i32_e32 vcc, -1, v129
	v_mul_f32_e32 v130, v169, v130
	v_exp_f32_e32 v130, v130
	s_nop 0
	v_cndmask_b32_e32 v130, 0, v130, vcc
	v_cmp_gt_i32_e32 vcc, 1, v129
	v_sub_u32_e32 v129, 0, v129
	v_cvt_f32_u32_e32 v129, v129
	v_mul_f32_e32 v129, v170, v129
	v_exp_f32_e32 v129, v129
	s_nop 0
	v_cndmask_b32_e32 v129, 0, v129, vcc
	v_add_f32_e32 v129, v130, v129
	v_mul_f32_e32 v124, v129, v124
	v_sub_u32_e32 v129, v171, v132
	v_cvt_f32_u32_e32 v130, v129
	v_cmp_lt_i32_e32 vcc, -1, v129
	v_mul_f32_e32 v130, v169, v130
	v_exp_f32_e32 v130, v130
	s_nop 0
	v_cndmask_b32_e32 v130, 0, v130, vcc
	v_cmp_gt_i32_e32 vcc, 1, v129
	v_sub_u32_e32 v129, 0, v129
	v_cvt_f32_u32_e32 v129, v129
	v_mul_f32_e32 v129, v170, v129
	v_exp_f32_e32 v129, v129
	s_nop 0
	v_cndmask_b32_e32 v129, 0, v129, vcc
	v_add_f32_e32 v129, v130, v129
	v_mul_f32_e32 v125, v129, v125
	v_sub_u32_e32 v129, v171, v172
	v_cvt_f32_u32_e32 v130, v129
	v_cmp_lt_i32_e32 vcc, -1, v129
	v_mul_f32_e32 v130, v169, v130
	v_exp_f32_e32 v130, v130
	s_nop 0
	v_cndmask_b32_e32 v130, 0, v130, vcc
	v_cmp_gt_i32_e32 vcc, 1, v129
	v_sub_u32_e32 v129, 0, v129
	v_cvt_f32_u32_e32 v129, v129
	v_mul_f32_e32 v129, v170, v129
	v_exp_f32_e32 v129, v129
	s_nop 0
	v_cndmask_b32_e32 v129, 0, v129, vcc
	v_add_f32_e32 v129, v130, v129
	v_mul_f32_e32 v129, v129, v114
	v_sub_u32_e32 v114, v171, v126
	v_cvt_f32_u32_e32 v126, v114
	v_cmp_lt_i32_e32 vcc, -1, v114
	v_mul_f32_e32 v126, v169, v126
	v_exp_f32_e32 v126, v126
	s_nop 0
	v_cndmask_b32_e32 v126, 0, v126, vcc
	v_cmp_gt_i32_e32 vcc, 1, v114
	v_sub_u32_e32 v114, 0, v114
	v_cvt_f32_u32_e32 v114, v114
	v_mul_f32_e32 v114, v170, v114
	v_exp_f32_e32 v114, v114
	s_nop 0
	v_cndmask_b32_e32 v114, 0, v114, vcc
	v_add_f32_e32 v114, v126, v114
	v_mul_f32_e32 v126, v114, v115
	v_sub_u32_e32 v114, v171, v127
	v_cvt_f32_u32_e32 v115, v114
	v_cmp_lt_i32_e32 vcc, -1, v114
	v_mul_f32_e32 v115, v169, v115
	v_exp_f32_e32 v115, v115
	s_nop 0
	v_cndmask_b32_e32 v115, 0, v115, vcc
	v_cmp_gt_i32_e32 vcc, 1, v114
	v_sub_u32_e32 v114, 0, v114
	v_cvt_f32_u32_e32 v114, v114
	v_mul_f32_e32 v114, v170, v114
	v_exp_f32_e32 v114, v114
	s_nop 0
	v_cndmask_b32_e32 v114, 0, v114, vcc
	v_add_f32_e32 v114, v115, v114
	v_mul_f32_e32 v127, v114, v116
	v_sub_u32_e32 v114, v171, v128
	v_cvt_f32_u32_e32 v115, v114
	v_cmp_lt_i32_e32 vcc, -1, v114
	v_cvt_pk_bf16_f32 v116, v129, v126
	v_mul_f32_e32 v115, v169, v115
	v_exp_f32_e32 v115, v115
	s_nop 0
	v_cndmask_b32_e32 v115, 0, v115, vcc
	v_cmp_gt_i32_e32 vcc, 1, v114
	v_sub_u32_e32 v114, 0, v114
	v_cvt_f32_u32_e32 v114, v114
	v_mul_f32_e32 v114, v170, v114
	v_exp_f32_e32 v114, v114
	s_nop 0
	v_cndmask_b32_e32 v114, 0, v114, vcc
	v_add_f32_e32 v114, v115, v114
	v_mul_f32_e32 v117, v114, v117
	v_cvt_pk_bf16_f32 v114, v122, v123
	v_cvt_pk_bf16_f32 v115, v124, v125
	v_cvt_pk_bf16_f32 v117, v127, v117
	s_nop 1
	s_nop 0
	v_mfma_f32_16x16x32_bf16 v[78:81], v[98:101], v[114:117], v[78:81]
	v_mfma_f32_16x16x32_bf16 v[98:101], v[94:97], v[30:33], 0
	v_mfma_f32_16x16x32_bf16 v[94:97], v[94:97], v[26:29], 0
	v_mfma_f32_16x16x32_bf16 v[98:101], v[90:93], v[22:25], v[98:101]
	v_mfma_f32_16x16x32_bf16 v[90:93], v[90:93], v[18:21], v[94:97]
	v_mfma_f32_16x16x32_bf16 v[94:97], v[86:89], v[30:33], 0
	v_mfma_f32_16x16x32_bf16 v[86:89], v[86:89], v[26:29], 0
	v_mfma_f32_16x16x32_bf16 v[70:73], v[102:105], v[114:117], v[70:73]
	v_or_b32_e32 v103, 0x60, v0
	v_or_b32_e32 v102, 0x64, v0
	v_mfma_f32_16x16x32_bf16 v[94:97], v[82:85], v[22:25], v[94:97]
	v_mfma_f32_16x16x32_bf16 v[82:85], v[82:85], v[18:21], v[86:89]
	s_nop 2
	v_sub_u32_e32 v86, v168, v103
	v_cvt_f32_u32_e32 v87, v86
	v_cmp_lt_i32_e32 vcc, -1, v86
	v_mfma_f32_16x16x32_bf16 v[62:65], v[106:109], v[114:117], v[62:65]
	v_mul_f32_e32 v87, v169, v87
	v_exp_f32_e32 v87, v87
	v_mfma_f32_16x16x32_bf16 v[54:57], v[110:113], v[114:117], v[54:57]
	v_cndmask_b32_e32 v87, 0, v87, vcc
	v_cmp_gt_i32_e32 vcc, 1, v86
	v_sub_u32_e32 v86, 0, v86
	v_cvt_f32_u32_e32 v86, v86
	v_mul_f32_e32 v86, v170, v86
	v_exp_f32_e32 v86, v86
	s_nop 0
	v_cndmask_b32_e32 v86, 0, v86, vcc
	v_add_f32_e32 v86, v87, v86
	v_mul_f32_e32 v86, v86, v98
	v_or_b32_e32 v98, 0x61, v0
	v_sub_u32_e32 v87, v168, v98
	v_cvt_f32_u32_e32 v88, v87
	v_cmp_lt_i32_e32 vcc, -1, v87
	v_mul_f32_e32 v88, v169, v88
	v_exp_f32_e32 v88, v88
	s_nop 0
	v_cndmask_b32_e32 v88, 0, v88, vcc
	v_cmp_gt_i32_e32 vcc, 1, v87
	v_sub_u32_e32 v87, 0, v87
	v_cvt_f32_u32_e32 v87, v87
	v_mul_f32_e32 v87, v170, v87
	v_exp_f32_e32 v87, v87
	s_nop 0
	v_cndmask_b32_e32 v87, 0, v87, vcc
	v_add_f32_e32 v87, v88, v87
	v_mul_f32_e32 v87, v87, v99
	v_or_b32_e32 v99, 0x62, v0
	v_sub_u32_e32 v88, v168, v99
	v_cvt_f32_u32_e32 v89, v88
	v_cmp_lt_i32_e32 vcc, -1, v88
	v_cvt_pk_bf16_f32 v86, v86, v87
	v_mul_f32_e32 v89, v169, v89
	v_exp_f32_e32 v89, v89
	s_nop 0
	v_cndmask_b32_e32 v89, 0, v89, vcc
	v_cmp_gt_i32_e32 vcc, 1, v88
	v_sub_u32_e32 v88, 0, v88
	v_cvt_f32_u32_e32 v88, v88
	v_mul_f32_e32 v88, v170, v88
	v_exp_f32_e32 v88, v88
	s_nop 0
	v_cndmask_b32_e32 v88, 0, v88, vcc
	v_add_f32_e32 v88, v89, v88
	v_mul_f32_e32 v88, v88, v100
	v_or_b32_e32 v100, 0x63, v0
	v_sub_u32_e32 v89, v168, v100
	v_cvt_f32_u32_e32 v104, v89
	v_cmp_lt_i32_e32 vcc, -1, v89
	v_mul_f32_e32 v104, v169, v104
	v_exp_f32_e32 v104, v104
	s_nop 0
	v_cndmask_b32_e32 v104, 0, v104, vcc
	v_cmp_gt_i32_e32 vcc, 1, v89
	v_sub_u32_e32 v89, 0, v89
	v_cvt_f32_u32_e32 v89, v89
	v_mul_f32_e32 v89, v170, v89
	v_exp_f32_e32 v89, v89
	s_nop 0
	v_cndmask_b32_e32 v89, 0, v89, vcc
	v_add_f32_e32 v89, v104, v89
	v_mul_f32_e32 v89, v89, v101
	v_sub_u32_e32 v101, v168, v102
	v_cvt_f32_u32_e32 v104, v101
	v_cmp_lt_i32_e32 vcc, -1, v101
	v_cvt_pk_bf16_f32 v87, v88, v89
	v_mul_f32_e32 v104, v169, v104
	v_exp_f32_e32 v104, v104
	s_nop 0
	v_cndmask_b32_e32 v104, 0, v104, vcc
	v_cmp_gt_i32_e32 vcc, 1, v101
	v_sub_u32_e32 v101, 0, v101
	v_cvt_f32_u32_e32 v101, v101
	v_mul_f32_e32 v101, v170, v101
	v_exp_f32_e32 v101, v101
	s_nop 0
	v_cndmask_b32_e32 v101, 0, v101, vcc
	v_add_f32_e32 v101, v104, v101
	v_mul_f32_e32 v101, v101, v94
	v_or_b32_e32 v94, 0x65, v0
	v_sub_u32_e32 v104, v168, v94
	v_cvt_f32_u32_e32 v105, v104
	v_cmp_lt_i32_e32 vcc, -1, v104
	v_sub_u32_e32 v94, v171, v94
	v_mul_f32_e32 v105, v169, v105
	v_exp_f32_e32 v105, v105
	s_nop 0
	v_cndmask_b32_e32 v105, 0, v105, vcc
	v_cmp_gt_i32_e32 vcc, 1, v104
	v_sub_u32_e32 v104, 0, v104
	v_cvt_f32_u32_e32 v104, v104
	v_mul_f32_e32 v104, v170, v104
	v_exp_f32_e32 v104, v104
	s_nop 0
	v_cndmask_b32_e32 v104, 0, v104, vcc
	v_add_f32_e32 v104, v105, v104
	v_mul_f32_e32 v104, v104, v95
	v_or_b32_e32 v95, 0x66, v0
	v_sub_u32_e32 v105, v168, v95
	v_cvt_f32_u32_e32 v106, v105
	v_cmp_lt_i32_e32 vcc, -1, v105
	v_cvt_pk_bf16_f32 v88, v101, v104
	v_mul_f32_e32 v106, v169, v106
	v_exp_f32_e32 v106, v106
	s_nop 0
	v_cndmask_b32_e32 v106, 0, v106, vcc
	v_cmp_gt_i32_e32 vcc, 1, v105
	v_sub_u32_e32 v105, 0, v105
	v_cvt_f32_u32_e32 v105, v105
	v_mul_f32_e32 v105, v170, v105
	v_exp_f32_e32 v105, v105
	s_nop 0
	v_cndmask_b32_e32 v105, 0, v105, vcc
	v_add_f32_e32 v105, v106, v105
	v_mul_f32_e32 v105, v105, v96
	v_or_b32_e32 v96, 0x67, v0
	v_sub_u32_e32 v106, v168, v96
	v_cvt_f32_u32_e32 v107, v106
	v_cmp_lt_i32_e32 vcc, -1, v106
	v_mul_f32_e32 v107, v169, v107
	v_exp_f32_e32 v107, v107
	s_nop 0
	v_cndmask_b32_e32 v107, 0, v107, vcc
	v_cmp_gt_i32_e32 vcc, 1, v106
	v_sub_u32_e32 v106, 0, v106
	v_cvt_f32_u32_e32 v106, v106
	v_mul_f32_e32 v106, v170, v106
	v_exp_f32_e32 v106, v106
	s_nop 0
	v_cndmask_b32_e32 v106, 0, v106, vcc
	v_add_f32_e32 v106, v107, v106
	v_mul_f32_e32 v97, v106, v97
	v_cvt_pk_bf16_f32 v89, v105, v97
	v_sub_u32_e32 v97, v171, v103
	v_cvt_f32_u32_e32 v101, v97
	v_cmp_lt_i32_e32 vcc, -1, v97
	v_mfma_f32_16x16x32_bf16 v[50:53], v[46:49], v[86:89], v[50:53]
	v_mul_f32_e32 v101, v169, v101
	v_exp_f32_e32 v101, v101
	v_mfma_f32_16x16x32_bf16 v[58:61], v[42:45], v[86:89], v[58:61]
	v_cndmask_b32_e32 v101, 0, v101, vcc
	v_cmp_gt_i32_e32 vcc, 1, v97
	v_sub_u32_e32 v97, 0, v97
	v_cvt_f32_u32_e32 v97, v97
	v_mul_f32_e32 v97, v170, v97
	v_exp_f32_e32 v97, v97
	s_nop 0
	v_cndmask_b32_e32 v97, 0, v97, vcc
	v_add_f32_e32 v97, v101, v97
	v_mul_f32_e32 v90, v97, v90
	v_sub_u32_e32 v97, v171, v98
	v_cvt_f32_u32_e32 v98, v97
	v_cmp_lt_i32_e32 vcc, -1, v97
	v_mul_f32_e32 v98, v169, v98
	v_exp_f32_e32 v98, v98
	s_nop 0
	v_cndmask_b32_e32 v98, 0, v98, vcc
	v_cmp_gt_i32_e32 vcc, 1, v97
	v_sub_u32_e32 v97, 0, v97
	v_cvt_f32_u32_e32 v97, v97
	v_mul_f32_e32 v97, v170, v97
	v_exp_f32_e32 v97, v97
	s_nop 0
	v_cndmask_b32_e32 v97, 0, v97, vcc
	v_add_f32_e32 v97, v98, v97
	v_mul_f32_e32 v91, v97, v91
	v_sub_u32_e32 v97, v171, v99
	v_cvt_f32_u32_e32 v98, v97
	v_cmp_lt_i32_e32 vcc, -1, v97
	v_cvt_pk_bf16_f32 v90, v90, v91
	v_mul_f32_e32 v98, v169, v98
	v_exp_f32_e32 v98, v98
	s_nop 0
	v_cndmask_b32_e32 v98, 0, v98, vcc
	v_cmp_gt_i32_e32 vcc, 1, v97
	v_sub_u32_e32 v97, 0, v97
	v_cvt_f32_u32_e32 v97, v97
	v_mul_f32_e32 v97, v170, v97
	v_exp_f32_e32 v97, v97
	s_nop 0
	v_cndmask_b32_e32 v97, 0, v97, vcc
	v_add_f32_e32 v97, v98, v97
	v_mul_f32_e32 v92, v97, v92
	v_sub_u32_e32 v97, v171, v100
	v_cvt_f32_u32_e32 v98, v97
	v_cmp_lt_i32_e32 vcc, -1, v97
	v_mul_f32_e32 v98, v169, v98
	v_exp_f32_e32 v98, v98
	s_nop 0
	v_cndmask_b32_e32 v98, 0, v98, vcc
	v_cmp_gt_i32_e32 vcc, 1, v97
	v_sub_u32_e32 v97, 0, v97
	v_cvt_f32_u32_e32 v97, v97
	v_mul_f32_e32 v97, v170, v97
	v_exp_f32_e32 v97, v97
	s_nop 0
	v_cndmask_b32_e32 v97, 0, v97, vcc
	v_add_f32_e32 v97, v98, v97
	v_mul_f32_e32 v93, v97, v93
	v_sub_u32_e32 v97, v171, v102
	v_cvt_f32_u32_e32 v98, v97
	v_cmp_lt_i32_e32 vcc, -1, v97
	v_cvt_pk_bf16_f32 v91, v92, v93
	v_mul_f32_e32 v98, v169, v98
	v_exp_f32_e32 v98, v98
	s_nop 0
	v_cndmask_b32_e32 v98, 0, v98, vcc
	v_cmp_gt_i32_e32 vcc, 1, v97
	v_sub_u32_e32 v97, 0, v97
	v_cvt_f32_u32_e32 v97, v97
	v_mul_f32_e32 v97, v170, v97
	v_exp_f32_e32 v97, v97
	s_nop 0
	v_cndmask_b32_e32 v97, 0, v97, vcc
	v_add_f32_e32 v97, v98, v97
	v_mul_f32_e32 v82, v97, v82
	v_cvt_f32_u32_e32 v97, v94
	v_cmp_lt_i32_e32 vcc, -1, v94
	v_mul_f32_e32 v97, v169, v97
	v_exp_f32_e32 v97, v97
	s_nop 0
	v_cndmask_b32_e32 v97, 0, v97, vcc
	v_cmp_gt_i32_e32 vcc, 1, v94
	v_sub_u32_e32 v94, 0, v94
	v_cvt_f32_u32_e32 v94, v94
	v_mul_f32_e32 v94, v170, v94
	v_exp_f32_e32 v94, v94
	s_nop 0
	v_cndmask_b32_e32 v94, 0, v94, vcc
	v_add_f32_e32 v94, v97, v94
	v_mul_f32_e32 v83, v94, v83
	v_sub_u32_e32 v94, v171, v95
	v_cvt_f32_u32_e32 v95, v94
	v_cmp_lt_i32_e32 vcc, -1, v94
	v_cvt_pk_bf16_f32 v92, v82, v83
	v_mul_f32_e32 v95, v169, v95
	v_exp_f32_e32 v95, v95
	s_nop 0
	v_cndmask_b32_e32 v95, 0, v95, vcc
	v_cmp_gt_i32_e32 vcc, 1, v94
	v_sub_u32_e32 v94, 0, v94
	v_cvt_f32_u32_e32 v94, v94
	v_mul_f32_e32 v94, v170, v94
	v_exp_f32_e32 v94, v94
	s_nop 0
	v_cndmask_b32_e32 v94, 0, v94, vcc
	v_add_f32_e32 v94, v95, v94
	v_mul_f32_e32 v84, v94, v84
	v_sub_u32_e32 v94, v171, v96
	v_cvt_f32_u32_e32 v95, v94
	v_cmp_lt_i32_e32 vcc, -1, v94
	v_mul_f32_e32 v95, v169, v95
	v_exp_f32_e32 v95, v95
	s_nop 0
	v_cndmask_b32_e32 v95, 0, v95, vcc
	v_cmp_gt_i32_e32 vcc, 1, v94
	v_sub_u32_e32 v94, 0, v94
	v_cvt_f32_u32_e32 v94, v94
	v_mul_f32_e32 v94, v170, v94
	v_exp_f32_e32 v94, v94
	s_nop 0
	v_cndmask_b32_e32 v94, 0, v94, vcc
	v_add_f32_e32 v94, v95, v94
	v_mul_f32_e32 v85, v94, v85
	v_cvt_pk_bf16_f32 v93, v84, v85
	v_cmp_lt_i32_e32 vcc, v210, v208
	v_mfma_f32_16x16x32_bf16 v[54:57], v[46:49], v[90:93], v[54:57]
	v_mfma_f32_16x16x32_bf16 v[62:65], v[42:45], v[90:93], v[62:65]
	v_mfma_f32_16x16x32_bf16 v[46:49], v[38:41], v[86:89], v[66:69]
	v_mfma_f32_16x16x32_bf16 v[66:69], v[38:41], v[90:93], v[70:73]
	v_mfma_f32_16x16x32_bf16 v[38:41], v[34:37], v[86:89], v[74:77]
	v_mfma_f32_16x16x32_bf16 v[70:73], v[34:37], v[90:93], v[78:81]
	global_load_dwordx4 v[34:37], v[162:163], off offset:64
	global_load_dwordx4 v[42:45], v[162:163], off
	global_load_dwordx4 v[74:77], v[158:159], off offset:64
	global_load_dwordx4 v[78:81], v[158:159], off
	global_load_dwordx4 v[82:85], v[152:153], off offset:2112
	global_load_dwordx4 v[86:89], v[152:153], off offset:2048
	global_load_dwordx4 v[90:93], v[152:153], off offset:64
	global_load_dwordx4 v[94:97], v[152:153], off
	global_load_dwordx4 v[98:101], v[160:161], off offset:64
	global_load_dwordx4 v[102:105], v[160:161], off
	global_load_dwordx4 v[106:109], v[156:157], off offset:64
	global_load_dwordx4 v[110:113], v[156:157], off
	global_load_dwordx4 v[114:117], v[154:155], off offset:2112
	global_load_dwordx4 v[118:121], v[154:155], off offset:2048
	global_load_dwordx4 v[122:125], v[154:155], off offset:64
	global_load_dwordx4 v[126:129], v[154:155], off
	s_waitcnt vmcnt(0)
	s_nop 0
	v_mfma_f32_16x16x32_bf16 v[130:133], v[94:97], v[30:33], 0
	v_mfma_f32_16x16x32_bf16 v[94:97], v[94:97], v[26:29], 0
	v_mfma_f32_16x16x32_bf16 v[130:133], v[90:93], v[22:25], v[130:133]
	v_mfma_f32_16x16x32_bf16 v[90:93], v[90:93], v[18:21], v[94:97]
	v_mfma_f32_16x16x32_bf16 v[94:97], v[86:89], v[30:33], 0
	v_mfma_f32_16x16x32_bf16 v[86:89], v[86:89], v[26:29], 0
	v_mfma_f32_16x16x32_bf16 v[94:97], v[82:85], v[22:25], v[94:97]
	v_mfma_f32_16x16x32_bf16 v[82:85], v[82:85], v[18:21], v[86:89]
	v_mfma_f32_16x16x32_bf16 v[86:89], v[78:81], v[30:33], 0
	v_mfma_f32_16x16x32_bf16 v[78:81], v[78:81], v[26:29], 0
	v_mfma_f32_16x16x32_bf16 v[86:89], v[74:77], v[22:25], v[86:89]
	v_mfma_f32_16x16x32_bf16 v[74:77], v[74:77], v[18:21], v[78:81]
	v_mfma_f32_16x16x32_bf16 v[78:81], v[42:45], v[30:33], 0
	v_mfma_f32_16x16x32_bf16 v[42:45], v[42:45], v[26:29], 0
	v_mfma_f32_16x16x32_bf16 v[78:81], v[34:37], v[22:25], v[78:81]
	v_mfma_f32_16x16x32_bf16 v[152:155], v[34:37], v[18:21], v[42:45]
	v_mfma_f32_16x16x32_bf16 v[34:37], v[126:129], v[30:33], 0
	v_mfma_f32_16x16x32_bf16 v[42:45], v[126:129], v[26:29], 0
	v_mfma_f32_16x16x32_bf16 v[126:129], v[122:125], v[22:25], v[34:37]
	v_mfma_f32_16x16x32_bf16 v[122:125], v[122:125], v[18:21], v[42:45]
	v_mfma_f32_16x16x32_bf16 v[34:37], v[118:121], v[30:33], 0
	v_mfma_f32_16x16x32_bf16 v[42:45], v[118:121], v[26:29], 0
	v_mfma_f32_16x16x32_bf16 v[118:121], v[114:117], v[22:25], v[34:37]
	v_mfma_f32_16x16x32_bf16 v[114:117], v[114:117], v[18:21], v[42:45]
	v_mfma_f32_16x16x32_bf16 v[34:37], v[110:113], v[30:33], 0
	v_mfma_f32_16x16x32_bf16 v[42:45], v[110:113], v[26:29], 0
	v_mfma_f32_16x16x32_bf16 v[30:33], v[102:105], v[30:33], 0
	v_mfma_f32_16x16x32_bf16 v[26:29], v[102:105], v[26:29], 0
	v_mfma_f32_16x16x32_bf16 v[34:37], v[106:109], v[22:25], v[34:37]
	v_mfma_f32_16x16x32_bf16 v[106:109], v[106:109], v[18:21], v[42:45]
	v_mfma_f32_16x16x32_bf16 v[22:25], v[98:101], v[22:25], v[30:33]
	v_mfma_f32_16x16x32_bf16 v[98:101], v[98:101], v[18:21], v[26:29]
	v_sub_u32_e32 v18, 0x80, v171
	v_cvt_f32_ubyte0_e32 v18, v18
	v_mul_f32_e32 v18, v170, v18
	s_nop 0
	v_exp_f32_e32 v28, v18
	v_add_u32_e32 v18, 1, v168
	v_cvt_f32_ubyte0_e32 v18, v18
	v_mul_f32_e32 v18, v169, v18
	v_exp_f32_e32 v18, v18
	s_nop 0
	v_pk_fma_f32 v[20:21], v[18:19], v[80:81], v[40:41] op_sel_hi:[0,1,1]
	v_pk_fma_f32 v[26:27], v[18:19], v[78:79], v[38:39] op_sel_hi:[0,1,1]
	v_sub_u32_e32 v19, 0x80, v168
	v_cvt_f32_ubyte0_e32 v19, v19
	v_mul_f32_e32 v19, v170, v19
	v_exp_f32_e32 v30, v19
	s_nop 0
	v_pk_fma_f32 v[42:43], v[30:31], v[24:25], v[20:21] op_sel_hi:[0,1,1]
	v_pk_fma_f32 v[20:21], v[18:19], v[88:89], v[48:49] op_sel_hi:[0,1,1]
	v_pk_fma_f32 v[44:45], v[30:31], v[22:23], v[26:27] op_sel_hi:[0,1,1]
	v_pk_fma_f32 v[22:23], v[18:19], v[86:87], v[46:47] op_sel_hi:[0,1,1]
	v_pk_fma_f32 v[46:47], v[30:31], v[36:37], v[20:21] op_sel_hi:[0,1,1]
	v_pk_fma_f32 v[20:21], v[18:19], v[96:97], v[60:61] op_sel_hi:[0,1,1]
	v_pk_fma_f32 v[48:49], v[30:31], v[34:35], v[22:23] op_sel_hi:[0,1,1]
	v_pk_fma_f32 v[22:23], v[18:19], v[94:95], v[58:59] op_sel_hi:[0,1,1]
	v_pk_fma_f32 v[34:35], v[30:31], v[120:121], v[20:21] op_sel_hi:[0,1,1]
	v_pk_fma_f32 v[20:21], v[18:19], v[132:133], v[52:53] op_sel_hi:[0,1,1]
	v_pk_fma_f32 v[18:19], v[18:19], v[130:131], v[50:51] op_sel_hi:[0,1,1]
	v_pk_fma_f32 v[40:41], v[30:31], v[126:127], v[18:19] op_sel_hi:[0,1,1]
	v_add_u32_e32 v18, 17, v168
	v_cvt_f32_ubyte0_e32 v18, v18
	v_mul_f32_e32 v18, v169, v18
	v_exp_f32_e32 v18, v18
	v_pk_fma_f32 v[36:37], v[30:31], v[118:119], v[22:23] op_sel_hi:[0,1,1]
	v_pk_fma_f32 v[38:39], v[30:31], v[128:129], v[20:21] op_sel_hi:[0,1,1]
	v_and_b32_e32 v58, 0xffff0000, v151
	v_pk_fma_f32 v[26:27], v[18:19], v[154:155], v[72:73] op_sel_hi:[0,1,1]
	v_pk_fma_f32 v[50:51], v[18:19], v[152:153], v[70:71] op_sel_hi:[0,1,1]
	v_pk_fma_f32 v[30:31], v[18:19], v[76:77], v[68:69] op_sel_hi:[0,1,1]
	v_pk_fma_f32 v[32:33], v[18:19], v[74:75], v[66:67] op_sel_hi:[0,1,1]
	v_pk_fma_f32 v[20:21], v[18:19], v[84:85], v[64:65] op_sel_hi:[0,1,1]
	v_pk_fma_f32 v[52:53], v[18:19], v[82:83], v[62:63] op_sel_hi:[0,1,1]
	v_pk_fma_f32 v[22:23], v[18:19], v[92:93], v[56:57] op_sel_hi:[0,1,1]
	v_pk_fma_f32 v[18:19], v[18:19], v[90:91], v[54:55] op_sel_hi:[0,1,1]
	v_pk_fma_f32 v[22:23], v[28:29], v[124:125], v[22:23] op_sel_hi:[0,1,1]
	v_pk_fma_f32 v[24:25], v[28:29], v[122:123], v[18:19] op_sel_hi:[0,1,1]
	v_pk_fma_f32 v[18:19], v[28:29], v[116:117], v[20:21] op_sel_hi:[0,1,1]
	v_pk_fma_f32 v[20:21], v[28:29], v[114:115], v[52:53] op_sel_hi:[0,1,1]
	v_pk_fma_f32 v[30:31], v[28:29], v[108:109], v[30:31] op_sel_hi:[0,1,1]
	v_pk_fma_f32 v[32:33], v[28:29], v[106:107], v[32:33] op_sel_hi:[0,1,1]
	v_pk_fma_f32 v[26:27], v[28:29], v[100:101], v[26:27] op_sel_hi:[0,1,1]
	v_pk_fma_f32 v[28:29], v[28:29], v[98:99], v[50:51] op_sel_hi:[0,1,1]
	v_cndmask_b32_e32 v50, v207, v210, vcc
	v_cmp_lt_i32_e32 vcc, v209, v208
	v_lshlrev_b32_e32 v54, 2, v50
	v_mov_b32_e32 v51, v36
	v_cndmask_b32_e32 v50, v207, v209, vcc
	v_lshlrev_b32_e32 v55, 2, v50
	v_mov_b32_e32 v50, v40
	v_mov_b32_e32 v52, v41
	v_mov_b32_e32 v53, v37
	v_pk_add_f32 v[50:51], v[50:51], v[52:53]
	v_mov_b32_e32 v52, v38
	v_mov_b32_e32 v53, v34
	v_pk_add_f32 v[50:51], v[52:53], v[50:51]
	v_mov_b32_e32 v52, v39
	v_mov_b32_e32 v53, v35
	v_pk_add_f32 v[50:51], v[52:53], v[50:51]
	v_mov_b32_e32 v52, v49
	v_add_f32_e32 v50, 0, v50
	v_add_f32_e32 v56, v50, v51
	v_mov_b32_e32 v50, v48
	v_mov_b32_e32 v51, v44
	v_mov_b32_e32 v53, v45
	v_pk_add_f32 v[50:51], v[50:51], v[52:53]
	v_mov_b32_e32 v52, v46
	v_mov_b32_e32 v53, v42
	v_pk_add_f32 v[50:51], v[52:53], v[50:51]
	v_mov_b32_e32 v52, v47
	v_mov_b32_e32 v53, v43
	v_pk_add_f32 v[50:51], v[52:53], v[50:51]
	v_lshlrev_b32_e32 v57, 16, v151
	v_add_f32_e32 v50, v56, v50
	v_add_f32_e32 v50, v50, v51
	ds_bpermute_b32 v51, v54, v50
	s_waitcnt lgkmcnt(0)
	v_add_f32_e32 v50, v50, v51
	ds_bpermute_b32 v51, v55, v50
	s_waitcnt lgkmcnt(0)
	v_add_f32_e32 v51, v50, v51
	v_fmac_f32_e32 v41, 0xbc800000, v51
	v_fmamk_f32 v40, v51, 0xbc800000, v40
	v_mul_f32_e32 v56, v41, v41
	v_fmac_f32_e32 v56, v40, v40
	v_fmamk_f32 v38, v51, 0xbc800000, v38
	v_fmac_f32_e32 v56, v38, v38
	v_fmac_f32_e32 v39, 0xbc800000, v51
	v_fmac_f32_e32 v56, v39, v39
	v_fmamk_f32 v36, v51, 0xbc800000, v36
	v_fmac_f32_e32 v56, v36, v36
	v_fmac_f32_e32 v37, 0xbc800000, v51
	v_mul_f32_e32 v50, 0x3c800000, v51
	v_fmac_f32_e32 v56, v37, v37
	v_fmamk_f32 v34, v51, 0xbc800000, v34
	v_fmac_f32_e32 v56, v34, v34
	v_fmac_f32_e32 v35, 0xbc800000, v51
	v_pk_add_f32 v[48:49], v[48:49], v[50:51] op_sel_hi:[1,0] neg_lo:[0,1] neg_hi:[0,1]
	v_fmac_f32_e32 v56, v35, v35
	v_pk_mul_f32 v[52:53], v[48:49], v[48:49]
	s_nop 0
	v_add_f32_e32 v51, v52, v56
	v_add_f32_e32 v51, v53, v51
	v_pk_add_f32 v[46:47], v[46:47], v[50:51] op_sel_hi:[1,0] neg_lo:[0,1] neg_hi:[0,1]
	v_and_b32_e32 v56, 0xffff0000, v150
	v_pk_mul_f32 v[52:53], v[46:47], v[46:47]
	s_nop 0
	v_add_f32_e32 v51, v52, v51
	v_add_f32_e32 v51, v53, v51
	v_pk_add_f32 v[44:45], v[44:45], v[50:51] op_sel_hi:[1,0] neg_lo:[0,1] neg_hi:[0,1]
	s_nop 0
	v_pk_mul_f32 v[52:53], v[44:45], v[44:45]
	s_nop 0
	v_add_f32_e32 v51, v52, v51
	v_pk_add_f32 v[42:43], v[42:43], v[50:51] op_sel_hi:[1,0] neg_lo:[0,1] neg_hi:[0,1]
	v_add_f32_e32 v52, v53, v51
	v_pk_mul_f32 v[50:51], v[42:43], v[42:43]
	v_lshlrev_b32_e32 v53, 16, v150
	v_add_f32_e32 v50, v50, v52
	v_add_f32_e32 v50, v51, v50
	ds_bpermute_b32 v51, v54, v50
	s_waitcnt lgkmcnt(0)
	v_add_f32_e32 v50, v50, v51
	ds_bpermute_b32 v51, v55, v50
	s_waitcnt lgkmcnt(0)
	v_add_f32_e32 v50, v50, v51
	v_fmamk_f32 v50, v50, 0x3c800000, v203
	v_cmp_gt_f32_e32 vcc, s28, v50
	v_mul_f32_e32 v51, 0x4b800000, v50
	s_nop 0
	v_cndmask_b32_e32 v50, v50, v51, vcc
	v_rsq_f32_e32 v50, v50
	s_nop 0
	v_mul_f32_e32 v51, 0x45800000, v50
	v_cndmask_b32_e32 v52, v50, v51, vcc
	v_cmp_gt_i32_e32 vcc, s37, v167
	v_mul_f32_e32 v40, v40, v52
	v_mul_f32_e32 v38, v38, v52
	v_cndmask_b32_e64 v50, 3, 1, vcc
	v_add_u32_e32 v50, v50, v167
	v_ashrrev_i32_e32 v51, 31, v50
	v_lshlrev_b64 v[50:51], 11, v[50:51]
	v_mul_f32_e32 v40, v14, v40
	v_mul_f32_e32 v41, v41, v52
	v_mul_f32_e32 v38, v16, v38
	v_lshl_add_u64 v[50:51], s[8:9], 0, v[50:51]
	v_mul_f32_e32 v40, v40, v53
	v_mul_f32_e32 v41, v15, v41
	v_mul_f32_e32 v53, v38, v57
	v_mul_f32_e32 v38, v39, v52
	v_lshl_add_u64 v[50:51], v[50:51], 0, v[134:135]
	v_mul_f32_e32 v41, v41, v56
	v_mul_f32_e32 v38, v17, v38
	v_mul_f32_e32 v39, v38, v58
	v_cvt_pk_bf16_f32 v38, v40, v41
	v_lshl_add_u64 v[40:41], v[50:51], 0, v[0:1]
	v_lshl_add_u64 v[50:51], v[40:41], 0, s[54:55]
	v_add_co_u32_e32 v40, vcc, s34, v40
	v_mul_f32_e32 v36, v36, v52
	s_nop 0
	v_addc_co_u32_e32 v41, vcc, 0, v41, vcc
	v_mul_f32_e32 v34, v34, v52
	v_cvt_pk_bf16_f32 v39, v53, v39
	global_store_dwordx2 v[40:41], v[38:39], off offset:1280
	v_lshlrev_b32_e32 v38, 16, v148
	v_lshlrev_b32_e32 v40, 16, v149
	v_mul_f32_e32 v36, v10, v36
	v_mul_f32_e32 v34, v12, v34
	v_mul_f32_e32 v36, v36, v38
	v_mul_f32_e32 v38, v34, v40
	v_mul_f32_e32 v34, v35, v52
	v_and_b32_e32 v41, 0xffff0000, v149
	v_mul_f32_e32 v37, v37, v52
	v_mul_f32_e32 v34, v13, v34
	v_and_b32_e32 v39, 0xffff0000, v148
	v_mul_f32_e32 v37, v11, v37
	v_mul_f32_e32 v35, v34, v41
	v_mul_f32_e32 v37, v37, v39
	v_cvt_pk_bf16_f32 v34, v36, v37
	v_cvt_pk_bf16_f32 v35, v38, v35
	v_mul_f32_e32 v38, v48, v52
	global_store_dwordx2 v[50:51], v[34:35], off offset:32
	v_lshlrev_b32_e32 v34, 16, v146
	v_mul_f32_e32 v38, v6, v38
	v_mul_f32_e32 v34, v38, v34
	v_mul_f32_e32 v38, v49, v52
	v_and_b32_e32 v35, 0xffff0000, v146
	v_mul_f32_e32 v38, v7, v38
	v_mul_f32_e32 v35, v38, v35
	v_mul_f32_e32 v38, v46, v52
	v_lshlrev_b32_e32 v36, 16, v147
	v_mul_f32_e32 v38, v8, v38
	v_mul_f32_e32 v36, v38, v36
	v_mul_f32_e32 v38, v47, v52
	v_and_b32_e32 v37, 0xffff0000, v147
	v_mul_f32_e32 v38, v9, v38
	v_mul_f32_e32 v37, v38, v37
	v_cvt_pk_bf16_f32 v34, v34, v35
	v_mul_f32_e32 v38, v44, v52
	v_cvt_pk_bf16_f32 v35, v36, v37
	global_store_dwordx2 v[50:51], v[34:35], off offset:64
	v_lshlrev_b32_e32 v34, 16, v144
	v_mul_f32_e32 v38, v2, v38
	v_mul_f32_e32 v34, v38, v34
	v_mul_f32_e32 v38, v45, v52
	v_and_b32_e32 v35, 0xffff0000, v144
	v_mul_f32_e32 v38, v3, v38
	v_mul_f32_e32 v35, v38, v35
	v_mul_f32_e32 v38, v42, v52
	v_lshlrev_b32_e32 v36, 16, v145
	v_mul_f32_e32 v38, v4, v38
	v_mul_f32_e32 v36, v38, v36
	v_mul_f32_e32 v38, v43, v52
	v_and_b32_e32 v37, 0xffff0000, v145
	v_mul_f32_e32 v38, v5, v38
	v_mul_f32_e32 v37, v38, v37
	v_cvt_pk_bf16_f32 v34, v34, v35
	v_cvt_pk_bf16_f32 v35, v36, v37
	global_store_dwordx2 v[50:51], v[34:35], off offset:96
	v_mov_b32_e32 v34, v24
	v_mov_b32_e32 v35, v20
	v_mov_b32_e32 v36, v25
	v_mov_b32_e32 v37, v21
	v_pk_add_f32 v[34:35], v[34:35], v[36:37]
	v_mov_b32_e32 v36, v22
	v_mov_b32_e32 v37, v18
	v_pk_add_f32 v[34:35], v[36:37], v[34:35]
	v_mov_b32_e32 v36, v23
	v_mov_b32_e32 v37, v19
	v_pk_add_f32 v[34:35], v[36:37], v[34:35]
	v_mov_b32_e32 v36, v33
	v_add_f32_e32 v34, 0, v34
	v_add_f32_e32 v38, v34, v35
	v_mov_b32_e32 v34, v32
	v_mov_b32_e32 v35, v28
	v_mov_b32_e32 v37, v29
	v_pk_add_f32 v[34:35], v[34:35], v[36:37]
	v_mov_b32_e32 v36, v30
	v_mov_b32_e32 v37, v26
	v_pk_add_f32 v[34:35], v[36:37], v[34:35]
	v_mov_b32_e32 v36, v31
	v_mov_b32_e32 v37, v27
	v_pk_add_f32 v[34:35], v[36:37], v[34:35]
	v_lshlrev_b32_e32 v39, 16, v143
	v_add_f32_e32 v34, v38, v34
	v_add_f32_e32 v34, v34, v35
	ds_bpermute_b32 v35, v54, v34
	v_and_b32_e32 v40, 0xffff0000, v143
	s_waitcnt lgkmcnt(0)
	v_add_f32_e32 v34, v34, v35
	ds_bpermute_b32 v35, v55, v34
	s_waitcnt lgkmcnt(0)
	v_add_f32_e32 v35, v34, v35
	v_fmac_f32_e32 v25, 0xbc800000, v35
	v_fmamk_f32 v24, v35, 0xbc800000, v24
	v_mul_f32_e32 v38, v25, v25
	v_fmac_f32_e32 v38, v24, v24
	v_fmamk_f32 v22, v35, 0xbc800000, v22
	v_fmac_f32_e32 v38, v22, v22
	v_fmac_f32_e32 v23, 0xbc800000, v35
	v_fmac_f32_e32 v38, v23, v23
	v_fmamk_f32 v20, v35, 0xbc800000, v20
	v_fmac_f32_e32 v38, v20, v20
	v_fmac_f32_e32 v21, 0xbc800000, v35
	v_mul_f32_e32 v34, 0x3c800000, v35
	v_fmac_f32_e32 v38, v21, v21
	v_fmamk_f32 v18, v35, 0xbc800000, v18
	v_fmac_f32_e32 v38, v18, v18
	v_fmac_f32_e32 v19, 0xbc800000, v35
	v_pk_add_f32 v[32:33], v[32:33], v[34:35] op_sel_hi:[1,0] neg_lo:[0,1] neg_hi:[0,1]
	v_fmac_f32_e32 v38, v19, v19
	v_pk_mul_f32 v[36:37], v[32:33], v[32:33]
	s_nop 0
	v_add_f32_e32 v35, v36, v38
	v_add_f32_e32 v35, v37, v35
	v_pk_add_f32 v[30:31], v[30:31], v[34:35] op_sel_hi:[1,0] neg_lo:[0,1] neg_hi:[0,1]
	v_and_b32_e32 v38, 0xffff0000, v142
	v_pk_mul_f32 v[36:37], v[30:31], v[30:31]
	s_nop 0
	v_add_f32_e32 v35, v36, v35
	v_add_f32_e32 v35, v37, v35
	v_pk_add_f32 v[28:29], v[28:29], v[34:35] op_sel_hi:[1,0] neg_lo:[0,1] neg_hi:[0,1]
	s_nop 0
	v_pk_mul_f32 v[36:37], v[28:29], v[28:29]
	s_nop 0
	v_add_f32_e32 v35, v36, v35
	v_pk_add_f32 v[26:27], v[26:27], v[34:35] op_sel_hi:[1,0] neg_lo:[0,1] neg_hi:[0,1]
	v_add_f32_e32 v36, v37, v35
	v_pk_mul_f32 v[34:35], v[26:27], v[26:27]
	v_lshlrev_b32_e32 v37, 16, v142
	v_add_f32_e32 v34, v34, v36
	v_add_f32_e32 v34, v35, v34
	ds_bpermute_b32 v35, v54, v34
	s_waitcnt lgkmcnt(0)
	v_add_f32_e32 v34, v34, v35
	ds_bpermute_b32 v35, v55, v34
	s_waitcnt lgkmcnt(0)
	v_add_f32_e32 v34, v34, v35
	v_fmamk_f32 v34, v34, 0x3c800000, v203
	v_cmp_gt_f32_e32 vcc, s28, v34
	v_mul_f32_e32 v35, 0x4b800000, v34
	s_nop 0
	v_cndmask_b32_e32 v34, v34, v35, vcc
	v_rsq_f32_e32 v34, v34
	s_nop 0
	v_mul_f32_e32 v35, 0x45800000, v34
	v_cndmask_b32_e32 v36, v34, v35, vcc
	v_cmp_gt_i32_e32 vcc, s37, v166
	v_mul_f32_e32 v24, v24, v36
	v_mul_f32_e32 v22, v22, v36
	v_cndmask_b32_e64 v34, 3, 1, vcc
	v_add_u32_e32 v34, v34, v166
	v_ashrrev_i32_e32 v35, 31, v34
	v_lshlrev_b64 v[34:35], 11, v[34:35]
	v_mul_f32_e32 v14, v14, v24
	v_mul_f32_e32 v24, v25, v36
	v_mul_f32_e32 v16, v16, v22
	v_mul_f32_e32 v22, v23, v36
	v_lshl_add_u64 v[34:35], s[8:9], 0, v[34:35]
	v_mul_f32_e32 v15, v15, v24
	v_mul_f32_e32 v17, v17, v22
	v_lshl_add_u64 v[34:35], v[34:35], 0, v[134:135]
	v_mul_f32_e32 v14, v14, v37
	v_mul_f32_e32 v15, v15, v38
	v_mul_f32_e32 v16, v16, v39
	v_mul_f32_e32 v17, v17, v40
	v_cvt_pk_bf16_f32 v14, v14, v15
	v_cvt_pk_bf16_f32 v15, v16, v17
	v_lshl_add_u64 v[16:17], v[34:35], 0, v[0:1]
	v_lshl_add_u64 v[22:23], v[16:17], 0, s[54:55]
	v_add_co_u32_e32 v16, vcc, s34, v16
	v_lshlrev_b32_e32 v0, 16, v140
	s_nop 0
	v_addc_co_u32_e32 v17, vcc, 0, v17, vcc
	global_store_dwordx2 v[16:17], v[14:15], off offset:1280
	v_mul_f32_e32 v17, v20, v36
	v_mul_f32_e32 v10, v10, v17
	v_mul_f32_e32 v0, v10, v0
	v_mul_f32_e32 v10, v21, v36
	v_mul_f32_e32 v10, v11, v10
	v_mul_f32_e32 v11, v18, v36
	v_and_b32_e32 v14, 0xffff0000, v140
	v_mul_f32_e32 v11, v12, v11
	v_mul_f32_e32 v12, v19, v36
	v_mul_f32_e32 v10, v10, v14
	v_mul_f32_e32 v12, v13, v12
	v_mul_f32_e32 v13, v32, v36
	v_cvt_pk_bf16_f32 v10, v0, v10
	v_lshlrev_b32_e32 v0, 16, v138
	v_mul_f32_e32 v6, v6, v13
	v_lshlrev_b32_e32 v15, 16, v141
	v_mul_f32_e32 v0, v6, v0
	v_mul_f32_e32 v6, v33, v36
	v_and_b32_e32 v16, 0xffff0000, v141
	v_mul_f32_e32 v11, v11, v15
	v_mul_f32_e32 v6, v7, v6
	v_mul_f32_e32 v7, v30, v36
	v_mul_f32_e32 v12, v12, v16
	v_cvt_pk_bf16_f32 v11, v11, v12
	global_store_dwordx2 v[22:23], v[10:11], off offset:32
	v_and_b32_e32 v10, 0xffff0000, v138
	v_mul_f32_e32 v7, v8, v7
	v_mul_f32_e32 v8, v31, v36
	v_mul_f32_e32 v6, v6, v10
	v_mul_f32_e32 v8, v9, v8
	v_mul_f32_e32 v9, v28, v36
	v_lshlrev_b32_e32 v11, 16, v139
	v_cvt_pk_bf16_f32 v6, v0, v6
	v_lshlrev_b32_e32 v0, 16, v136
	v_mul_f32_e32 v2, v2, v9
	v_and_b32_e32 v12, 0xffff0000, v139
	v_mul_f32_e32 v7, v7, v11
	v_mul_f32_e32 v0, v2, v0
	v_mul_f32_e32 v2, v29, v36
	v_mul_f32_e32 v8, v8, v12
	v_cvt_pk_bf16_f32 v7, v7, v8
	v_mul_f32_e32 v2, v3, v2
	v_mul_f32_e32 v3, v26, v36
	global_store_dwordx2 v[22:23], v[6:7], off offset:64
	v_and_b32_e32 v6, 0xffff0000, v136
	v_lshlrev_b32_e32 v7, 16, v137
	v_mul_f32_e32 v3, v4, v3
	v_mul_f32_e32 v4, v27, v36
	v_cmp_le_i32_e32 vcc, s2, v164
	v_and_b32_e32 v8, 0xffff0000, v137
	v_mul_f32_e32 v2, v2, v6
	v_mul_f32_e32 v3, v3, v7
	v_mul_f32_e32 v4, v5, v4
	s_or_b64 s[40:41], vcc, s[40:41]
	v_mul_f32_e32 v4, v4, v8
	v_cvt_pk_bf16_f32 v2, v0, v2
	v_cvt_pk_bf16_f32 v3, v3, v4
	global_store_dwordx2 v[22:23], v[2:3], off offset:96
	s_andn2_b64 exec, exec, s[40:41]
	s_cbranch_execnz .LBB0_149

.LBB0_181:
	s_add_i32 s88, s44, -2
	s_add_u32 s34, s34, 0x80
	s_addc_u32 s35, s35, 0
	s_add_u32 s89, s42, 0x100
	v_mov_b32_e32 v2, 0
	s_addc_u32 s90, s43, 0
	s_mov_b32 s2, 0
	s_add_i32 s91, s2, 2
	s_add_u32 s12, s34, 0x80
	s_addc_u32 s3, s35, 0
	s_add_i32 s13, 0, 0x10000
	v_add_u32_e32 v142, s13, v183
	ds_read_b128 v[130:133], v142
	ds_read_b128 v[134:137], v142 offset:1024
	ds_read_b128 v[138:141], v142 offset:2048
	ds_read_b128 v[142:145], v142 offset:3072
	s_cmp_eq_u32 s88, s2
	s_cselect_b32 s2, s0, s12
	s_cselect_b32 s3, s1, s3
	s_cselect_b32 s43, s41, s90
	s_cselect_b32 s42, s40, s89
	v_lshl_add_u64 v[190:191], s[34:35], 0, v[174:175]
	s_add_i32 m0, s55, 0xc000
	ds_read_b128 v[146:149], v184
	ds_read_b128 v[150:153], v184 offset:1024
	ds_read_b128 v[154:157], v184 offset:2048
	ds_read_b128 v[158:161], v184 offset:3072
	ds_read_b128 v[162:165], v184 offset:4096
	ds_read_b128 v[166:169], v184 offset:5120
	ds_read_b128 v[178:181], v184 offset:6144
	ds_read_b128 v[186:189], v184 offset:7168
	global_load_lds_dwordx4 v[190:191], off
	v_lshl_add_u64 v[190:191], s[34:35], 0, v[176:177]
	s_add_i32 m0, s55, 0xe000
	s_nop 0
	global_load_lds_dwordx4 v[190:191], off
	s_waitcnt lgkmcnt(8)
	s_add_i32 s92, 0, 0x14000
	s_add_i32 s12, s13, s54
	v_add_u32_e32 v185, s92, v183
	ds_read_b128 v[190:193], v185
	ds_read_b128 v[194:197], v185 offset:1024
	ds_read_b128 v[198:201], v185 offset:2048
	ds_read_b128 v[226:229], v185 offset:3072
	s_barrier
	s_waitcnt lgkmcnt(0)
	s_waitcnt lgkmcnt(0)
	s_nop 0
	v_mfma_f32_16x16x32_bf16 v[126:129], v[130:133], v[146:149], 0
	v_mfma_f32_16x16x32_bf16 v[122:125], v[138:141], v[146:149], 0
	v_mfma_f32_16x16x32_bf16 v[118:121], v[130:133], v[154:157], 0
	v_mfma_f32_16x16x32_bf16 v[114:117], v[138:141], v[154:157], 0
	v_mfma_f32_16x16x32_bf16 v[110:113], v[130:133], v[162:165], 0
	v_mfma_f32_16x16x32_bf16 v[106:109], v[138:141], v[162:165], 0
	v_mfma_f32_16x16x32_bf16 v[102:105], v[130:133], v[178:181], 0
	v_mfma_f32_16x16x32_bf16 v[98:101], v[138:141], v[178:181], 0
	v_mfma_f32_16x16x32_bf16 v[126:129], v[134:137], v[150:153], v[126:129]
	v_mfma_f32_16x16x32_bf16 v[122:125], v[142:145], v[150:153], v[122:125]
	v_mfma_f32_16x16x32_bf16 v[118:121], v[134:137], v[158:161], v[118:121]
	v_mfma_f32_16x16x32_bf16 v[114:117], v[142:145], v[158:161], v[114:117]
	v_mfma_f32_16x16x32_bf16 v[110:113], v[134:137], v[166:169], v[110:113]
	v_mfma_f32_16x16x32_bf16 v[106:109], v[142:145], v[166:169], v[106:109]
	v_mfma_f32_16x16x32_bf16 v[102:105], v[134:137], v[186:189], v[102:105]
	v_mfma_f32_16x16x32_bf16 v[98:101], v[142:145], v[186:189], v[98:101]
	s_waitcnt lgkmcnt(0)
	s_waitcnt lgkmcnt(0)
	v_mfma_f32_16x16x32_bf16 v[62:65], v[190:193], v[146:149], 0
	v_mfma_f32_16x16x32_bf16 v[58:61], v[198:201], v[146:149], 0
	v_mfma_f32_16x16x32_bf16 v[54:57], v[190:193], v[154:157], 0
	v_mfma_f32_16x16x32_bf16 v[50:53], v[198:201], v[154:157], 0
	v_mfma_f32_16x16x32_bf16 v[46:49], v[190:193], v[162:165], 0
	v_mfma_f32_16x16x32_bf16 v[42:45], v[198:201], v[162:165], 0
	v_mfma_f32_16x16x32_bf16 v[38:41], v[190:193], v[178:181], 0
	v_mfma_f32_16x16x32_bf16 v[34:37], v[198:201], v[178:181], 0
	v_mfma_f32_16x16x32_bf16 v[62:65], v[194:197], v[150:153], v[62:65]
	v_mfma_f32_16x16x32_bf16 v[58:61], v[226:229], v[150:153], v[58:61]
	v_mfma_f32_16x16x32_bf16 v[54:57], v[194:197], v[158:161], v[54:57]
	v_mfma_f32_16x16x32_bf16 v[50:53], v[226:229], v[158:161], v[50:53]
	v_mfma_f32_16x16x32_bf16 v[46:49], v[194:197], v[166:169], v[46:49]
	v_mfma_f32_16x16x32_bf16 v[42:45], v[226:229], v[166:169], v[42:45]
	v_mfma_f32_16x16x32_bf16 v[38:41], v[194:197], v[186:189], v[38:41]
	v_mfma_f32_16x16x32_bf16 v[34:37], v[226:229], v[186:189], v[34:37]
	s_mov_b32 m0, s55
	v_lshl_add_u64 v[234:235], s[2:3], 0, v[170:171]
	s_barrier
	ds_read_b128 v[146:149], v184 offset:16384
	ds_read_b128 v[150:153], v184 offset:17408
	ds_read_b128 v[154:157], v184 offset:18432
	ds_read_b128 v[158:161], v184 offset:19456
	ds_read_b128 v[162:165], v184 offset:20480
	ds_read_b128 v[166:169], v184 offset:21504
	ds_read_b128 v[178:181], v184 offset:22528
	ds_read_b128 v[186:189], v184 offset:23552
	global_load_lds_dwordx4 v[234:235], off
	v_lshl_add_u64 v[236:237], s[2:3], 0, v[172:173]
	s_mov_b32 m0, s58
	s_nop 0
	global_load_lds_dwordx4 v[236:237], off
	s_waitcnt vmcnt(2)
	s_barrier
	s_waitcnt lgkmcnt(0)
	s_waitcnt lgkmcnt(0)
	v_mfma_f32_16x16x32_bf16 v[94:97], v[130:133], v[146:149], 0
	v_mfma_f32_16x16x32_bf16 v[90:93], v[138:141], v[146:149], 0
	v_mfma_f32_16x16x32_bf16 v[86:89], v[130:133], v[154:157], 0
	v_mfma_f32_16x16x32_bf16 v[82:85], v[138:141], v[154:157], 0
	v_lshl_add_u64 v[230:231], s[42:43], 0, v[170:171]
	s_mov_b32 m0, s12
	s_nop 0
	global_load_lds_dwordx4 v[230:231], off
	v_mfma_f32_16x16x32_bf16 v[78:81], v[130:133], v[162:165], 0
	v_mfma_f32_16x16x32_bf16 v[74:77], v[138:141], v[162:165], 0
	v_mfma_f32_16x16x32_bf16 v[70:73], v[130:133], v[178:181], 0
	v_mfma_f32_16x16x32_bf16 v[66:69], v[138:141], v[178:181], 0
	v_mfma_f32_16x16x32_bf16 v[94:97], v[134:137], v[150:153], v[94:97]
	v_mfma_f32_16x16x32_bf16 v[90:93], v[142:145], v[150:153], v[90:93]
	v_mfma_f32_16x16x32_bf16 v[86:89], v[134:137], v[158:161], v[86:89]
	v_mfma_f32_16x16x32_bf16 v[82:85], v[142:145], v[158:161], v[82:85]
	v_lshl_add_u64 v[232:233], s[42:43], 0, v[172:173]
	s_add_i32 m0, s12, 0x2000
	s_nop 0
	global_load_lds_dwordx4 v[232:233], off
	s_nop 0
	v_mfma_f32_16x16x32_bf16 v[78:81], v[134:137], v[166:169], v[78:81]
	v_mfma_f32_16x16x32_bf16 v[74:77], v[142:145], v[166:169], v[74:77]
	v_mfma_f32_16x16x32_bf16 v[70:73], v[134:137], v[186:189], v[70:73]
	v_mfma_f32_16x16x32_bf16 v[66:69], v[142:145], v[186:189], v[66:69]
	v_mfma_f32_16x16x32_bf16 v[30:33], v[190:193], v[146:149], 0
	v_mfma_f32_16x16x32_bf16 v[26:29], v[198:201], v[146:149], 0
	v_mfma_f32_16x16x32_bf16 v[22:25], v[190:193], v[154:157], 0
	v_mfma_f32_16x16x32_bf16 v[18:21], v[198:201], v[154:157], 0
	s_add_u32 s12, s42, s18
	s_addc_u32 s13, s43, 0
	s_add_i32 s42, s92, s54
	v_lshl_add_u64 v[242:243], s[12:13], 0, v[170:171]
	s_mov_b32 m0, s42
	v_lshl_add_u64 v[244:245], s[12:13], 0, v[172:173]
	global_load_lds_dwordx4 v[242:243], off
	v_mfma_f32_16x16x32_bf16 v[14:17], v[190:193], v[162:165], 0
	v_mfma_f32_16x16x32_bf16 v[10:13], v[198:201], v[162:165], 0
	v_mfma_f32_16x16x32_bf16 v[6:9], v[190:193], v[178:181], 0
	v_mfma_f32_16x16x32_bf16 v[2:5], v[198:201], v[178:181], 0
	v_mfma_f32_16x16x32_bf16 v[30:33], v[194:197], v[150:153], v[30:33]
	v_mfma_f32_16x16x32_bf16 v[26:29], v[226:229], v[150:153], v[26:29]
	v_mfma_f32_16x16x32_bf16 v[22:25], v[194:197], v[158:161], v[22:25]
	v_mfma_f32_16x16x32_bf16 v[18:21], v[226:229], v[158:161], v[18:21]
	s_add_i32 m0, s42, 0x2000
	s_nop 0
	global_load_lds_dwordx4 v[244:245], off
	v_mfma_f32_16x16x32_bf16 v[14:17], v[194:197], v[166:169], v[14:17]
	v_mfma_f32_16x16x32_bf16 v[10:13], v[226:229], v[166:169], v[10:13]
	v_mfma_f32_16x16x32_bf16 v[6:9], v[194:197], v[186:189], v[6:9]
	v_mfma_f32_16x16x32_bf16 v[2:5], v[226:229], v[186:189], v[2:5]
	s_add_i32 s12, 0, 0x18000
	v_add_u32_e32 v142, s12, v183
	s_barrier
	ds_read_b128 v[130:133], v142
	ds_read_b128 v[134:137], v142 offset:1024
	ds_read_b128 v[138:141], v142 offset:2048
	ds_read_b128 v[142:145], v142 offset:3072
	s_add_u32 s2, s2, s18
	s_addc_u32 s3, s3, 0
	s_mov_b32 m0, s59
	v_lshl_add_u64 v[190:191], s[2:3], 0, v[170:171]
	ds_read_b128 v[146:149], v184 offset:32768
	ds_read_b128 v[150:153], v184 offset:33792
	ds_read_b128 v[154:157], v184 offset:34816
	ds_read_b128 v[158:161], v184 offset:35840
	ds_read_b128 v[162:165], v184 offset:36864
	ds_read_b128 v[166:169], v184 offset:37888
	ds_read_b128 v[178:181], v184 offset:38912
	ds_read_b128 v[186:189], v184 offset:39936
	global_load_lds_dwordx4 v[190:191], off
	v_lshl_add_u64 v[190:191], s[2:3], 0, v[172:173]
	s_mov_b32 m0, s77
	s_nop 0
	global_load_lds_dwordx4 v[190:191], off
	s_waitcnt lgkmcnt(8)
	s_add_i32 s2, 0, 0x1c000
	s_add_i32 s3, s12, s54
	v_add_u32_e32 v185, s2, v183
	ds_read_b128 v[190:193], v185
	ds_read_b128 v[194:197], v185 offset:1024
	ds_read_b128 v[198:201], v185 offset:2048
	ds_read_b128 v[226:229], v185 offset:3072
	s_barrier
	s_waitcnt lgkmcnt(0)
	s_waitcnt lgkmcnt(0)
	v_mfma_f32_16x16x32_bf16 v[126:129], v[130:133], v[146:149], v[126:129]
	v_mfma_f32_16x16x32_bf16 v[122:125], v[138:141], v[146:149], v[122:125]
	v_mfma_f32_16x16x32_bf16 v[118:121], v[130:133], v[154:157], v[118:121]
	v_mfma_f32_16x16x32_bf16 v[114:117], v[138:141], v[154:157], v[114:117]
	v_mfma_f32_16x16x32_bf16 v[110:113], v[130:133], v[162:165], v[110:113]
	v_mfma_f32_16x16x32_bf16 v[106:109], v[138:141], v[162:165], v[106:109]
	v_mfma_f32_16x16x32_bf16 v[102:105], v[130:133], v[178:181], v[102:105]
	v_mfma_f32_16x16x32_bf16 v[98:101], v[138:141], v[178:181], v[98:101]
	v_mfma_f32_16x16x32_bf16 v[126:129], v[134:137], v[150:153], v[126:129]
	v_mfma_f32_16x16x32_bf16 v[122:125], v[142:145], v[150:153], v[122:125]
	v_mfma_f32_16x16x32_bf16 v[118:121], v[134:137], v[158:161], v[118:121]
	v_mfma_f32_16x16x32_bf16 v[114:117], v[142:145], v[158:161], v[114:117]
	v_mfma_f32_16x16x32_bf16 v[110:113], v[134:137], v[166:169], v[110:113]
	v_mfma_f32_16x16x32_bf16 v[106:109], v[142:145], v[166:169], v[106:109]
	v_mfma_f32_16x16x32_bf16 v[102:105], v[134:137], v[186:189], v[102:105]
	v_mfma_f32_16x16x32_bf16 v[98:101], v[142:145], v[186:189], v[98:101]
	s_waitcnt lgkmcnt(0)
	s_waitcnt lgkmcnt(0)
	v_mfma_f32_16x16x32_bf16 v[62:65], v[190:193], v[146:149], v[62:65]
	v_mfma_f32_16x16x32_bf16 v[58:61], v[198:201], v[146:149], v[58:61]
	v_mfma_f32_16x16x32_bf16 v[54:57], v[190:193], v[154:157], v[54:57]
	v_mfma_f32_16x16x32_bf16 v[50:53], v[198:201], v[154:157], v[50:53]
	v_mfma_f32_16x16x32_bf16 v[46:49], v[190:193], v[162:165], v[46:49]
	v_mfma_f32_16x16x32_bf16 v[42:45], v[198:201], v[162:165], v[42:45]
	v_mfma_f32_16x16x32_bf16 v[38:41], v[190:193], v[178:181], v[38:41]
	v_mfma_f32_16x16x32_bf16 v[34:37], v[198:201], v[178:181], v[34:37]
	v_mfma_f32_16x16x32_bf16 v[62:65], v[194:197], v[150:153], v[62:65]
	v_mfma_f32_16x16x32_bf16 v[58:61], v[226:229], v[150:153], v[58:61]
	v_mfma_f32_16x16x32_bf16 v[54:57], v[194:197], v[158:161], v[54:57]
	v_mfma_f32_16x16x32_bf16 v[50:53], v[226:229], v[158:161], v[50:53]
	v_mfma_f32_16x16x32_bf16 v[46:49], v[194:197], v[166:169], v[46:49]
	v_mfma_f32_16x16x32_bf16 v[42:45], v[226:229], v[166:169], v[42:45]
	v_mfma_f32_16x16x32_bf16 v[38:41], v[194:197], v[186:189], v[38:41]
	v_mfma_f32_16x16x32_bf16 v[34:37], v[226:229], v[186:189], v[34:37]
	s_mov_b32 m0, s80
	v_lshl_add_u64 v[234:235], v[234:235], 0, s[20:21]
	s_barrier
	ds_read_b128 v[146:149], v184 offset:49152
	ds_read_b128 v[150:153], v184 offset:50176
	ds_read_b128 v[154:157], v184 offset:51200
	ds_read_b128 v[158:161], v184 offset:52224
	ds_read_b128 v[162:165], v184 offset:53248
	ds_read_b128 v[166:169], v184 offset:54272
	ds_read_b128 v[178:181], v184 offset:55296
	ds_read_b128 v[186:189], v184 offset:56320
	global_load_lds_dwordx4 v[234:235], off
	v_lshl_add_u64 v[236:237], v[236:237], 0, s[20:21]
	s_mov_b32 m0, s81
	s_nop 0
	global_load_lds_dwordx4 v[236:237], off
	s_waitcnt vmcnt(2)
	s_barrier
	s_waitcnt lgkmcnt(0)
	s_waitcnt lgkmcnt(0)
	v_mfma_f32_16x16x32_bf16 v[94:97], v[130:133], v[146:149], v[94:97]
	v_mfma_f32_16x16x32_bf16 v[90:93], v[138:141], v[146:149], v[90:93]
	v_mfma_f32_16x16x32_bf16 v[86:89], v[130:133], v[154:157], v[86:89]
	v_mfma_f32_16x16x32_bf16 v[82:85], v[138:141], v[154:157], v[82:85]
	v_lshl_add_u64 v[230:231], v[230:231], 0, s[20:21]
	s_mov_b32 m0, s3
	s_nop 0
	global_load_lds_dwordx4 v[230:231], off
	v_mfma_f32_16x16x32_bf16 v[78:81], v[130:133], v[162:165], v[78:81]
	v_mfma_f32_16x16x32_bf16 v[74:77], v[138:141], v[162:165], v[74:77]
	v_mfma_f32_16x16x32_bf16 v[70:73], v[130:133], v[178:181], v[70:73]
	v_mfma_f32_16x16x32_bf16 v[66:69], v[138:141], v[178:181], v[66:69]
	v_mfma_f32_16x16x32_bf16 v[94:97], v[134:137], v[150:153], v[94:97]
	v_mfma_f32_16x16x32_bf16 v[90:93], v[142:145], v[150:153], v[90:93]
	v_mfma_f32_16x16x32_bf16 v[86:89], v[134:137], v[158:161], v[86:89]
	v_mfma_f32_16x16x32_bf16 v[82:85], v[142:145], v[158:161], v[82:85]
	v_lshl_add_u64 v[230:231], v[232:233], 0, s[20:21]
	s_add_i32 m0, s3, 0x2000
	s_nop 0
	global_load_lds_dwordx4 v[230:231], off
	s_nop 0
	v_mfma_f32_16x16x32_bf16 v[78:81], v[134:137], v[166:169], v[78:81]
	v_mfma_f32_16x16x32_bf16 v[74:77], v[142:145], v[166:169], v[74:77]
	v_mfma_f32_16x16x32_bf16 v[70:73], v[134:137], v[186:189], v[70:73]
	v_mfma_f32_16x16x32_bf16 v[66:69], v[142:145], v[186:189], v[66:69]
	v_mfma_f32_16x16x32_bf16 v[30:33], v[190:193], v[146:149], v[30:33]
	v_mfma_f32_16x16x32_bf16 v[26:29], v[198:201], v[146:149], v[26:29]
	v_mfma_f32_16x16x32_bf16 v[22:25], v[190:193], v[154:157], v[22:25]
	v_mfma_f32_16x16x32_bf16 v[18:21], v[198:201], v[154:157], v[18:21]
	s_add_i32 s2, s2, s54
	v_lshl_add_u64 v[242:243], v[242:243], 0, s[20:21]
	s_mov_b32 m0, s2
	s_nop 0
	global_load_lds_dwordx4 v[242:243], off
	s_nop 0
	v_mfma_f32_16x16x32_bf16 v[14:17], v[190:193], v[162:165], v[14:17]
	v_mfma_f32_16x16x32_bf16 v[10:13], v[198:201], v[162:165], v[10:13]
	v_mfma_f32_16x16x32_bf16 v[6:9], v[190:193], v[178:181], v[6:9]
	v_mfma_f32_16x16x32_bf16 v[2:5], v[198:201], v[178:181], v[2:5]
	v_mfma_f32_16x16x32_bf16 v[30:33], v[194:197], v[150:153], v[30:33]
	v_mfma_f32_16x16x32_bf16 v[26:29], v[226:229], v[150:153], v[26:29]
	v_mfma_f32_16x16x32_bf16 v[22:25], v[194:197], v[158:161], v[22:25]
	v_mfma_f32_16x16x32_bf16 v[18:21], v[226:229], v[158:161], v[18:21]
	v_lshl_add_u64 v[244:245], v[244:245], 0, s[20:21]
	s_add_i32 m0, s2, 0x2000
	s_nop 0
	global_load_lds_dwordx4 v[244:245], off
	v_mfma_f32_16x16x32_bf16 v[14:17], v[194:197], v[166:169], v[14:17]
	v_mfma_f32_16x16x32_bf16 v[10:13], v[226:229], v[166:169], v[10:13]
	v_mfma_f32_16x16x32_bf16 v[6:9], v[194:197], v[186:189], v[6:9]
	v_mfma_f32_16x16x32_bf16 v[2:5], v[226:229], v[186:189], v[2:5]
	s_add_u32 s34, s34, 0x100
	s_addc_u32 s35, s35, 0
	s_add_u32 s89, s89, 0x100
	s_addc_u32 s90, s90, 0
	s_cmp_ge_i32 s91, s44
	s_mov_b32 s2, s91
	s_barrier
	s_cbranch_scc1 .Lpeel_x_182
.LBB0_182:
	s_add_i32 s91, s2, 2
	s_add_u32 s12, s34, 0x80
	s_addc_u32 s3, s35, 0
	s_add_i32 s13, 0, 0x10000
	v_add_u32_e32 v142, s13, v183
	ds_read_b128 v[130:133], v142
	ds_read_b128 v[134:137], v142 offset:1024
	ds_read_b128 v[138:141], v142 offset:2048
	ds_read_b128 v[142:145], v142 offset:3072
	s_cmp_eq_u32 s88, s2
	s_cselect_b32 s2, s0, s12
	s_cselect_b32 s3, s1, s3
	s_cselect_b32 s43, s41, s90
	s_cselect_b32 s42, s40, s89
	v_lshl_add_u64 v[190:191], s[34:35], 0, v[174:175]
	s_add_i32 m0, s55, 0xc000
	ds_read_b128 v[146:149], v184
	ds_read_b128 v[150:153], v184 offset:1024
	ds_read_b128 v[154:157], v184 offset:2048
	ds_read_b128 v[158:161], v184 offset:3072
	ds_read_b128 v[162:165], v184 offset:4096
	ds_read_b128 v[166:169], v184 offset:5120
	ds_read_b128 v[178:181], v184 offset:6144
	ds_read_b128 v[186:189], v184 offset:7168
	global_load_lds_dwordx4 v[190:191], off
	v_lshl_add_u64 v[190:191], s[34:35], 0, v[176:177]
	s_add_i32 m0, s55, 0xe000
	s_nop 0
	global_load_lds_dwordx4 v[190:191], off
	s_waitcnt lgkmcnt(8)
	s_add_i32 s92, 0, 0x14000
	s_add_i32 s12, s13, s54
	v_add_u32_e32 v185, s92, v183
	ds_read_b128 v[190:193], v185
	ds_read_b128 v[194:197], v185 offset:1024
	ds_read_b128 v[198:201], v185 offset:2048
	ds_read_b128 v[226:229], v185 offset:3072
	s_barrier
	s_waitcnt lgkmcnt(0)
	s_waitcnt lgkmcnt(0)
	v_mfma_f32_16x16x32_bf16 v[126:129], v[130:133], v[146:149], v[126:129]
	v_mfma_f32_16x16x32_bf16 v[122:125], v[138:141], v[146:149], v[122:125]
	v_mfma_f32_16x16x32_bf16 v[118:121], v[130:133], v[154:157], v[118:121]
	v_mfma_f32_16x16x32_bf16 v[114:117], v[138:141], v[154:157], v[114:117]
	v_mfma_f32_16x16x32_bf16 v[110:113], v[130:133], v[162:165], v[110:113]
	v_mfma_f32_16x16x32_bf16 v[106:109], v[138:141], v[162:165], v[106:109]
	v_mfma_f32_16x16x32_bf16 v[102:105], v[130:133], v[178:181], v[102:105]
	v_mfma_f32_16x16x32_bf16 v[98:101], v[138:141], v[178:181], v[98:101]
	v_mfma_f32_16x16x32_bf16 v[126:129], v[134:137], v[150:153], v[126:129]
	v_mfma_f32_16x16x32_bf16 v[122:125], v[142:145], v[150:153], v[122:125]
	v_mfma_f32_16x16x32_bf16 v[118:121], v[134:137], v[158:161], v[118:121]
	v_mfma_f32_16x16x32_bf16 v[114:117], v[142:145], v[158:161], v[114:117]
	v_mfma_f32_16x16x32_bf16 v[110:113], v[134:137], v[166:169], v[110:113]
	v_mfma_f32_16x16x32_bf16 v[106:109], v[142:145], v[166:169], v[106:109]
	v_mfma_f32_16x16x32_bf16 v[102:105], v[134:137], v[186:189], v[102:105]
	v_mfma_f32_16x16x32_bf16 v[98:101], v[142:145], v[186:189], v[98:101]
	s_waitcnt lgkmcnt(0)
	s_waitcnt lgkmcnt(0)
	v_mfma_f32_16x16x32_bf16 v[62:65], v[190:193], v[146:149], v[62:65]
	v_mfma_f32_16x16x32_bf16 v[58:61], v[198:201], v[146:149], v[58:61]
	v_mfma_f32_16x16x32_bf16 v[54:57], v[190:193], v[154:157], v[54:57]
	v_mfma_f32_16x16x32_bf16 v[50:53], v[198:201], v[154:157], v[50:53]
	v_mfma_f32_16x16x32_bf16 v[46:49], v[190:193], v[162:165], v[46:49]
	v_mfma_f32_16x16x32_bf16 v[42:45], v[198:201], v[162:165], v[42:45]
	v_mfma_f32_16x16x32_bf16 v[38:41], v[190:193], v[178:181], v[38:41]
	v_mfma_f32_16x16x32_bf16 v[34:37], v[198:201], v[178:181], v[34:37]
	v_mfma_f32_16x16x32_bf16 v[62:65], v[194:197], v[150:153], v[62:65]
	v_mfma_f32_16x16x32_bf16 v[58:61], v[226:229], v[150:153], v[58:61]
	v_mfma_f32_16x16x32_bf16 v[54:57], v[194:197], v[158:161], v[54:57]
	v_mfma_f32_16x16x32_bf16 v[50:53], v[226:229], v[158:161], v[50:53]
	v_mfma_f32_16x16x32_bf16 v[46:49], v[194:197], v[166:169], v[46:49]
	v_mfma_f32_16x16x32_bf16 v[42:45], v[226:229], v[166:169], v[42:45]
	v_mfma_f32_16x16x32_bf16 v[38:41], v[194:197], v[186:189], v[38:41]
	v_mfma_f32_16x16x32_bf16 v[34:37], v[226:229], v[186:189], v[34:37]
	s_mov_b32 m0, s55
	v_lshl_add_u64 v[234:235], s[2:3], 0, v[170:171]
	s_barrier
	ds_read_b128 v[146:149], v184 offset:16384
	ds_read_b128 v[150:153], v184 offset:17408
	ds_read_b128 v[154:157], v184 offset:18432
	ds_read_b128 v[158:161], v184 offset:19456
	ds_read_b128 v[162:165], v184 offset:20480
	ds_read_b128 v[166:169], v184 offset:21504
	ds_read_b128 v[178:181], v184 offset:22528
	ds_read_b128 v[186:189], v184 offset:23552
	global_load_lds_dwordx4 v[234:235], off
	v_lshl_add_u64 v[236:237], s[2:3], 0, v[172:173]
	s_mov_b32 m0, s58
	s_nop 0
	global_load_lds_dwordx4 v[236:237], off
	s_waitcnt vmcnt(2)
	s_barrier
	s_waitcnt lgkmcnt(0)
	s_waitcnt lgkmcnt(0)
	v_mfma_f32_16x16x32_bf16 v[94:97], v[130:133], v[146:149], v[94:97]
	v_mfma_f32_16x16x32_bf16 v[90:93], v[138:141], v[146:149], v[90:93]
	v_mfma_f32_16x16x32_bf16 v[86:89], v[130:133], v[154:157], v[86:89]
	v_mfma_f32_16x16x32_bf16 v[82:85], v[138:141], v[154:157], v[82:85]
	v_lshl_add_u64 v[230:231], s[42:43], 0, v[170:171]
	s_mov_b32 m0, s12
	s_nop 0
	global_load_lds_dwordx4 v[230:231], off
	v_mfma_f32_16x16x32_bf16 v[78:81], v[130:133], v[162:165], v[78:81]
	v_mfma_f32_16x16x32_bf16 v[74:77], v[138:141], v[162:165], v[74:77]
	v_mfma_f32_16x16x32_bf16 v[70:73], v[130:133], v[178:181], v[70:73]
	v_mfma_f32_16x16x32_bf16 v[66:69], v[138:141], v[178:181], v[66:69]
	v_mfma_f32_16x16x32_bf16 v[94:97], v[134:137], v[150:153], v[94:97]
	v_mfma_f32_16x16x32_bf16 v[90:93], v[142:145], v[150:153], v[90:93]
	v_mfma_f32_16x16x32_bf16 v[86:89], v[134:137], v[158:161], v[86:89]
	v_mfma_f32_16x16x32_bf16 v[82:85], v[142:145], v[158:161], v[82:85]
	v_lshl_add_u64 v[232:233], s[42:43], 0, v[172:173]
	s_add_i32 m0, s12, 0x2000
	s_nop 0
	global_load_lds_dwordx4 v[232:233], off
	s_nop 0
	v_mfma_f32_16x16x32_bf16 v[78:81], v[134:137], v[166:169], v[78:81]
	v_mfma_f32_16x16x32_bf16 v[74:77], v[142:145], v[166:169], v[74:77]
	v_mfma_f32_16x16x32_bf16 v[70:73], v[134:137], v[186:189], v[70:73]
	v_mfma_f32_16x16x32_bf16 v[66:69], v[142:145], v[186:189], v[66:69]
	v_mfma_f32_16x16x32_bf16 v[30:33], v[190:193], v[146:149], v[30:33]
	v_mfma_f32_16x16x32_bf16 v[26:29], v[198:201], v[146:149], v[26:29]
	v_mfma_f32_16x16x32_bf16 v[22:25], v[190:193], v[154:157], v[22:25]
	v_mfma_f32_16x16x32_bf16 v[18:21], v[198:201], v[154:157], v[18:21]
	s_add_u32 s12, s42, s18
	s_addc_u32 s13, s43, 0
	s_add_i32 s42, s92, s54
	v_lshl_add_u64 v[242:243], s[12:13], 0, v[170:171]
	s_mov_b32 m0, s42
	v_lshl_add_u64 v[244:245], s[12:13], 0, v[172:173]
	global_load_lds_dwordx4 v[242:243], off
	v_mfma_f32_16x16x32_bf16 v[14:17], v[190:193], v[162:165], v[14:17]
	v_mfma_f32_16x16x32_bf16 v[10:13], v[198:201], v[162:165], v[10:13]
	v_mfma_f32_16x16x32_bf16 v[6:9], v[190:193], v[178:181], v[6:9]
	v_mfma_f32_16x16x32_bf16 v[2:5], v[198:201], v[178:181], v[2:5]
	v_mfma_f32_16x16x32_bf16 v[30:33], v[194:197], v[150:153], v[30:33]
	v_mfma_f32_16x16x32_bf16 v[26:29], v[226:229], v[150:153], v[26:29]
	v_mfma_f32_16x16x32_bf16 v[22:25], v[194:197], v[158:161], v[22:25]
	v_mfma_f32_16x16x32_bf16 v[18:21], v[226:229], v[158:161], v[18:21]
	s_add_i32 m0, s42, 0x2000
	s_nop 0
	global_load_lds_dwordx4 v[244:245], off
	v_mfma_f32_16x16x32_bf16 v[14:17], v[194:197], v[166:169], v[14:17]
	v_mfma_f32_16x16x32_bf16 v[10:13], v[226:229], v[166:169], v[10:13]
	v_mfma_f32_16x16x32_bf16 v[6:9], v[194:197], v[186:189], v[6:9]
	v_mfma_f32_16x16x32_bf16 v[2:5], v[226:229], v[186:189], v[2:5]
	s_add_i32 s12, 0, 0x18000
	v_add_u32_e32 v142, s12, v183
	s_barrier
	ds_read_b128 v[130:133], v142
	ds_read_b128 v[134:137], v142 offset:1024
	ds_read_b128 v[138:141], v142 offset:2048
	ds_read_b128 v[142:145], v142 offset:3072
	s_add_u32 s2, s2, s18
	s_addc_u32 s3, s3, 0
	s_mov_b32 m0, s59
	v_lshl_add_u64 v[190:191], s[2:3], 0, v[170:171]
	ds_read_b128 v[146:149], v184 offset:32768
	ds_read_b128 v[150:153], v184 offset:33792
	ds_read_b128 v[154:157], v184 offset:34816
	ds_read_b128 v[158:161], v184 offset:35840
	ds_read_b128 v[162:165], v184 offset:36864
	ds_read_b128 v[166:169], v184 offset:37888
	ds_read_b128 v[178:181], v184 offset:38912
	ds_read_b128 v[186:189], v184 offset:39936
	global_load_lds_dwordx4 v[190:191], off
	v_lshl_add_u64 v[190:191], s[2:3], 0, v[172:173]
	s_mov_b32 m0, s77
	s_nop 0
	global_load_lds_dwordx4 v[190:191], off
	s_waitcnt lgkmcnt(8)
	s_add_i32 s2, 0, 0x1c000
	s_add_i32 s3, s12, s54
	v_add_u32_e32 v185, s2, v183
	ds_read_b128 v[190:193], v185
	ds_read_b128 v[194:197], v185 offset:1024
	ds_read_b128 v[198:201], v185 offset:2048
	ds_read_b128 v[226:229], v185 offset:3072
	s_barrier
	s_waitcnt lgkmcnt(0)
	s_waitcnt lgkmcnt(0)
	v_mfma_f32_16x16x32_bf16 v[126:129], v[130:133], v[146:149], v[126:129]
	v_mfma_f32_16x16x32_bf16 v[122:125], v[138:141], v[146:149], v[122:125]
	v_mfma_f32_16x16x32_bf16 v[118:121], v[130:133], v[154:157], v[118:121]
	v_mfma_f32_16x16x32_bf16 v[114:117], v[138:141], v[154:157], v[114:117]
	v_mfma_f32_16x16x32_bf16 v[110:113], v[130:133], v[162:165], v[110:113]
	v_mfma_f32_16x16x32_bf16 v[106:109], v[138:141], v[162:165], v[106:109]
	v_mfma_f32_16x16x32_bf16 v[102:105], v[130:133], v[178:181], v[102:105]
	v_mfma_f32_16x16x32_bf16 v[98:101], v[138:141], v[178:181], v[98:101]
	v_mfma_f32_16x16x32_bf16 v[126:129], v[134:137], v[150:153], v[126:129]
	v_mfma_f32_16x16x32_bf16 v[122:125], v[142:145], v[150:153], v[122:125]
	v_mfma_f32_16x16x32_bf16 v[118:121], v[134:137], v[158:161], v[118:121]
	v_mfma_f32_16x16x32_bf16 v[114:117], v[142:145], v[158:161], v[114:117]
	v_mfma_f32_16x16x32_bf16 v[110:113], v[134:137], v[166:169], v[110:113]
	v_mfma_f32_16x16x32_bf16 v[106:109], v[142:145], v[166:169], v[106:109]
	v_mfma_f32_16x16x32_bf16 v[102:105], v[134:137], v[186:189], v[102:105]
	v_mfma_f32_16x16x32_bf16 v[98:101], v[142:145], v[186:189], v[98:101]
	s_waitcnt lgkmcnt(0)
	s_waitcnt lgkmcnt(0)
	v_mfma_f32_16x16x32_bf16 v[62:65], v[190:193], v[146:149], v[62:65]
	v_mfma_f32_16x16x32_bf16 v[58:61], v[198:201], v[146:149], v[58:61]
	v_mfma_f32_16x16x32_bf16 v[54:57], v[190:193], v[154:157], v[54:57]
	v_mfma_f32_16x16x32_bf16 v[50:53], v[198:201], v[154:157], v[50:53]
	v_mfma_f32_16x16x32_bf16 v[46:49], v[190:193], v[162:165], v[46:49]
	v_mfma_f32_16x16x32_bf16 v[42:45], v[198:201], v[162:165], v[42:45]
	v_mfma_f32_16x16x32_bf16 v[38:41], v[190:193], v[178:181], v[38:41]
	v_mfma_f32_16x16x32_bf16 v[34:37], v[198:201], v[178:181], v[34:37]
	v_mfma_f32_16x16x32_bf16 v[62:65], v[194:197], v[150:153], v[62:65]
	v_mfma_f32_16x16x32_bf16 v[58:61], v[226:229], v[150:153], v[58:61]
	v_mfma_f32_16x16x32_bf16 v[54:57], v[194:197], v[158:161], v[54:57]
	v_mfma_f32_16x16x32_bf16 v[50:53], v[226:229], v[158:161], v[50:53]
	v_mfma_f32_16x16x32_bf16 v[46:49], v[194:197], v[166:169], v[46:49]
	v_mfma_f32_16x16x32_bf16 v[42:45], v[226:229], v[166:169], v[42:45]
	v_mfma_f32_16x16x32_bf16 v[38:41], v[194:197], v[186:189], v[38:41]
	v_mfma_f32_16x16x32_bf16 v[34:37], v[226:229], v[186:189], v[34:37]
	s_mov_b32 m0, s80
	v_lshl_add_u64 v[234:235], v[234:235], 0, s[20:21]
	s_barrier
	ds_read_b128 v[146:149], v184 offset:49152
	ds_read_b128 v[150:153], v184 offset:50176
	ds_read_b128 v[154:157], v184 offset:51200
	ds_read_b128 v[158:161], v184 offset:52224
	ds_read_b128 v[162:165], v184 offset:53248
	ds_read_b128 v[166:169], v184 offset:54272
	ds_read_b128 v[178:181], v184 offset:55296
	ds_read_b128 v[186:189], v184 offset:56320
	global_load_lds_dwordx4 v[234:235], off
	v_lshl_add_u64 v[236:237], v[236:237], 0, s[20:21]
	s_mov_b32 m0, s81
	s_nop 0
	global_load_lds_dwordx4 v[236:237], off
	s_waitcnt vmcnt(2)
	s_barrier
	s_waitcnt lgkmcnt(0)
	s_waitcnt lgkmcnt(0)
	v_mfma_f32_16x16x32_bf16 v[94:97], v[130:133], v[146:149], v[94:97]
	v_mfma_f32_16x16x32_bf16 v[90:93], v[138:141], v[146:149], v[90:93]
	v_mfma_f32_16x16x32_bf16 v[86:89], v[130:133], v[154:157], v[86:89]
	v_mfma_f32_16x16x32_bf16 v[82:85], v[138:141], v[154:157], v[82:85]
	v_lshl_add_u64 v[230:231], v[230:231], 0, s[20:21]
	s_mov_b32 m0, s3
	s_nop 0
	global_load_lds_dwordx4 v[230:231], off
	v_mfma_f32_16x16x32_bf16 v[78:81], v[130:133], v[162:165], v[78:81]
	v_mfma_f32_16x16x32_bf16 v[74:77], v[138:141], v[162:165], v[74:77]
	v_mfma_f32_16x16x32_bf16 v[70:73], v[130:133], v[178:181], v[70:73]
	v_mfma_f32_16x16x32_bf16 v[66:69], v[138:141], v[178:181], v[66:69]
	v_mfma_f32_16x16x32_bf16 v[94:97], v[134:137], v[150:153], v[94:97]
	v_mfma_f32_16x16x32_bf16 v[90:93], v[142:145], v[150:153], v[90:93]
	v_mfma_f32_16x16x32_bf16 v[86:89], v[134:137], v[158:161], v[86:89]
	v_mfma_f32_16x16x32_bf16 v[82:85], v[142:145], v[158:161], v[82:85]
	v_lshl_add_u64 v[230:231], v[232:233], 0, s[20:21]
	s_add_i32 m0, s3, 0x2000
	s_nop 0
	global_load_lds_dwordx4 v[230:231], off
	s_nop 0
	v_mfma_f32_16x16x32_bf16 v[78:81], v[134:137], v[166:169], v[78:81]
	v_mfma_f32_16x16x32_bf16 v[74:77], v[142:145], v[166:169], v[74:77]
	v_mfma_f32_16x16x32_bf16 v[70:73], v[134:137], v[186:189], v[70:73]
	v_mfma_f32_16x16x32_bf16 v[66:69], v[142:145], v[186:189], v[66:69]
	v_mfma_f32_16x16x32_bf16 v[30:33], v[190:193], v[146:149], v[30:33]
	v_mfma_f32_16x16x32_bf16 v[26:29], v[198:201], v[146:149], v[26:29]
	v_mfma_f32_16x16x32_bf16 v[22:25], v[190:193], v[154:157], v[22:25]
	v_mfma_f32_16x16x32_bf16 v[18:21], v[198:201], v[154:157], v[18:21]
	s_add_i32 s2, s2, s54
	v_lshl_add_u64 v[242:243], v[242:243], 0, s[20:21]
	s_mov_b32 m0, s2
	s_nop 0
	global_load_lds_dwordx4 v[242:243], off
	s_nop 0
	v_mfma_f32_16x16x32_bf16 v[14:17], v[190:193], v[162:165], v[14:17]
	v_mfma_f32_16x16x32_bf16 v[10:13], v[198:201], v[162:165], v[10:13]
	v_mfma_f32_16x16x32_bf16 v[6:9], v[190:193], v[178:181], v[6:9]
	v_mfma_f32_16x16x32_bf16 v[2:5], v[198:201], v[178:181], v[2:5]
	v_mfma_f32_16x16x32_bf16 v[30:33], v[194:197], v[150:153], v[30:33]
	v_mfma_f32_16x16x32_bf16 v[26:29], v[226:229], v[150:153], v[26:29]
	v_mfma_f32_16x16x32_bf16 v[22:25], v[194:197], v[158:161], v[22:25]
	v_mfma_f32_16x16x32_bf16 v[18:21], v[226:229], v[158:161], v[18:21]
	v_lshl_add_u64 v[244:245], v[244:245], 0, s[20:21]
	s_add_i32 m0, s2, 0x2000
	s_nop 0
	global_load_lds_dwordx4 v[244:245], off
	v_mfma_f32_16x16x32_bf16 v[14:17], v[194:197], v[166:169], v[14:17]
	v_mfma_f32_16x16x32_bf16 v[10:13], v[226:229], v[166:169], v[10:13]
	v_mfma_f32_16x16x32_bf16 v[6:9], v[194:197], v[186:189], v[6:9]
	v_mfma_f32_16x16x32_bf16 v[2:5], v[226:229], v[186:189], v[2:5]
	s_add_u32 s34, s34, 0x100
	s_addc_u32 s35, s35, 0
	s_add_u32 s89, s89, 0x100
	s_addc_u32 s90, s90, 0
	s_cmp_ge_i32 s91, s44
	s_mov_b32 s2, s91
	s_barrier
	s_cbranch_scc0 .LBB0_182

.LBB0_347:
	v_ashrrev_i32_e32 v7, 1, v4
	v_mul_hi_i32 v8, v7, s16
	v_lshrrev_b32_e32 v9, 31, v8
	v_add_u32_e32 v9, v8, v9
	v_mul_lo_u32 v8, v9, 6
	v_sub_u32_e32 v8, v7, v8
	v_mul_lo_u32 v10, v8, s18
	v_ashrrev_i32_e32 v11, 31, v10
	v_lshlrev_b32_e32 v12, 7, v9
	v_lshl_or_b32 v7, v9, 1, v6
	v_ashrrev_i32_e32 v9, 31, v8
	v_mov_b32_e32 v0, v202
	v_ashrrev_i32_e32 v13, 31, v12
	v_lshlrev_b64 v[10:11], 1, v[10:11]
	v_mad_i64_i32 v[8:9], s[2:3], v7, 6, v[8:9]
	v_lshl_add_u64 v[14:15], v[2:3], 0, v[10:11]
	v_lshlrev_b64 v[12:13], 1, v[12:13]
	v_lshlrev_b64 v[172:173], 14, v[8:9]
	v_bfe_u32 v174, v0, 4, 2
	v_lshl_add_u64 v[8:9], s[12:13], 0, v[10:11]
	v_lshl_add_u64 v[14:15], v[14:15], 0, v[12:13]
	v_and_b32_e32 v7, 15, v0
	v_lshl_add_u64 v[8:9], v[8:9], 0, v[12:13]
	v_lshlrev_b32_e32 v0, 4, v174
	v_lshl_add_u64 v[8:9], v[8:9], 0, v[0:1]
	v_lshl_add_u64 v[10:11], v[14:15], 0, v[0:1]
	v_mul_u32_u24_e32 v0, 0x4100, v7
	v_lshlrev_b32_e32 v0, 1, v0
	v_lshl_add_u64 v[104:105], v[10:11], 0, v[0:1]
	v_lshl_add_u64 v[108:109], v[8:9], 0, v[0:1]
	v_add_co_u32_e32 v8, vcc, s17, v104
	v_lshl_add_u64 v[132:133], v[108:109], 0, s[22:23]
	s_nop 0
	v_addc_co_u32_e32 v9, vcc, 0, v105, vcc
	v_add_co_u32_e32 v12, vcc, s17, v108
	v_lshl_add_u64 v[128:129], v[104:105], 0, s[22:23]
	s_nop 0
	v_addc_co_u32_e32 v13, vcc, 0, v109, vcc
	v_add_co_u32_e32 v16, vcc, s18, v104
	v_lshl_add_u64 v[124:125], v[108:109], 0, s[34:35]
	s_nop 0
	v_addc_co_u32_e32 v17, vcc, 0, v105, vcc
	v_add_co_u32_e32 v20, vcc, s18, v108
	v_lshl_add_u64 v[120:121], v[104:105], 0, s[34:35]
	s_nop 0
	v_addc_co_u32_e32 v21, vcc, 0, v109, vcc
	v_add_co_u32_e32 v24, vcc, s19, v104
	v_lshl_add_u64 v[116:117], v[108:109], 0, s[38:39]
	s_nop 0
	v_addc_co_u32_e32 v25, vcc, 0, v105, vcc
	v_add_co_u32_e32 v28, vcc, s19, v108
	v_lshl_add_u64 v[112:113], v[104:105], 0, s[38:39]
	s_nop 0
	v_addc_co_u32_e32 v29, vcc, 0, v109, vcc
	global_load_dwordx4 v[8:11], v[8:9], off
	v_or_b32_e32 v175, 16, v7
	global_load_dwordx4 v[12:15], v[12:13], off
	v_or_b32_e32 v176, 32, v7
	global_load_dwordx4 v[16:19], v[16:17], off
	v_or_b32_e32 v177, 48, v7
	global_load_dwordx4 v[20:23], v[20:21], off
	v_add_u32_e32 v4, v4, v5
	global_load_dwordx4 v[24:27], v[24:25], off
	s_nop 0
	global_load_dwordx4 v[28:31], v[28:29], off
	s_nop 0
	global_load_dwordx4 v[32:35], v[104:105], off
	global_load_dwordx4 v[36:39], v[108:109], off
	global_load_dwordx4 v[40:43], v[104:105], off offset:64
	global_load_dwordx4 v[44:47], v[108:109], off offset:64
	global_load_dwordx4 v[48:51], v[112:113], off offset:64
	global_load_dwordx4 v[52:55], v[116:117], off offset:64
	global_load_dwordx4 v[56:59], v[120:121], off offset:64
	global_load_dwordx4 v[60:63], v[124:125], off offset:64
	global_load_dwordx4 v[64:67], v[128:129], off offset:64
	global_load_dwordx4 v[68:71], v[132:133], off offset:64
	global_load_dwordx4 v[72:75], v[104:105], off offset:128
	global_load_dwordx4 v[76:79], v[108:109], off offset:128
	global_load_dwordx4 v[80:83], v[112:113], off offset:128
	global_load_dwordx4 v[84:87], v[116:117], off offset:128
	global_load_dwordx4 v[88:91], v[120:121], off offset:128
	global_load_dwordx4 v[92:95], v[124:125], off offset:128
	global_load_dwordx4 v[96:99], v[128:129], off offset:128
	global_load_dwordx4 v[100:103], v[132:133], off offset:128
	s_nop 0
	global_load_dwordx4 v[104:107], v[104:105], off offset:192
	s_nop 0
	global_load_dwordx4 v[108:111], v[108:109], off offset:192
	s_nop 0
	global_load_dwordx4 v[112:115], v[112:113], off offset:192
	s_nop 0
	global_load_dwordx4 v[116:119], v[116:117], off offset:192
	s_nop 0
	global_load_dwordx4 v[120:123], v[120:121], off offset:192
	s_nop 0
	global_load_dwordx4 v[124:127], v[124:125], off offset:192
	s_nop 0
	global_load_dwordx4 v[128:131], v[128:129], off offset:192
	s_nop 0
	global_load_dwordx4 v[132:135], v[132:133], off offset:192
	s_movk_i32 s2, 0x617
	v_cmp_lt_i32_e32 vcc, s2, v4
	s_or_b64 s[14:15], vcc, s[14:15]
	s_waitcnt vmcnt(24)
	s_nop 0
	v_mfma_f32_16x16x32_bf16 v[136:139], v[36:39], v[32:35], 0
	s_waitcnt vmcnt(16)
	v_mfma_f32_16x16x32_bf16 v[140:143], v[36:39], v[24:27], 0
	s_waitcnt vmcnt(8)
	v_mfma_f32_16x16x32_bf16 v[144:147], v[36:39], v[16:19], 0
	s_waitcnt vmcnt(0)
	s_nop 0
	v_mfma_f32_16x16x32_bf16 v[36:39], v[36:39], v[8:11], 0
	v_mfma_f32_16x16x32_bf16 v[148:151], v[28:31], v[32:35], 0
	v_mfma_f32_16x16x32_bf16 v[152:155], v[28:31], v[24:27], 0
	v_mfma_f32_16x16x32_bf16 v[156:159], v[28:31], v[16:19], 0
	v_mfma_f32_16x16x32_bf16 v[28:31], v[28:31], v[8:11], 0
	v_mfma_f32_16x16x32_bf16 v[160:163], v[20:23], v[32:35], 0
	v_mfma_f32_16x16x32_bf16 v[164:167], v[20:23], v[24:27], 0
	v_mfma_f32_16x16x32_bf16 v[168:171], v[20:23], v[16:19], 0
	v_mfma_f32_16x16x32_bf16 v[20:23], v[20:23], v[8:11], 0
	v_mfma_f32_16x16x32_bf16 v[32:35], v[12:15], v[32:35], 0
	v_mfma_f32_16x16x32_bf16 v[24:27], v[12:15], v[24:27], 0
	v_mfma_f32_16x16x32_bf16 v[16:19], v[12:15], v[16:19], 0
	v_mfma_f32_16x16x32_bf16 v[8:11], v[12:15], v[8:11], 0
	v_mfma_f32_16x16x32_bf16 v[12:15], v[44:47], v[40:43], v[136:139]
	v_mfma_f32_16x16x32_bf16 v[136:139], v[44:47], v[64:67], v[140:143]
	v_mfma_f32_16x16x32_bf16 v[140:143], v[44:47], v[56:59], v[144:147]
	v_mfma_f32_16x16x32_bf16 v[36:39], v[44:47], v[48:51], v[36:39]
	v_mfma_f32_16x16x32_bf16 v[12:15], v[76:79], v[72:75], v[12:15]
	v_mfma_f32_16x16x32_bf16 v[44:47], v[68:71], v[40:43], v[148:151]
	v_mfma_f32_16x16x32_bf16 v[144:147], v[68:71], v[64:67], v[152:155]
	v_mfma_f32_16x16x32_bf16 v[148:151], v[68:71], v[56:59], v[156:159]
	v_mfma_f32_16x16x32_bf16 v[28:31], v[68:71], v[48:51], v[28:31]
	v_mfma_f32_16x16x32_bf16 v[68:71], v[60:63], v[40:43], v[160:163]
	v_mfma_f32_16x16x32_bf16 v[32:35], v[52:55], v[40:43], v[32:35]
	v_mfma_f32_16x16x32_bf16 v[40:43], v[76:79], v[96:99], v[136:139]
	v_mfma_f32_16x16x32_bf16 v[20:23], v[60:63], v[48:51], v[20:23]
	v_mfma_f32_16x16x32_bf16 v[8:11], v[52:55], v[48:51], v[8:11]
	v_mfma_f32_16x16x32_bf16 v[48:51], v[76:79], v[88:91], v[140:143]
	v_mfma_f32_16x16x32_bf16 v[36:39], v[76:79], v[80:83], v[36:39]
	v_lshlrev_b32_e32 v76, 8, v174
	v_or_b32_e32 v0, v76, v7
	v_lshlrev_b32_e32 v0, 2, v0
	v_mfma_f32_16x16x32_bf16 v[12:15], v[108:111], v[104:107], v[12:15]
	v_mfma_f32_16x16x32_bf16 v[152:155], v[60:63], v[64:67], v[164:167]
	v_mfma_f32_16x16x32_bf16 v[156:159], v[60:63], v[56:59], v[168:171]
	v_mfma_f32_16x16x32_bf16 v[44:47], v[100:103], v[72:75], v[44:47]
	v_mfma_f32_16x16x32_bf16 v[60:63], v[92:95], v[72:75], v[68:71]
	v_mfma_f32_16x16x32_bf16 v[32:35], v[84:87], v[72:75], v[32:35]
	v_lshl_add_u64 v[72:73], s[94:95], 0, v[172:173]
	v_lshl_add_u64 v[74:75], v[72:73], 0, v[0:1]
	v_or_b32_e32 v0, v76, v175
	v_mfma_f32_16x16x32_bf16 v[40:43], v[108:111], v[128:131], v[40:43]
	v_lshlrev_b32_e32 v0, 2, v0
	global_store_dword v[74:75], v12, off
	global_store_dword v[74:75], v13, off offset:256
	global_store_dword v[74:75], v14, off offset:512
	global_store_dword v[74:75], v15, off offset:768
	s_nop 2
	global_store_dword v[74:75], v40, off offset:64
	v_lshl_add_u64 v[12:13], v[72:73], 0, v[0:1]
	v_mfma_f32_16x16x32_bf16 v[48:51], v[108:111], v[120:123], v[48:51]
	v_or_b32_e32 v0, v76, v176
	v_lshlrev_b32_e32 v0, 2, v0
	global_store_dword v[12:13], v41, off offset:256
	global_store_dword v[12:13], v42, off offset:512
	global_store_dword v[12:13], v43, off offset:768
	s_nop 2
	global_store_dword v[74:75], v48, off offset:128
	v_mfma_f32_16x16x32_bf16 v[36:39], v[108:111], v[112:115], v[36:39]
	v_lshl_add_u64 v[12:13], v[72:73], 0, v[0:1]
	v_or_b32_e32 v0, v76, v177
	v_lshlrev_b32_e32 v0, 2, v0
	v_or_b32_e32 v14, 0x400, v76
	v_mfma_f32_16x16x32_bf16 v[44:47], v[132:135], v[104:107], v[44:47]
	global_store_dword v[12:13], v49, off offset:256
	global_store_dword v[12:13], v50, off offset:512
	global_store_dword v[12:13], v51, off offset:768
	global_store_dword v[74:75], v36, off offset:192
	v_lshl_add_u64 v[12:13], v[72:73], 0, v[0:1]
	v_or_b32_e32 v0, v14, v7
	v_lshlrev_b32_e32 v0, 2, v0
	v_or_b32_e32 v15, 0x440, v76
	global_store_dword v[12:13], v37, off offset:256
	global_store_dword v[12:13], v38, off offset:512
	global_store_dword v[12:13], v39, off offset:768
	v_lshl_add_u64 v[12:13], v[72:73], 0, v[0:1]
	v_or_b32_e32 v0, v15, v7
	v_lshlrev_b32_e32 v0, 2, v0
	v_or_b32_e32 v36, 0x480, v76
	v_mfma_f32_16x16x32_bf16 v[24:27], v[52:55], v[64:67], v[24:27]
	global_store_dword v[12:13], v44, off
	v_lshl_add_u64 v[12:13], v[72:73], 0, v[0:1]
	v_or_b32_e32 v0, v36, v7
	v_mfma_f32_16x16x32_bf16 v[16:19], v[52:55], v[56:59], v[16:19]
	v_lshlrev_b32_e32 v0, 2, v0
	v_or_b32_e32 v37, 0x4c0, v76
	global_store_dword v[12:13], v45, off
	v_mfma_f32_16x16x32_bf16 v[52:55], v[100:103], v[96:99], v[144:147]
	v_lshl_add_u64 v[12:13], v[72:73], 0, v[0:1]
	v_or_b32_e32 v0, v37, v7
	v_lshlrev_b32_e32 v0, 2, v0
	v_mfma_f32_16x16x32_bf16 v[52:55], v[132:135], v[128:131], v[52:55]
	global_store_dword v[12:13], v46, off
	v_lshl_add_u64 v[12:13], v[72:73], 0, v[0:1]
	v_or_b32_e32 v0, v14, v175
	v_lshlrev_b32_e32 v0, 2, v0
	global_store_dword v[12:13], v47, off
	v_lshl_add_u64 v[12:13], v[72:73], 0, v[0:1]
	v_or_b32_e32 v0, v15, v175
	v_lshlrev_b32_e32 v0, 2, v0
	v_mfma_f32_16x16x32_bf16 v[56:59], v[100:103], v[88:91], v[148:151]
	global_store_dword v[12:13], v52, off
	v_lshl_add_u64 v[12:13], v[72:73], 0, v[0:1]
	v_or_b32_e32 v0, v36, v175
	v_lshlrev_b32_e32 v0, 2, v0
	global_store_dword v[12:13], v53, off
	v_lshl_add_u64 v[12:13], v[72:73], 0, v[0:1]
	v_or_b32_e32 v0, v37, v175
	v_lshlrev_b32_e32 v0, 2, v0
	v_mfma_f32_16x16x32_bf16 v[56:59], v[132:135], v[120:123], v[56:59]
	global_store_dword v[12:13], v54, off
	v_lshl_add_u64 v[12:13], v[72:73], 0, v[0:1]
	v_or_b32_e32 v0, v14, v176
	v_lshlrev_b32_e32 v0, 2, v0
	global_store_dword v[12:13], v55, off
	v_lshl_add_u64 v[12:13], v[72:73], 0, v[0:1]
	v_or_b32_e32 v0, v15, v176
	v_lshlrev_b32_e32 v0, 2, v0
	v_mfma_f32_16x16x32_bf16 v[28:31], v[100:103], v[80:83], v[28:31]
	global_store_dword v[12:13], v56, off
	v_lshl_add_u64 v[12:13], v[72:73], 0, v[0:1]
	v_or_b32_e32 v0, v36, v176
	v_lshlrev_b32_e32 v0, 2, v0
	global_store_dword v[12:13], v57, off
	v_lshl_add_u64 v[12:13], v[72:73], 0, v[0:1]
	v_or_b32_e32 v0, v37, v176
	v_lshlrev_b32_e32 v0, 2, v0
	v_mfma_f32_16x16x32_bf16 v[28:31], v[132:135], v[112:115], v[28:31]
	global_store_dword v[12:13], v58, off
	v_lshl_add_u64 v[12:13], v[72:73], 0, v[0:1]
	v_or_b32_e32 v0, v14, v177
	v_lshlrev_b32_e32 v0, 2, v0
	global_store_dword v[12:13], v59, off
	v_lshl_add_u64 v[12:13], v[72:73], 0, v[0:1]
	v_or_b32_e32 v0, v15, v177
	v_lshlrev_b32_e32 v0, 2, v0
	global_store_dword v[12:13], v28, off
	v_lshl_add_u64 v[12:13], v[72:73], 0, v[0:1]
	v_or_b32_e32 v0, v36, v177
	v_lshlrev_b32_e32 v0, 2, v0
	global_store_dword v[12:13], v29, off
	v_lshl_add_u64 v[12:13], v[72:73], 0, v[0:1]
	v_or_b32_e32 v0, v37, v177
	v_lshlrev_b32_e32 v0, 2, v0
	v_or_b32_e32 v14, 0x800, v76
	v_mfma_f32_16x16x32_bf16 v[60:63], v[124:127], v[104:107], v[60:63]
	global_store_dword v[12:13], v30, off
	v_lshl_add_u64 v[12:13], v[72:73], 0, v[0:1]
	v_or_b32_e32 v0, v14, v7
	v_lshlrev_b32_e32 v0, 2, v0
	v_or_b32_e32 v15, 0x840, v76
	global_store_dword v[12:13], v31, off
	v_lshl_add_u64 v[12:13], v[72:73], 0, v[0:1]
	v_or_b32_e32 v0, v15, v7
	v_lshlrev_b32_e32 v0, 2, v0
	v_or_b32_e32 v28, 0x880, v76
	v_mfma_f32_16x16x32_bf16 v[64:67], v[92:95], v[96:99], v[152:155]
	global_store_dword v[12:13], v60, off
	v_lshl_add_u64 v[12:13], v[72:73], 0, v[0:1]
	v_or_b32_e32 v0, v28, v7
	v_lshlrev_b32_e32 v0, 2, v0
	v_or_b32_e32 v29, 0x8c0, v76
	global_store_dword v[12:13], v61, off
	v_lshl_add_u64 v[12:13], v[72:73], 0, v[0:1]
	v_or_b32_e32 v0, v29, v7
	v_lshlrev_b32_e32 v0, 2, v0
	v_mfma_f32_16x16x32_bf16 v[64:67], v[124:127], v[128:131], v[64:67]
	global_store_dword v[12:13], v62, off
	v_lshl_add_u64 v[12:13], v[72:73], 0, v[0:1]
	v_or_b32_e32 v0, v14, v175
	v_lshlrev_b32_e32 v0, 2, v0
	global_store_dword v[12:13], v63, off
	v_lshl_add_u64 v[12:13], v[72:73], 0, v[0:1]
	v_or_b32_e32 v0, v15, v175
	v_lshlrev_b32_e32 v0, 2, v0
	v_mfma_f32_16x16x32_bf16 v[68:71], v[92:95], v[88:91], v[156:159]
	global_store_dword v[12:13], v64, off
	v_lshl_add_u64 v[12:13], v[72:73], 0, v[0:1]
	v_or_b32_e32 v0, v28, v175
	v_lshlrev_b32_e32 v0, 2, v0
	global_store_dword v[12:13], v65, off
	v_lshl_add_u64 v[12:13], v[72:73], 0, v[0:1]
	v_or_b32_e32 v0, v29, v175
	v_lshlrev_b32_e32 v0, 2, v0
	v_mfma_f32_16x16x32_bf16 v[68:71], v[124:127], v[120:123], v[68:71]
	global_store_dword v[12:13], v66, off
	v_lshl_add_u64 v[12:13], v[72:73], 0, v[0:1]
	v_or_b32_e32 v0, v14, v176
	v_lshlrev_b32_e32 v0, 2, v0
	global_store_dword v[12:13], v67, off
	v_lshl_add_u64 v[12:13], v[72:73], 0, v[0:1]
	v_or_b32_e32 v0, v15, v176
	v_lshlrev_b32_e32 v0, 2, v0
	v_mfma_f32_16x16x32_bf16 v[20:23], v[92:95], v[80:83], v[20:23]
	global_store_dword v[12:13], v68, off
	v_lshl_add_u64 v[12:13], v[72:73], 0, v[0:1]
	v_or_b32_e32 v0, v28, v176
	v_lshlrev_b32_e32 v0, 2, v0
	global_store_dword v[12:13], v69, off
	v_lshl_add_u64 v[12:13], v[72:73], 0, v[0:1]
	v_or_b32_e32 v0, v29, v176
	v_lshlrev_b32_e32 v0, 2, v0
	v_mfma_f32_16x16x32_bf16 v[20:23], v[124:127], v[112:115], v[20:23]
	global_store_dword v[12:13], v70, off
	v_lshl_add_u64 v[12:13], v[72:73], 0, v[0:1]
	v_or_b32_e32 v0, v14, v177
	v_lshlrev_b32_e32 v0, 2, v0
	global_store_dword v[12:13], v71, off
	v_lshl_add_u64 v[12:13], v[72:73], 0, v[0:1]
	v_or_b32_e32 v0, v15, v177
	v_lshlrev_b32_e32 v0, 2, v0
	global_store_dword v[12:13], v20, off
	v_lshl_add_u64 v[12:13], v[72:73], 0, v[0:1]
	v_or_b32_e32 v0, v28, v177
	v_lshlrev_b32_e32 v0, 2, v0
	global_store_dword v[12:13], v21, off
	v_lshl_add_u64 v[12:13], v[72:73], 0, v[0:1]
	v_or_b32_e32 v0, v29, v177
	v_lshlrev_b32_e32 v0, 2, v0
	v_or_b32_e32 v14, 0xc00, v76
	v_mfma_f32_16x16x32_bf16 v[32:35], v[116:119], v[104:107], v[32:35]
	global_store_dword v[12:13], v22, off
	v_lshl_add_u64 v[12:13], v[72:73], 0, v[0:1]
	v_or_b32_e32 v0, v14, v7
	v_lshlrev_b32_e32 v0, 2, v0
	v_or_b32_e32 v15, 0xc40, v76
	global_store_dword v[12:13], v23, off
	v_lshl_add_u64 v[12:13], v[72:73], 0, v[0:1]
	v_or_b32_e32 v0, v15, v7
	v_lshlrev_b32_e32 v0, 2, v0
	v_or_b32_e32 v20, 0xc80, v76
	v_mfma_f32_16x16x32_bf16 v[24:27], v[84:87], v[96:99], v[24:27]
	global_store_dword v[12:13], v32, off
	v_lshl_add_u64 v[12:13], v[72:73], 0, v[0:1]
	v_or_b32_e32 v0, v20, v7
	v_lshlrev_b32_e32 v0, 2, v0
	v_or_b32_e32 v21, 0xcc0, v76
	global_store_dword v[12:13], v33, off
	v_lshl_add_u64 v[12:13], v[72:73], 0, v[0:1]
	v_or_b32_e32 v0, v21, v7
	v_lshlrev_b32_e32 v0, 2, v0
	v_mfma_f32_16x16x32_bf16 v[24:27], v[116:119], v[128:131], v[24:27]
	global_store_dword v[12:13], v34, off
	v_lshl_add_u64 v[12:13], v[72:73], 0, v[0:1]
	v_or_b32_e32 v0, v14, v175
	v_lshlrev_b32_e32 v0, 2, v0
	global_store_dword v[12:13], v35, off
	v_lshl_add_u64 v[12:13], v[72:73], 0, v[0:1]
	v_or_b32_e32 v0, v15, v175
	v_lshlrev_b32_e32 v0, 2, v0
	v_mfma_f32_16x16x32_bf16 v[16:19], v[84:87], v[88:91], v[16:19]
	global_store_dword v[12:13], v24, off
	v_lshl_add_u64 v[12:13], v[72:73], 0, v[0:1]
	v_or_b32_e32 v0, v20, v175
	v_lshlrev_b32_e32 v0, 2, v0
	global_store_dword v[12:13], v25, off
	v_lshl_add_u64 v[12:13], v[72:73], 0, v[0:1]
	v_or_b32_e32 v0, v21, v175
	v_lshlrev_b32_e32 v0, 2, v0
	v_mfma_f32_16x16x32_bf16 v[16:19], v[116:119], v[120:123], v[16:19]
	global_store_dword v[12:13], v26, off
	v_lshl_add_u64 v[12:13], v[72:73], 0, v[0:1]
	v_or_b32_e32 v0, v14, v176
	v_lshlrev_b32_e32 v0, 2, v0
	global_store_dword v[12:13], v27, off
	v_lshl_add_u64 v[12:13], v[72:73], 0, v[0:1]
	v_or_b32_e32 v0, v15, v176
	v_lshlrev_b32_e32 v0, 2, v0
	v_mfma_f32_16x16x32_bf16 v[8:11], v[84:87], v[80:83], v[8:11]
	global_store_dword v[12:13], v16, off
	v_lshl_add_u64 v[12:13], v[72:73], 0, v[0:1]
	v_or_b32_e32 v0, v20, v176
	v_lshlrev_b32_e32 v0, 2, v0
	global_store_dword v[12:13], v17, off
	v_lshl_add_u64 v[12:13], v[72:73], 0, v[0:1]
	v_or_b32_e32 v0, v21, v176
	v_lshlrev_b32_e32 v0, 2, v0
	v_mfma_f32_16x16x32_bf16 v[8:11], v[116:119], v[112:115], v[8:11]
	global_store_dword v[12:13], v18, off
	v_lshl_add_u64 v[12:13], v[72:73], 0, v[0:1]
	v_or_b32_e32 v0, v14, v177
	v_lshlrev_b32_e32 v0, 2, v0
	global_store_dword v[12:13], v19, off
	v_lshl_add_u64 v[12:13], v[72:73], 0, v[0:1]
	v_or_b32_e32 v0, v15, v177
	v_lshlrev_b32_e32 v0, 2, v0
	global_store_dword v[12:13], v8, off
	v_lshl_add_u64 v[12:13], v[72:73], 0, v[0:1]
	v_or_b32_e32 v0, v20, v177
	v_lshlrev_b32_e32 v0, 2, v0
	global_store_dword v[12:13], v9, off
	v_lshl_add_u64 v[8:9], v[72:73], 0, v[0:1]
	v_or_b32_e32 v0, v21, v177
	v_lshlrev_b32_e32 v0, 2, v0
	global_store_dword v[8:9], v10, off
	v_lshl_add_u64 v[8:9], v[72:73], 0, v[0:1]
	global_store_dword v[8:9], v11, off
	s_andn2_b64 exec, exec, s[14:15]
	s_cbranch_execnz .LBB0_347
